# GEMM K-loops: removed the duplicate s_waitcnt lgkmcnt(0) that followed s_setprio 1 (an identical wait sits right before it) in front of every MFMA section
# speedup vs baseline: 1.0065x; 1.0046x over previous
.LBB0_175:
	ds_read_b128 v[16:19], v233
	ds_read_b128 v[20:23], v233 offset:1024
	ds_read_b128 v[24:27], v233 offset:2048
	ds_read_b128 v[28:31], v233 offset:3072
	s_add_u32 s6, s4, 0xfffc0080
	s_addc_u32 s7, s5, -1
	s_cmp_eq_u32 s34, 12
	s_cselect_b32 s9, s10, s7
	s_cselect_b32 s8, s11, s6
	s_cselect_b32 s7, s25, s31
	s_cselect_b32 s6, s29, s30
	v_lshl_add_u64 v[202:203], s[4:5], 0, v[182:183]
	s_add_i32 m0, s92, 0xc000
	ds_read_b128 v[40:43], v234
	ds_read_b128 v[44:47], v234 offset:1024
	ds_read_b128 v[48:51], v234 offset:2048
	ds_read_b128 v[52:55], v234 offset:3072
	ds_read_b128 v[186:189], v234 offset:4096
	ds_read_b128 v[190:193], v234 offset:5120
	ds_read_b128 v[194:197], v234 offset:6144
	ds_read_b128 v[198:201], v234 offset:7168
	global_load_lds_dwordx4 v[202:203], off
	v_lshl_add_u64 v[202:203], s[4:5], 0, v[184:185]
	s_add_i32 m0, s92, 0xe000
	s_nop 0
	global_load_lds_dwordx4 v[202:203], off
	s_waitcnt lgkmcnt(8)
	s_barrier
	s_waitcnt lgkmcnt(0)
	s_setprio 1
	v_mfma_f32_16x16x32_bf16 v[156:159], v[16:19], v[40:43], v[156:159]
	v_mfma_f32_16x16x32_bf16 v[152:155], v[24:27], v[40:43], v[152:155]
	v_mfma_f32_16x16x32_bf16 v[140:143], v[16:19], v[48:51], v[140:143]
	v_mfma_f32_16x16x32_bf16 v[136:139], v[24:27], v[48:51], v[136:139]
	v_mfma_f32_16x16x32_bf16 v[124:127], v[16:19], v[186:189], v[124:127]
	v_mfma_f32_16x16x32_bf16 v[120:123], v[24:27], v[186:189], v[120:123]
	v_mfma_f32_16x16x32_bf16 v[108:111], v[16:19], v[194:197], v[108:111]
	v_mfma_f32_16x16x32_bf16 v[104:107], v[24:27], v[194:197], v[104:107]
	v_mfma_f32_16x16x32_bf16 v[156:159], v[20:23], v[44:47], v[156:159]
	v_mfma_f32_16x16x32_bf16 v[152:155], v[28:31], v[44:47], v[152:155]
	v_mfma_f32_16x16x32_bf16 v[140:143], v[20:23], v[52:55], v[140:143]
	v_mfma_f32_16x16x32_bf16 v[136:139], v[28:31], v[52:55], v[136:139]
	v_mfma_f32_16x16x32_bf16 v[124:127], v[20:23], v[190:193], v[124:127]
	v_mfma_f32_16x16x32_bf16 v[120:123], v[28:31], v[190:193], v[120:123]
	v_mfma_f32_16x16x32_bf16 v[108:111], v[20:23], v[198:201], v[108:111]
	v_mfma_f32_16x16x32_bf16 v[104:107], v[28:31], v[198:201], v[104:107]
	s_setprio 0
	s_barrier
	s_add_i32 s35, s1, s33
	v_lshl_add_u64 v[218:219], s[6:7], 0, v[166:167]
	s_mov_b32 m0, s35
	ds_read_b128 v[202:205], v235
	ds_read_b128 v[206:209], v235 offset:1024
	ds_read_b128 v[210:213], v235 offset:2048
	ds_read_b128 v[214:217], v235 offset:3072
	global_load_lds_dwordx4 v[218:219], off
	v_lshl_add_u64 v[246:247], s[6:7], 0, v[162:163]
	s_add_i32 m0, s35, 0x2000
	s_nop 0
	global_load_lds_dwordx4 v[246:247], off
	s_barrier
	s_waitcnt lgkmcnt(0)
	s_setprio 1
	v_mfma_f32_16x16x32_bf16 v[148:151], v[202:205], v[40:43], v[148:151]
	v_mfma_f32_16x16x32_bf16 v[40:43], v[210:213], v[40:43], v[144:147]
	v_mfma_f32_16x16x32_bf16 v[148:151], v[206:209], v[44:47], v[148:151]
	v_mfma_f32_16x16x32_bf16 v[40:43], v[214:217], v[44:47], v[40:43]
	v_mfma_f32_16x16x32_bf16 v[44:47], v[202:205], v[48:51], v[132:135]
	v_mfma_f32_16x16x32_bf16 v[48:51], v[210:213], v[48:51], v[128:131]
	v_mfma_f32_16x16x32_bf16 v[112:115], v[210:213], v[186:189], v[112:115]
	v_mfma_f32_16x16x32_bf16 v[100:103], v[202:205], v[194:197], v[100:103]
	v_mfma_f32_16x16x32_bf16 v[96:99], v[210:213], v[194:197], v[96:99]
	v_mfma_f32_16x16x32_bf16 v[44:47], v[206:209], v[52:55], v[44:47]
	v_mfma_f32_16x16x32_bf16 v[48:51], v[214:217], v[52:55], v[48:51]
	v_mfma_f32_16x16x32_bf16 v[52:55], v[202:205], v[186:189], v[116:119]
	v_mfma_f32_16x16x32_bf16 v[112:115], v[214:217], v[190:193], v[112:115]
	v_mfma_f32_16x16x32_bf16 v[100:103], v[206:209], v[198:201], v[100:103]
	v_mfma_f32_16x16x32_bf16 v[96:99], v[214:217], v[198:201], v[96:99]
	v_mfma_f32_16x16x32_bf16 v[52:55], v[206:209], v[190:193], v[52:55]
	s_setprio 0
	s_mov_b32 m0, s92
	v_lshl_add_u64 v[248:249], s[8:9], 0, v[168:169]
	s_barrier
	ds_read_b128 v[116:119], v234 offset:16384
	ds_read_b128 v[128:131], v234 offset:17408
	ds_read_b128 v[132:135], v234 offset:18432
	ds_read_b128 v[144:147], v234 offset:19456
	ds_read_b128 v[186:189], v234 offset:20480
	ds_read_b128 v[190:193], v234 offset:21504
	ds_read_b128 v[194:197], v234 offset:22528
	ds_read_b128 v[198:201], v234 offset:23552
	global_load_lds_dwordx4 v[248:249], off
	v_lshl_add_u64 v[250:251], s[8:9], 0, v[164:165]
	s_mov_b32 m0, s93
	s_nop 0
	global_load_lds_dwordx4 v[250:251], off
	s_barrier
	s_waitcnt lgkmcnt(0)
	s_setprio 1
	v_mfma_f32_16x16x32_bf16 v[92:95], v[16:19], v[116:119], v[92:95]
	v_mfma_f32_16x16x32_bf16 v[88:91], v[24:27], v[116:119], v[88:91]
	v_mfma_f32_16x16x32_bf16 v[76:79], v[16:19], v[132:135], v[76:79]
	v_mfma_f32_16x16x32_bf16 v[72:75], v[24:27], v[132:135], v[72:75]
	v_mfma_f32_16x16x32_bf16 v[60:63], v[16:19], v[186:189], v[60:63]
	v_mfma_f32_16x16x32_bf16 v[56:59], v[24:27], v[186:189], v[56:59]
	v_mfma_f32_16x16x32_bf16 v[12:15], v[16:19], v[194:197], v[12:15]
	v_mfma_f32_16x16x32_bf16 v[8:11], v[24:27], v[194:197], v[8:11]
	v_mfma_f32_16x16x32_bf16 v[92:95], v[20:23], v[128:131], v[92:95]
	v_mfma_f32_16x16x32_bf16 v[88:91], v[28:31], v[128:131], v[88:91]
	v_mfma_f32_16x16x32_bf16 v[76:79], v[20:23], v[144:147], v[76:79]
	v_mfma_f32_16x16x32_bf16 v[72:75], v[28:31], v[144:147], v[72:75]
	v_mfma_f32_16x16x32_bf16 v[60:63], v[20:23], v[190:193], v[60:63]
	v_mfma_f32_16x16x32_bf16 v[56:59], v[28:31], v[190:193], v[56:59]
	v_mfma_f32_16x16x32_bf16 v[12:15], v[20:23], v[198:201], v[12:15]
	v_mfma_f32_16x16x32_bf16 v[8:11], v[28:31], v[198:201], v[8:11]
	s_setprio 0
	s_barrier
	s_add_u32 s56, s6, 0x40000
	s_addc_u32 s57, s7, 0
	s_add_i32 s35, s18, s33
	v_lshl_add_u64 v[16:17], s[56:57], 0, v[166:167]
	s_mov_b32 m0, s35
	s_nop 0
	global_load_lds_dwordx4 v[16:17], off
	v_lshl_add_u64 v[16:17], s[56:57], 0, v[162:163]
	s_add_i32 m0, s35, 0x2000
	s_nop 0
	global_load_lds_dwordx4 v[16:17], off
	s_waitcnt vmcnt(6)
	s_barrier
	s_setprio 1
	v_mfma_f32_16x16x32_bf16 v[36:39], v[202:205], v[186:189], v[36:39]
	v_mfma_f32_16x16x32_bf16 v[32:35], v[210:213], v[186:189], v[32:35]
	v_mfma_f32_16x16x32_bf16 v[4:7], v[202:205], v[194:197], v[4:7]
	v_mfma_f32_16x16x32_bf16 v[0:3], v[210:213], v[194:197], v[0:3]
	v_mfma_f32_16x16x32_bf16 v[16:19], v[202:205], v[116:119], v[84:87]
	v_mfma_f32_16x16x32_bf16 v[20:23], v[210:213], v[116:119], v[80:83]
	v_mfma_f32_16x16x32_bf16 v[24:27], v[202:205], v[132:135], v[68:71]
	v_mfma_f32_16x16x32_bf16 v[28:31], v[210:213], v[132:135], v[64:67]
	v_mfma_f32_16x16x32_bf16 v[36:39], v[206:209], v[190:193], v[36:39]
	v_mfma_f32_16x16x32_bf16 v[32:35], v[214:217], v[190:193], v[32:35]
	v_mfma_f32_16x16x32_bf16 v[4:7], v[206:209], v[198:201], v[4:7]
	v_mfma_f32_16x16x32_bf16 v[0:3], v[214:217], v[198:201], v[0:3]
	v_mfma_f32_16x16x32_bf16 v[16:19], v[206:209], v[128:131], v[16:19]
	v_mfma_f32_16x16x32_bf16 v[20:23], v[214:217], v[128:131], v[20:23]
	v_mfma_f32_16x16x32_bf16 v[24:27], v[206:209], v[144:147], v[24:27]
	v_mfma_f32_16x16x32_bf16 v[28:31], v[214:217], v[144:147], v[28:31]
	s_setprio 0
	s_add_i32 s35, 0, 0x18000
	v_add_u32_e32 v84, s35, v232
	s_barrier
	ds_read_b128 v[64:67], v84
	ds_read_b128 v[68:71], v84 offset:1024
	ds_read_b128 v[80:83], v84 offset:2048
	ds_read_b128 v[84:87], v84 offset:3072
	s_add_u32 s8, s8, 0x40000
	s_addc_u32 s9, s9, 0
	s_mov_b32 m0, s96
	v_lshl_add_u64 v[132:133], s[8:9], 0, v[168:169]
	ds_read_b128 v[116:119], v234 offset:32768
	ds_read_b128 v[128:131], v234 offset:33792
	ds_read_b128 v[186:189], v234 offset:34816
	ds_read_b128 v[190:193], v234 offset:35840
	ds_read_b128 v[194:197], v234 offset:36864
	ds_read_b128 v[198:201], v234 offset:37888
	ds_read_b128 v[202:205], v234 offset:38912
	ds_read_b128 v[206:209], v234 offset:39936
	global_load_lds_dwordx4 v[132:133], off
	v_lshl_add_u64 v[132:133], s[8:9], 0, v[164:165]
	s_mov_b32 m0, s97
	s_nop 0
	global_load_lds_dwordx4 v[132:133], off
	s_waitcnt lgkmcnt(8)
	s_barrier
	s_waitcnt lgkmcnt(0)
	s_setprio 1
	v_mfma_f32_16x16x32_bf16 v[132:135], v[64:67], v[116:119], v[156:159]
	v_mfma_f32_16x16x32_bf16 v[156:159], v[68:71], v[128:131], v[132:135]
	v_mfma_f32_16x16x32_bf16 v[132:135], v[80:83], v[116:119], v[152:155]
	v_mfma_f32_16x16x32_bf16 v[152:155], v[84:87], v[128:131], v[132:135]
	v_mfma_f32_16x16x32_bf16 v[132:135], v[64:67], v[186:189], v[140:143]
	v_mfma_f32_16x16x32_bf16 v[140:143], v[68:71], v[190:193], v[132:135]
	v_mfma_f32_16x16x32_bf16 v[132:135], v[80:83], v[186:189], v[136:139]
	v_mfma_f32_16x16x32_bf16 v[124:127], v[64:67], v[194:197], v[124:127]
	v_mfma_f32_16x16x32_bf16 v[120:123], v[80:83], v[194:197], v[120:123]
	v_mfma_f32_16x16x32_bf16 v[108:111], v[64:67], v[202:205], v[108:111]
	v_mfma_f32_16x16x32_bf16 v[104:107], v[80:83], v[202:205], v[104:107]
	v_mfma_f32_16x16x32_bf16 v[136:139], v[84:87], v[190:193], v[132:135]
	v_mfma_f32_16x16x32_bf16 v[124:127], v[68:71], v[198:201], v[124:127]
	v_mfma_f32_16x16x32_bf16 v[120:123], v[84:87], v[198:201], v[120:123]
	v_mfma_f32_16x16x32_bf16 v[108:111], v[68:71], v[206:209], v[108:111]
	v_mfma_f32_16x16x32_bf16 v[104:107], v[84:87], v[206:209], v[104:107]
	s_setprio 0
	s_barrier
	s_add_i32 s8, 0, 0x1c000
	v_add_u32_e32 v132, s8, v232
	s_add_i32 s9, s35, s33
	ds_read_b128 v[210:213], v132
	ds_read_b128 v[214:217], v132 offset:1024
	ds_read_b128 v[238:241], v132 offset:2048
	ds_read_b128 v[242:245], v132 offset:3072
	v_lshl_add_u64 v[132:133], v[218:219], 0, s[14:15]
	s_mov_b32 m0, s9
	s_nop 0
	global_load_lds_dwordx4 v[132:133], off
	v_lshl_add_u64 v[132:133], v[246:247], 0, s[14:15]
	s_add_i32 m0, s9, 0x2000
	s_nop 0
	global_load_lds_dwordx4 v[132:133], off
	s_barrier
	s_waitcnt lgkmcnt(0)
	s_setprio 1
	v_mfma_f32_16x16x32_bf16 v[40:43], v[238:241], v[116:119], v[40:43]
	v_mfma_f32_16x16x32_bf16 v[132:135], v[210:213], v[116:119], v[148:151]
	v_mfma_f32_16x16x32_bf16 v[144:147], v[242:245], v[128:131], v[40:43]
	v_mfma_f32_16x16x32_bf16 v[40:43], v[210:213], v[186:189], v[44:47]
	v_mfma_f32_16x16x32_bf16 v[148:151], v[214:217], v[128:131], v[132:135]
	v_mfma_f32_16x16x32_bf16 v[132:135], v[214:217], v[190:193], v[40:43]
	v_mfma_f32_16x16x32_bf16 v[40:43], v[238:241], v[186:189], v[48:51]
	v_mfma_f32_16x16x32_bf16 v[128:131], v[242:245], v[190:193], v[40:43]
	v_mfma_f32_16x16x32_bf16 v[40:43], v[210:213], v[194:197], v[52:55]
	v_mfma_f32_16x16x32_bf16 v[116:119], v[214:217], v[198:201], v[40:43]
	v_mfma_f32_16x16x32_bf16 v[40:43], v[238:241], v[194:197], v[112:115]
	v_mfma_f32_16x16x32_bf16 v[112:115], v[242:245], v[198:201], v[40:43]
	v_mfma_f32_16x16x32_bf16 v[40:43], v[210:213], v[202:205], v[100:103]
	v_mfma_f32_16x16x32_bf16 v[100:103], v[214:217], v[206:209], v[40:43]
	v_mfma_f32_16x16x32_bf16 v[40:43], v[238:241], v[202:205], v[96:99]
	v_mfma_f32_16x16x32_bf16 v[96:99], v[242:245], v[206:209], v[40:43]
	s_setprio 0
	s_mov_b32 m0, s53
	v_lshl_add_u64 v[202:203], v[248:249], 0, s[14:15]
	s_barrier
	s_nop 2
	ds_read_b128 v[40:43], v234 offset:49152
	ds_read_b128 v[44:47], v234 offset:50176
	ds_read_b128 v[48:51], v234 offset:51200
	ds_read_b128 v[52:55], v234 offset:52224
	ds_read_b128 v[186:189], v234 offset:53248
	ds_read_b128 v[190:193], v234 offset:54272
	ds_read_b128 v[194:197], v234 offset:55296
	ds_read_b128 v[198:201], v234 offset:56320
	global_load_lds_dwordx4 v[202:203], off
	v_lshl_add_u64 v[202:203], v[250:251], 0, s[14:15]
	s_mov_b32 m0, s23
	s_nop 0
	global_load_lds_dwordx4 v[202:203], off
	s_barrier
	s_waitcnt lgkmcnt(0)
	s_setprio 1
	v_mfma_f32_16x16x32_bf16 v[92:95], v[64:67], v[40:43], v[92:95]
	v_mfma_f32_16x16x32_bf16 v[88:91], v[80:83], v[40:43], v[88:91]
	v_mfma_f32_16x16x32_bf16 v[76:79], v[64:67], v[48:51], v[76:79]
	v_mfma_f32_16x16x32_bf16 v[72:75], v[80:83], v[48:51], v[72:75]
	v_mfma_f32_16x16x32_bf16 v[60:63], v[64:67], v[186:189], v[60:63]
	v_mfma_f32_16x16x32_bf16 v[56:59], v[80:83], v[186:189], v[56:59]
	v_mfma_f32_16x16x32_bf16 v[12:15], v[64:67], v[194:197], v[12:15]
	v_mfma_f32_16x16x32_bf16 v[8:11], v[80:83], v[194:197], v[8:11]
	v_mfma_f32_16x16x32_bf16 v[92:95], v[68:71], v[44:47], v[92:95]
	v_mfma_f32_16x16x32_bf16 v[88:91], v[84:87], v[44:47], v[88:91]
	v_mfma_f32_16x16x32_bf16 v[76:79], v[68:71], v[52:55], v[76:79]
	v_mfma_f32_16x16x32_bf16 v[72:75], v[84:87], v[52:55], v[72:75]
	v_mfma_f32_16x16x32_bf16 v[60:63], v[68:71], v[190:193], v[60:63]
	v_mfma_f32_16x16x32_bf16 v[56:59], v[84:87], v[190:193], v[56:59]
	v_mfma_f32_16x16x32_bf16 v[12:15], v[68:71], v[198:201], v[12:15]
	v_mfma_f32_16x16x32_bf16 v[8:11], v[84:87], v[198:201], v[8:11]
	s_setprio 0
	s_barrier
	s_add_u32 s6, s6, 0x40080
	s_addc_u32 s7, s7, 0
	s_add_i32 s8, s8, s33
	v_lshl_add_u64 v[64:65], s[6:7], 0, v[166:167]
	s_mov_b32 m0, s8
	s_nop 0
	global_load_lds_dwordx4 v[64:65], off
	v_lshl_add_u64 v[64:65], s[6:7], 0, v[162:163]
	s_add_i32 m0, s8, 0x2000
	s_nop 0
	global_load_lds_dwordx4 v[64:65], off
	s_waitcnt vmcnt(6)
	s_barrier
	s_setprio 1
	v_mfma_f32_16x16x32_bf16 v[16:19], v[210:213], v[40:43], v[16:19]
	v_mfma_f32_16x16x32_bf16 v[84:87], v[214:217], v[44:47], v[16:19]
	v_mfma_f32_16x16x32_bf16 v[16:19], v[238:241], v[40:43], v[20:23]
	v_mfma_f32_16x16x32_bf16 v[80:83], v[242:245], v[44:47], v[16:19]
	v_mfma_f32_16x16x32_bf16 v[16:19], v[210:213], v[48:51], v[24:27]
	v_mfma_f32_16x16x32_bf16 v[68:71], v[214:217], v[52:55], v[16:19]
	v_mfma_f32_16x16x32_bf16 v[16:19], v[238:241], v[48:51], v[28:31]
	v_mfma_f32_16x16x32_bf16 v[64:67], v[242:245], v[52:55], v[16:19]
	v_mfma_f32_16x16x32_bf16 v[16:19], v[210:213], v[186:189], v[36:39]
	v_mfma_f32_16x16x32_bf16 v[36:39], v[214:217], v[190:193], v[16:19]
	v_mfma_f32_16x16x32_bf16 v[16:19], v[238:241], v[186:189], v[32:35]
	v_mfma_f32_16x16x32_bf16 v[4:7], v[210:213], v[194:197], v[4:7]
	v_mfma_f32_16x16x32_bf16 v[0:3], v[238:241], v[194:197], v[0:3]
	v_mfma_f32_16x16x32_bf16 v[32:35], v[242:245], v[190:193], v[16:19]
	v_mfma_f32_16x16x32_bf16 v[4:7], v[214:217], v[198:201], v[4:7]
	v_mfma_f32_16x16x32_bf16 v[0:3], v[242:245], v[198:201], v[0:3]
	s_setprio 0
	s_add_i32 s34, s34, 2
	s_add_u32 s4, s4, 0x100
	s_addc_u32 s5, s5, 0
	s_add_u32 s30, s30, 0x100
	s_addc_u32 s31, s31, 0
	s_cmp_gt_u32 s34, 13
	s_barrier
	s_cbranch_scc0 .LBB0_175
	s_cmp_gt_i32 s28, 1
	s_cselect_b64 s[6:7], -1, 0
	s_cmp_lt_i32 s28, 2
	s_cselect_b64 s[4:5], -1, 0
	s_add_i32 s8, s28, -3
	s_cmp_lt_u32 s8, 2
	s_cselect_b64 s[8:9], -1, 0
	s_lshl_b32 s29, s12, 8
	s_add_i32 s29, s29, s52
	v_or_b32_e32 v196, s29, v179
	s_nop 0
	v_ashrrev_i32_e32 v197, 31, v196
	v_readlane_b32 s72, v253, 63
	v_readlane_b32 s73, v252, 0
	s_or_b64 s[4:5], s[4:5], s[8:9]
	s_and_b32 s8, s29, 0xfc0
	v_lshl_add_u64 v[16:17], v[196:197], 2, s[72:73]
	global_load_dword v204, v[16:17], off
	global_load_dword v200, v[16:17], off offset:64
	global_load_dword v198, v[16:17], off offset:128
	global_load_dword v194, v[16:17], off offset:192
	global_load_dword v192, v[16:17], off offset:512
	global_load_dword v190, v[16:17], off offset:576
	global_load_dword v188, v[16:17], off offset:640
	global_load_dword v186, v[16:17], off offset:704
	v_or_b32_e32 v16, s8, v179
	v_readlane_b32 s8, v252, 45
	v_readlane_b32 s9, v252, 46
	s_and_b64 s[62:63], s[8:9], s[4:5]
	v_cndmask_b32_e64 v17, 0, 1, s[62:63]
	v_readlane_b32 s68, v253, 59
	v_readlane_b32 s69, v253, 60
	v_readlane_b32 s76, v252, 3
	v_readlane_b32 s77, v252, 4
	v_readlane_b32 s78, v252, 5
	v_readlane_b32 s79, v252, 6
	v_cmp_ne_u32_e64 s[4:5], 1, v17
	s_andn2_b64 vcc, exec, s[62:63]
	v_lshlrev_b32_e32 v187, 6, v16
	s_nop 6
	s_cbranch_vccnz .LBB0_178
	global_load_dwordx4 v[40:43], v187, s[76:77] offset:48
	global_load_dwordx4 v[44:47], v187, s[76:77] offset:32
	global_load_dwordx4 v[48:51], v187, s[76:77] offset:16
	global_load_dwordx4 v[52:55], v187, s[76:77]
	global_load_dwordx4 v[16:19], v187, s[76:77] offset:1072
	global_load_dwordx4 v[20:23], v187, s[76:77] offset:1056
	global_load_dwordx4 v[24:27], v187, s[76:77] offset:1040
	global_load_dwordx4 v[28:31], v187, s[76:77] offset:1024

.LBB0_612:
	ds_read_b128 v[164:167], v159
	ds_read_b128 v[168:171], v159 offset:1024
	ds_read_b128 v[180:183], v159 offset:2048
	ds_read_b128 v[184:187], v159 offset:3072
	s_add_u32 s24, s22, 0xfffc0080
	s_addc_u32 s25, s23, -1
	s_cmp_eq_u32 s45, 4
	s_cselect_b32 s35, s9, s25
	s_cselect_b32 s34, s41, s24
	s_cselect_b32 s25, s7, s44
	s_cselect_b32 s24, s42, s43
	v_lshl_add_u64 v[172:173], s[22:23], 0, v[154:155]
	s_add_i32 m0, s3, 0xc000
	ds_read_b128 v[188:191], v162
	ds_read_b128 v[192:195], v162 offset:1024
	ds_read_b128 v[196:199], v162 offset:2048
	ds_read_b128 v[200:203], v162 offset:3072
	ds_read_b128 v[204:207], v162 offset:4096
	ds_read_b128 v[208:211], v162 offset:5120
	ds_read_b128 v[212:215], v162 offset:6144
	ds_read_b128 v[216:219], v162 offset:7168
	global_load_lds_dwordx4 v[172:173], off
	v_lshl_add_u64 v[172:173], s[22:23], 0, v[156:157]
	s_add_i32 m0, s3, 0xe000
	s_nop 0
	global_load_lds_dwordx4 v[172:173], off
	s_waitcnt lgkmcnt(8)
	s_barrier
	s_waitcnt lgkmcnt(0)
	s_setprio 1
	v_mfma_f32_16x16x32_bf16 v[124:127], v[164:167], v[188:191], v[124:127]
	v_mfma_f32_16x16x32_bf16 v[120:123], v[180:183], v[188:191], v[120:123]
	v_mfma_f32_16x16x32_bf16 v[116:119], v[164:167], v[196:199], v[116:119]
	v_mfma_f32_16x16x32_bf16 v[112:115], v[180:183], v[196:199], v[112:115]
	v_mfma_f32_16x16x32_bf16 v[108:111], v[164:167], v[204:207], v[108:111]
	v_mfma_f32_16x16x32_bf16 v[100:103], v[180:183], v[204:207], v[100:103]
	v_mfma_f32_16x16x32_bf16 v[92:95], v[164:167], v[212:215], v[92:95]
	v_mfma_f32_16x16x32_bf16 v[84:87], v[180:183], v[212:215], v[84:87]
	v_mfma_f32_16x16x32_bf16 v[124:127], v[168:171], v[192:195], v[124:127]
	v_mfma_f32_16x16x32_bf16 v[120:123], v[184:187], v[192:195], v[120:123]
	v_mfma_f32_16x16x32_bf16 v[116:119], v[168:171], v[200:203], v[116:119]
	v_mfma_f32_16x16x32_bf16 v[112:115], v[184:187], v[200:203], v[112:115]
	v_mfma_f32_16x16x32_bf16 v[108:111], v[168:171], v[208:211], v[108:111]
	v_mfma_f32_16x16x32_bf16 v[100:103], v[184:187], v[208:211], v[100:103]
	v_mfma_f32_16x16x32_bf16 v[92:95], v[168:171], v[216:219], v[92:95]
	v_mfma_f32_16x16x32_bf16 v[84:87], v[184:187], v[216:219], v[84:87]
	s_setprio 0
	s_barrier
	s_add_i32 s52, s31, s19
	v_lshl_add_u64 v[172:173], s[24:25], 0, v[130:131]
	s_mov_b32 m0, s52
	ds_read_b128 v[232:235], v163
	ds_read_b128 v[236:239], v163 offset:1024
	ds_read_b128 v[240:243], v163 offset:2048
	ds_read_b128 v[244:247], v163 offset:3072
	global_load_lds_dwordx4 v[172:173], off
	v_lshl_add_u64 v[176:177], s[24:25], 0, v[134:135]
	s_add_i32 m0, s52, 0x2000
	s_nop 0
	global_load_lds_dwordx4 v[176:177], off
	s_barrier
	s_waitcnt lgkmcnt(0)
	s_setprio 1
	v_mfma_f32_16x16x32_bf16 v[104:107], v[232:235], v[188:191], v[104:107]
	v_mfma_f32_16x16x32_bf16 v[96:99], v[240:243], v[188:191], v[96:99]
	v_mfma_f32_16x16x32_bf16 v[88:91], v[232:235], v[196:199], v[88:91]
	v_mfma_f32_16x16x32_bf16 v[80:83], v[240:243], v[196:199], v[80:83]
	v_mfma_f32_16x16x32_bf16 v[76:79], v[232:235], v[204:207], v[76:79]
	v_mfma_f32_16x16x32_bf16 v[72:75], v[240:243], v[204:207], v[72:75]
	v_mfma_f32_16x16x32_bf16 v[68:71], v[232:235], v[212:215], v[68:71]
	v_mfma_f32_16x16x32_bf16 v[64:67], v[240:243], v[212:215], v[64:67]
	v_mfma_f32_16x16x32_bf16 v[104:107], v[236:239], v[192:195], v[104:107]
	v_mfma_f32_16x16x32_bf16 v[96:99], v[244:247], v[192:195], v[96:99]
	v_mfma_f32_16x16x32_bf16 v[88:91], v[236:239], v[200:203], v[88:91]
	v_mfma_f32_16x16x32_bf16 v[80:83], v[244:247], v[200:203], v[80:83]
	v_mfma_f32_16x16x32_bf16 v[76:79], v[236:239], v[208:211], v[76:79]
	v_mfma_f32_16x16x32_bf16 v[72:75], v[244:247], v[208:211], v[72:75]
	v_mfma_f32_16x16x32_bf16 v[68:71], v[236:239], v[216:219], v[68:71]
	v_mfma_f32_16x16x32_bf16 v[64:67], v[244:247], v[216:219], v[64:67]
	s_setprio 0
	s_mov_b32 m0, s3
	v_lshl_add_u64 v[248:249], s[34:35], 0, v[128:129]
	s_barrier
	ds_read_b128 v[188:191], v162 offset:16384
	ds_read_b128 v[192:195], v162 offset:17408
	ds_read_b128 v[196:199], v162 offset:18432
	ds_read_b128 v[200:203], v162 offset:19456
	ds_read_b128 v[204:207], v162 offset:20480
	ds_read_b128 v[208:211], v162 offset:21504
	ds_read_b128 v[212:215], v162 offset:22528
	ds_read_b128 v[216:219], v162 offset:23552
	global_load_lds_dwordx4 v[248:249], off
	v_lshl_add_u64 v[250:251], s[34:35], 0, v[132:133]
	s_mov_b32 m0, s20
	s_nop 0
	global_load_lds_dwordx4 v[250:251], off
	s_barrier
	s_waitcnt lgkmcnt(0)
	s_setprio 1
	v_mfma_f32_16x16x32_bf16 v[60:63], v[164:167], v[188:191], v[60:63]
	v_mfma_f32_16x16x32_bf16 v[56:59], v[180:183], v[188:191], v[56:59]
	v_mfma_f32_16x16x32_bf16 v[52:55], v[164:167], v[196:199], v[52:55]
	v_mfma_f32_16x16x32_bf16 v[48:51], v[180:183], v[196:199], v[48:51]
	v_mfma_f32_16x16x32_bf16 v[44:47], v[164:167], v[204:207], v[44:47]
	v_mfma_f32_16x16x32_bf16 v[40:43], v[180:183], v[204:207], v[40:43]
	v_mfma_f32_16x16x32_bf16 v[28:31], v[164:167], v[212:215], v[28:31]
	v_mfma_f32_16x16x32_bf16 v[24:27], v[180:183], v[212:215], v[24:27]
	v_mfma_f32_16x16x32_bf16 v[60:63], v[168:171], v[192:195], v[60:63]
	v_mfma_f32_16x16x32_bf16 v[56:59], v[184:187], v[192:195], v[56:59]
	v_mfma_f32_16x16x32_bf16 v[52:55], v[168:171], v[200:203], v[52:55]
	v_mfma_f32_16x16x32_bf16 v[48:51], v[184:187], v[200:203], v[48:51]
	v_mfma_f32_16x16x32_bf16 v[44:47], v[168:171], v[208:211], v[44:47]
	v_mfma_f32_16x16x32_bf16 v[40:43], v[184:187], v[208:211], v[40:43]
	v_mfma_f32_16x16x32_bf16 v[28:31], v[168:171], v[216:219], v[28:31]
	v_mfma_f32_16x16x32_bf16 v[24:27], v[184:187], v[216:219], v[24:27]
	s_setprio 0
	s_barrier
	s_add_u32 s52, s24, 0x80000
	s_addc_u32 s53, s25, 0
	s_add_i32 s54, s33, s19
	v_lshl_add_u64 v[164:165], s[52:53], 0, v[130:131]
	s_mov_b32 m0, s54
	s_nop 0
	global_load_lds_dwordx4 v[164:165], off
	v_lshl_add_u64 v[164:165], s[52:53], 0, v[134:135]
	s_add_i32 m0, s54, 0x2000
	s_nop 0
	global_load_lds_dwordx4 v[164:165], off
	s_waitcnt vmcnt(6)
	s_barrier
	s_setprio 1
	v_mfma_f32_16x16x32_bf16 v[36:39], v[232:235], v[188:191], v[36:39]
	v_mfma_f32_16x16x32_bf16 v[32:35], v[240:243], v[188:191], v[32:35]
	v_mfma_f32_16x16x32_bf16 v[20:23], v[232:235], v[196:199], v[20:23]
	v_mfma_f32_16x16x32_bf16 v[16:19], v[240:243], v[196:199], v[16:19]
	v_mfma_f32_16x16x32_bf16 v[12:15], v[232:235], v[204:207], v[12:15]
	v_mfma_f32_16x16x32_bf16 v[8:11], v[240:243], v[204:207], v[8:11]
	v_mfma_f32_16x16x32_bf16 v[4:7], v[232:235], v[212:215], v[4:7]
	v_mfma_f32_16x16x32_bf16 v[0:3], v[240:243], v[212:215], v[0:3]
	v_mfma_f32_16x16x32_bf16 v[36:39], v[236:239], v[192:195], v[36:39]
	v_mfma_f32_16x16x32_bf16 v[32:35], v[244:247], v[192:195], v[32:35]
	v_mfma_f32_16x16x32_bf16 v[20:23], v[236:239], v[200:203], v[20:23]
	v_mfma_f32_16x16x32_bf16 v[16:19], v[244:247], v[200:203], v[16:19]
	v_mfma_f32_16x16x32_bf16 v[12:15], v[236:239], v[208:211], v[12:15]
	v_mfma_f32_16x16x32_bf16 v[8:11], v[244:247], v[208:211], v[8:11]
	v_mfma_f32_16x16x32_bf16 v[4:7], v[236:239], v[216:219], v[4:7]
	v_mfma_f32_16x16x32_bf16 v[0:3], v[244:247], v[216:219], v[0:3]
	s_setprio 0
	s_add_i32 s52, 0, 0x18000
	v_add_u32_e32 v174, s52, v158
	s_barrier
	ds_read_b128 v[164:167], v174
	ds_read_b128 v[168:171], v174 offset:1024
	ds_read_b128 v[180:183], v174 offset:2048
	ds_read_b128 v[184:187], v174 offset:3072
	s_add_u32 s34, s34, 0x40000
	s_addc_u32 s35, s35, 0
	s_mov_b32 m0, s21
	v_lshl_add_u64 v[232:233], s[34:35], 0, v[128:129]
	ds_read_b128 v[188:191], v162 offset:32768
	ds_read_b128 v[192:195], v162 offset:33792
	ds_read_b128 v[196:199], v162 offset:34816
	ds_read_b128 v[200:203], v162 offset:35840
	ds_read_b128 v[204:207], v162 offset:36864
	ds_read_b128 v[208:211], v162 offset:37888
	ds_read_b128 v[212:215], v162 offset:38912
	ds_read_b128 v[216:219], v162 offset:39936
	global_load_lds_dwordx4 v[232:233], off
	v_lshl_add_u64 v[232:233], s[34:35], 0, v[132:133]
	s_mov_b32 m0, s27
	s_nop 0
	global_load_lds_dwordx4 v[232:233], off
	s_waitcnt lgkmcnt(8)
	s_barrier
	s_waitcnt lgkmcnt(0)
	s_setprio 1
	v_mfma_f32_16x16x32_bf16 v[124:127], v[164:167], v[188:191], v[124:127]
	v_mfma_f32_16x16x32_bf16 v[120:123], v[180:183], v[188:191], v[120:123]
	v_mfma_f32_16x16x32_bf16 v[116:119], v[164:167], v[196:199], v[116:119]
	v_mfma_f32_16x16x32_bf16 v[112:115], v[180:183], v[196:199], v[112:115]
	v_mfma_f32_16x16x32_bf16 v[108:111], v[164:167], v[204:207], v[108:111]
	v_mfma_f32_16x16x32_bf16 v[100:103], v[180:183], v[204:207], v[100:103]
	v_mfma_f32_16x16x32_bf16 v[92:95], v[164:167], v[212:215], v[92:95]
	v_mfma_f32_16x16x32_bf16 v[84:87], v[180:183], v[212:215], v[84:87]
	v_mfma_f32_16x16x32_bf16 v[124:127], v[168:171], v[192:195], v[124:127]
	v_mfma_f32_16x16x32_bf16 v[120:123], v[184:187], v[192:195], v[120:123]
	v_mfma_f32_16x16x32_bf16 v[116:119], v[168:171], v[200:203], v[116:119]
	v_mfma_f32_16x16x32_bf16 v[112:115], v[184:187], v[200:203], v[112:115]
	v_mfma_f32_16x16x32_bf16 v[108:111], v[168:171], v[208:211], v[108:111]
	v_mfma_f32_16x16x32_bf16 v[100:103], v[184:187], v[208:211], v[100:103]
	v_mfma_f32_16x16x32_bf16 v[92:95], v[168:171], v[216:219], v[92:95]
	v_mfma_f32_16x16x32_bf16 v[84:87], v[184:187], v[216:219], v[84:87]
	s_setprio 0
	s_barrier
	s_add_i32 s34, 0, 0x1c000
	s_add_i32 s35, s52, s19
	v_add_u32_e32 v174, s34, v158
	v_lshl_add_u64 v[172:173], v[172:173], 0, s[4:5]
	s_mov_b32 m0, s35
	ds_read_b128 v[232:235], v174
	ds_read_b128 v[236:239], v174 offset:1024
	ds_read_b128 v[240:243], v174 offset:2048
	ds_read_b128 v[244:247], v174 offset:3072
	global_load_lds_dwordx4 v[172:173], off
	v_lshl_add_u64 v[172:173], v[176:177], 0, s[4:5]
	s_add_i32 m0, s35, 0x2000
	s_nop 0
	global_load_lds_dwordx4 v[172:173], off
	s_barrier
	s_waitcnt lgkmcnt(0)
	s_setprio 1
	v_mfma_f32_16x16x32_bf16 v[104:107], v[232:235], v[188:191], v[104:107]
	v_mfma_f32_16x16x32_bf16 v[96:99], v[240:243], v[188:191], v[96:99]
	v_mfma_f32_16x16x32_bf16 v[88:91], v[232:235], v[196:199], v[88:91]
	v_mfma_f32_16x16x32_bf16 v[80:83], v[240:243], v[196:199], v[80:83]
	v_mfma_f32_16x16x32_bf16 v[76:79], v[232:235], v[204:207], v[76:79]
	v_mfma_f32_16x16x32_bf16 v[72:75], v[240:243], v[204:207], v[72:75]
	v_mfma_f32_16x16x32_bf16 v[68:71], v[232:235], v[212:215], v[68:71]
	v_mfma_f32_16x16x32_bf16 v[64:67], v[240:243], v[212:215], v[64:67]
	v_mfma_f32_16x16x32_bf16 v[104:107], v[236:239], v[192:195], v[104:107]
	v_mfma_f32_16x16x32_bf16 v[96:99], v[244:247], v[192:195], v[96:99]
	v_mfma_f32_16x16x32_bf16 v[88:91], v[236:239], v[200:203], v[88:91]
	v_mfma_f32_16x16x32_bf16 v[80:83], v[244:247], v[200:203], v[80:83]
	v_mfma_f32_16x16x32_bf16 v[76:79], v[236:239], v[208:211], v[76:79]
	v_mfma_f32_16x16x32_bf16 v[72:75], v[244:247], v[208:211], v[72:75]
	v_mfma_f32_16x16x32_bf16 v[68:71], v[236:239], v[216:219], v[68:71]
	v_mfma_f32_16x16x32_bf16 v[64:67], v[244:247], v[216:219], v[64:67]
	s_setprio 0
	s_mov_b32 m0, s29
	v_lshl_add_u64 v[172:173], v[248:249], 0, s[4:5]
	s_barrier
	ds_read_b128 v[188:191], v162 offset:49152
	ds_read_b128 v[192:195], v162 offset:50176
	ds_read_b128 v[196:199], v162 offset:51200
	ds_read_b128 v[200:203], v162 offset:52224
	ds_read_b128 v[204:207], v162 offset:53248
	ds_read_b128 v[208:211], v162 offset:54272
	ds_read_b128 v[212:215], v162 offset:55296
	ds_read_b128 v[216:219], v162 offset:56320
	global_load_lds_dwordx4 v[172:173], off
	v_lshl_add_u64 v[172:173], v[250:251], 0, s[4:5]
	s_mov_b32 m0, s30
	s_nop 0
	global_load_lds_dwordx4 v[172:173], off
	s_barrier
	s_waitcnt lgkmcnt(0)
	s_setprio 1
	v_mfma_f32_16x16x32_bf16 v[60:63], v[164:167], v[188:191], v[60:63]
	v_mfma_f32_16x16x32_bf16 v[56:59], v[180:183], v[188:191], v[56:59]
	v_mfma_f32_16x16x32_bf16 v[52:55], v[164:167], v[196:199], v[52:55]
	v_mfma_f32_16x16x32_bf16 v[48:51], v[180:183], v[196:199], v[48:51]
	v_mfma_f32_16x16x32_bf16 v[44:47], v[164:167], v[204:207], v[44:47]
	v_mfma_f32_16x16x32_bf16 v[40:43], v[180:183], v[204:207], v[40:43]
	v_mfma_f32_16x16x32_bf16 v[28:31], v[164:167], v[212:215], v[28:31]
	v_mfma_f32_16x16x32_bf16 v[24:27], v[180:183], v[212:215], v[24:27]
	v_mfma_f32_16x16x32_bf16 v[60:63], v[168:171], v[192:195], v[60:63]
	v_mfma_f32_16x16x32_bf16 v[56:59], v[184:187], v[192:195], v[56:59]
	v_mfma_f32_16x16x32_bf16 v[52:55], v[168:171], v[200:203], v[52:55]
	v_mfma_f32_16x16x32_bf16 v[48:51], v[184:187], v[200:203], v[48:51]
	v_mfma_f32_16x16x32_bf16 v[44:47], v[168:171], v[208:211], v[44:47]
	v_mfma_f32_16x16x32_bf16 v[40:43], v[184:187], v[208:211], v[40:43]
	v_mfma_f32_16x16x32_bf16 v[28:31], v[168:171], v[216:219], v[28:31]
	v_mfma_f32_16x16x32_bf16 v[24:27], v[184:187], v[216:219], v[24:27]
	s_setprio 0
	s_barrier
	s_add_u32 s24, s24, 0x80080
	s_addc_u32 s25, s25, 0
	s_add_i32 s34, s34, s19
	v_lshl_add_u64 v[164:165], s[24:25], 0, v[130:131]
	s_mov_b32 m0, s34
	s_nop 0
	global_load_lds_dwordx4 v[164:165], off
	v_lshl_add_u64 v[164:165], s[24:25], 0, v[134:135]
	s_add_i32 m0, s34, 0x2000
	s_nop 0
	global_load_lds_dwordx4 v[164:165], off
	s_waitcnt vmcnt(6)
	s_barrier
	s_setprio 1
	v_mfma_f32_16x16x32_bf16 v[36:39], v[232:235], v[188:191], v[36:39]
	v_mfma_f32_16x16x32_bf16 v[32:35], v[240:243], v[188:191], v[32:35]
	v_mfma_f32_16x16x32_bf16 v[20:23], v[232:235], v[196:199], v[20:23]
	v_mfma_f32_16x16x32_bf16 v[16:19], v[240:243], v[196:199], v[16:19]
	v_mfma_f32_16x16x32_bf16 v[12:15], v[232:235], v[204:207], v[12:15]
	v_mfma_f32_16x16x32_bf16 v[8:11], v[240:243], v[204:207], v[8:11]
	v_mfma_f32_16x16x32_bf16 v[4:7], v[232:235], v[212:215], v[4:7]
	v_mfma_f32_16x16x32_bf16 v[0:3], v[240:243], v[212:215], v[0:3]
	v_mfma_f32_16x16x32_bf16 v[36:39], v[236:239], v[192:195], v[36:39]
	v_mfma_f32_16x16x32_bf16 v[32:35], v[244:247], v[192:195], v[32:35]
	v_mfma_f32_16x16x32_bf16 v[20:23], v[236:239], v[200:203], v[20:23]
	v_mfma_f32_16x16x32_bf16 v[16:19], v[244:247], v[200:203], v[16:19]
	v_mfma_f32_16x16x32_bf16 v[12:15], v[236:239], v[208:211], v[12:15]
	v_mfma_f32_16x16x32_bf16 v[8:11], v[244:247], v[208:211], v[8:11]
	v_mfma_f32_16x16x32_bf16 v[4:7], v[236:239], v[216:219], v[4:7]
	v_mfma_f32_16x16x32_bf16 v[0:3], v[244:247], v[216:219], v[0:3]
	s_setprio 0
	s_add_i32 s45, s45, 2
	s_add_u32 s22, s22, 0x100
	s_addc_u32 s23, s23, 0
	s_add_u32 s43, s43, 0x100
	s_addc_u32 s44, s44, 0
	s_cmp_gt_u32 s45, 5
	s_barrier
	s_cbranch_scc0 .LBB0_612
	s_lshl_b32 s7, s26, 2
	s_and_b32 s7, s7, 0x7fffffe0
	s_add_i32 s22, s7, s2
	s_ashr_i32 s23, s22, 31
	s_lshl_b64 s[22:23], s[22:23], 18
	s_add_u32 s22, s82, s22
	s_addc_u32 s23, s83, s23
	v_lshl_add_u64 v[164:165], s[22:23], 0, v[138:139]
	v_lshl_add_u64 v[164:165], v[164:165], 0, v[136:137]
	global_store_dwordx4 v[164:165], v[124:127], off
	global_store_dwordx4 v[164:165], v[120:123], off offset:16
	global_store_dwordx4 v[164:165], v[104:107], off offset:512
	global_store_dwordx4 v[164:165], v[96:99], off offset:528
	s_and_b64 vcc, exec, s[10:11]
	s_mov_b32 s26, s40
	v_lshl_add_u64 v[96:97], s[22:23], 0, v[140:141]
	v_lshl_add_u64 v[96:97], v[96:97], 0, v[136:137]
	global_store_dwordx4 v[96:97], v[116:119], off
	global_store_dwordx4 v[96:97], v[112:115], off offset:16
	global_store_dwordx4 v[96:97], v[88:91], off offset:512
	global_store_dwordx4 v[96:97], v[80:83], off offset:528
	s_mov_b32 s2, s8
	s_mov_b64 s[24:25], s[16:17]
	v_lshl_add_u64 v[80:81], s[22:23], 0, v[142:143]
	v_lshl_add_u64 v[80:81], v[80:81], 0, v[136:137]
	global_store_dwordx4 v[80:81], v[108:111], off
	global_store_dwordx4 v[80:81], v[100:103], off offset:16
	global_store_dwordx4 v[80:81], v[76:79], off offset:512
	global_store_dwordx4 v[80:81], v[72:75], off offset:528
	s_nop 1
	v_lshl_add_u64 v[72:73], s[22:23], 0, v[144:145]
	v_lshl_add_u64 v[72:73], v[72:73], 0, v[136:137]
	global_store_dwordx4 v[72:73], v[92:95], off
	global_store_dwordx4 v[72:73], v[84:87], off offset:16
	global_store_dwordx4 v[72:73], v[68:71], off offset:512
	global_store_dwordx4 v[72:73], v[64:67], off offset:528
	s_nop 1
	v_lshl_add_u64 v[64:65], s[22:23], 0, v[146:147]
	v_lshl_add_u64 v[64:65], v[64:65], 0, v[136:137]
	global_store_dwordx4 v[64:65], v[60:63], off
	global_store_dwordx4 v[64:65], v[56:59], off offset:16
	global_store_dwordx4 v[64:65], v[36:39], off offset:512
	global_store_dwordx4 v[64:65], v[32:35], off offset:528
	s_nop 1
	v_lshl_add_u64 v[32:33], s[22:23], 0, v[148:149]
	v_lshl_add_u64 v[32:33], v[32:33], 0, v[136:137]
	global_store_dwordx4 v[32:33], v[52:55], off
	global_store_dwordx4 v[32:33], v[48:51], off offset:16
	global_store_dwordx4 v[32:33], v[20:23], off offset:512
	global_store_dwordx4 v[32:33], v[16:19], off offset:528
	s_nop 1
	v_lshl_add_u64 v[16:17], s[22:23], 0, v[150:151]
	v_lshl_add_u64 v[16:17], v[16:17], 0, v[136:137]
	global_store_dwordx4 v[16:17], v[44:47], off
	global_store_dwordx4 v[16:17], v[40:43], off offset:16
	global_store_dwordx4 v[16:17], v[12:15], off offset:512
	global_store_dwordx4 v[16:17], v[8:11], off offset:528
	s_nop 1
	v_lshl_add_u64 v[8:9], s[22:23], 0, v[152:153]
	v_lshl_add_u64 v[8:9], v[8:9], 0, v[136:137]
	s_mov_b64 s[22:23], s[14:15]
	global_store_dwordx4 v[8:9], v[28:31], off
	global_store_dwordx4 v[8:9], v[24:27], off offset:16
	global_store_dwordx4 v[8:9], v[4:7], off offset:512
	global_store_dwordx4 v[8:9], v[0:3], off offset:528
	s_cbranch_vccz .LBB0_606
	s_waitcnt vmcnt(0)
	s_cmpk_gt_u32 s18, 0xff
	s_cbranch_scc1 .LBB0_616
	s_barrier

.LBB0_730:
	s_ashr_i32 s45, s44, 31
	s_nop 0
	s_lshl_b64 s[56:57], s[44:45], 17
	v_readlane_b32 s68, v252, 15
	v_readlane_b32 s69, v252, 16
	s_add_u32 s56, s68, s56
	v_add_u32_e32 v157, s53, v154
	s_addc_u32 s57, s69, s57
	ds_read_b128 v[0:3], v157
	ds_read_b128 v[4:7], v157 offset:1024
	s_waitcnt lgkmcnt(0)
	ds_read_b128 v[8:11], v157 offset:2048
	ds_read_b128 v[12:15], v157 offset:3072
	s_nop 7
	s_nop 3
	s_and_b64 s[58:59], s[54:55], exec
	s_cselect_b32 s63, s57, s7
	s_cselect_b32 s62, s56, s6
	s_ashr_i32 s43, s42, 31
	s_nop 0
	s_lshl_b64 s[58:59], s[42:43], 17
	v_readlane_b32 s70, v253, 61
	v_readlane_b32 s71, v253, 62
	s_add_u32 s58, s70, s58
	s_nop 0
	s_addc_u32 s59, s71, s59
	s_and_b64 s[60:61], s[54:55], exec
	s_nop 7
	s_nop 4
	s_cselect_b32 s61, s59, s11
	s_cselect_b32 s60, s58, s10
	s_add_u32 vcc_lo, s6, 0x10080
	s_addc_u32 vcc_hi, s7, 0
	s_mov_b32 m0, s14
	s_waitcnt vmcnt(0)
	v_lshl_add_u64 v[48:49], vcc, 0, v[112:113]
	ds_read_b128 v[16:19], v155
	ds_read_b128 v[20:23], v155 offset:1024
	ds_read_b128 v[24:27], v155 offset:2048
	ds_read_b128 v[28:31], v155 offset:3072
	ds_read_b128 v[32:35], v155 offset:4096
	ds_read_b128 v[36:39], v155 offset:5120
	ds_read_b128 v[40:43], v155 offset:6144
	ds_read_b128 v[44:47], v155 offset:7168
	global_load_lds_dwordx4 v[48:49], off
	v_lshl_add_u64 v[48:49], vcc, 0, v[116:117]
	s_mov_b32 m0, s92
	s_nop 0
	global_load_lds_dwordx4 v[48:49], off
	s_waitcnt lgkmcnt(8)
	s_barrier
	s_waitcnt lgkmcnt(0)
	s_setprio 1
	v_mfma_f32_16x16x32_bf16 v[48:51], v[0:3], v[16:19], 0
	v_mfma_f32_16x16x32_bf16 v[16:19], v[8:11], v[16:19], 0
	v_mfma_f32_16x16x32_bf16 v[48:51], v[4:7], v[20:23], v[48:51]
	v_mfma_f32_16x16x32_bf16 v[16:19], v[12:15], v[20:23], v[16:19]
	v_mfma_f32_16x16x32_bf16 v[20:23], v[0:3], v[24:27], 0
	v_mfma_f32_16x16x32_bf16 v[24:27], v[8:11], v[24:27], 0
	v_mfma_f32_16x16x32_bf16 v[20:23], v[4:7], v[28:31], v[20:23]
	v_mfma_f32_16x16x32_bf16 v[24:27], v[12:15], v[28:31], v[24:27]
	v_mfma_f32_16x16x32_bf16 v[28:31], v[0:3], v[32:35], 0
	v_mfma_f32_16x16x32_bf16 v[32:35], v[8:11], v[32:35], 0
	v_mfma_f32_16x16x32_bf16 v[28:31], v[4:7], v[36:39], v[28:31]
	v_mfma_f32_16x16x32_bf16 v[32:35], v[12:15], v[36:39], v[32:35]
	v_mfma_f32_16x16x32_bf16 v[36:39], v[0:3], v[40:43], 0
	v_mfma_f32_16x16x32_bf16 v[40:43], v[8:11], v[40:43], 0
	v_mfma_f32_16x16x32_bf16 v[36:39], v[4:7], v[44:47], v[36:39]
	v_mfma_f32_16x16x32_bf16 v[40:43], v[12:15], v[44:47], v[40:43]
	s_setprio 0
	s_barrier
	v_lshl_add_u64 v[150:151], s[10:11], 0, v[114:115]
	s_mov_b32 m0, s93
	v_lshl_add_u64 v[44:45], v[150:151], 0, s[34:35]
	v_lshl_add_u64 v[152:153], s[10:11], 0, v[118:119]
	global_load_lds_dwordx4 v[44:45], off
	v_lshl_add_u64 v[44:45], v[152:153], 0, s[34:35]
	s_mov_b32 m0, s94
	s_nop 0
	global_load_lds_dwordx4 v[44:45], off
	s_barrier
	s_waitcnt lgkmcnt(0)
	s_setprio 1
	s_setprio 0
	v_lshl_add_u64 v[158:159], s[6:7], 0, v[112:113]
	s_mov_b32 m0, s19
	v_lshl_add_u64 v[80:81], v[158:159], 0, s[34:35]
	v_lshl_add_u64 v[162:163], s[6:7], 0, v[116:117]
	s_barrier
	ds_read_b128 v[44:47], v155 offset:16384
	ds_read_b128 v[52:55], v155 offset:17408
	ds_read_b128 v[56:59], v155 offset:18432
	ds_read_b128 v[60:63], v155 offset:19456
	ds_read_b128 v[64:67], v155 offset:20480
	ds_read_b128 v[68:71], v155 offset:21504
	ds_read_b128 v[72:75], v155 offset:22528
	ds_read_b128 v[76:79], v155 offset:23552
	global_load_lds_dwordx4 v[80:81], off
	v_lshl_add_u64 v[80:81], v[162:163], 0, s[34:35]
	s_mov_b32 m0, s20
	s_nop 0
	global_load_lds_dwordx4 v[80:81], off
	s_barrier
	s_waitcnt lgkmcnt(0)
	s_setprio 1
	v_mfma_f32_16x16x32_bf16 v[80:83], v[0:3], v[44:47], 0
	v_mfma_f32_16x16x32_bf16 v[44:47], v[8:11], v[44:47], 0
	v_mfma_f32_16x16x32_bf16 v[80:83], v[4:7], v[52:55], v[80:83]
	v_mfma_f32_16x16x32_bf16 v[44:47], v[12:15], v[52:55], v[44:47]
	v_mfma_f32_16x16x32_bf16 v[52:55], v[0:3], v[56:59], 0
	v_mfma_f32_16x16x32_bf16 v[56:59], v[8:11], v[56:59], 0
	v_mfma_f32_16x16x32_bf16 v[52:55], v[4:7], v[60:63], v[52:55]
	v_mfma_f32_16x16x32_bf16 v[56:59], v[12:15], v[60:63], v[56:59]
	v_mfma_f32_16x16x32_bf16 v[60:63], v[0:3], v[64:67], 0
	v_mfma_f32_16x16x32_bf16 v[0:3], v[0:3], v[72:75], 0
	v_mfma_f32_16x16x32_bf16 v[60:63], v[4:7], v[68:71], v[60:63]
	v_mfma_f32_16x16x32_bf16 v[64:67], v[8:11], v[64:67], 0
	v_mfma_f32_16x16x32_bf16 v[0:3], v[4:7], v[76:79], v[0:3]
	v_mfma_f32_16x16x32_bf16 v[4:7], v[8:11], v[72:75], 0
	v_mfma_f32_16x16x32_bf16 v[64:67], v[12:15], v[68:71], v[64:67]
	v_mfma_f32_16x16x32_bf16 v[4:7], v[12:15], v[76:79], v[4:7]
	s_setprio 0
	s_barrier
	s_add_u32 vcc_lo, s10, 0x10100
	s_addc_u32 vcc_hi, s11, 0
	s_mov_b32 m0, s21
	v_lshl_add_u64 v[8:9], vcc, 0, v[114:115]
	global_load_lds_dwordx4 v[8:9], off
	v_lshl_add_u64 v[8:9], vcc, 0, v[118:119]
	s_mov_b32 m0, s26
	s_nop 0
	global_load_lds_dwordx4 v[8:9], off
	s_waitcnt vmcnt(6)
	s_barrier
	s_setprio 1
	s_setprio 0
	v_add_u32_e32 v161, s96, v154
	s_barrier
	ds_read_b128 v[8:11], v161
	ds_read_b128 v[12:15], v161 offset:1024
	ds_read_b128 v[68:71], v161 offset:2048
	ds_read_b128 v[72:75], v161 offset:3072
	s_add_u32 vcc_lo, s6, 0x10100
	s_addc_u32 vcc_hi, s7, 0
	s_mov_b32 m0, s27
	v_lshl_add_u64 v[164:165], vcc, 0, v[112:113]
	ds_read_b128 v[76:79], v155 offset:32768
	ds_read_b128 v[84:87], v155 offset:33792
	ds_read_b128 v[88:91], v155 offset:34816
	ds_read_b128 v[92:95], v155 offset:35840
	ds_read_b128 v[96:99], v155 offset:36864
	ds_read_b128 v[100:103], v155 offset:37888
	ds_read_b128 v[104:107], v155 offset:38912
	ds_read_b128 v[108:111], v155 offset:39936
	global_load_lds_dwordx4 v[164:165], off
	v_lshl_add_u64 v[164:165], vcc, 0, v[116:117]
	s_mov_b32 m0, s28
	s_nop 0
	global_load_lds_dwordx4 v[164:165], off
	s_waitcnt lgkmcnt(8)
	s_barrier
	s_waitcnt lgkmcnt(0)
	s_setprio 1
	v_mfma_f32_16x16x32_bf16 v[48:51], v[8:11], v[76:79], v[48:51]
	v_mfma_f32_16x16x32_bf16 v[16:19], v[68:71], v[76:79], v[16:19]
	v_mfma_f32_16x16x32_bf16 v[20:23], v[8:11], v[88:91], v[20:23]
	v_mfma_f32_16x16x32_bf16 v[24:27], v[68:71], v[88:91], v[24:27]
	v_mfma_f32_16x16x32_bf16 v[28:31], v[8:11], v[96:99], v[28:31]
	v_mfma_f32_16x16x32_bf16 v[32:35], v[68:71], v[96:99], v[32:35]
	v_mfma_f32_16x16x32_bf16 v[36:39], v[8:11], v[104:107], v[36:39]
	v_mfma_f32_16x16x32_bf16 v[40:43], v[68:71], v[104:107], v[40:43]
	v_mfma_f32_16x16x32_bf16 v[48:51], v[12:15], v[84:87], v[48:51]
	v_mfma_f32_16x16x32_bf16 v[16:19], v[72:75], v[84:87], v[16:19]
	v_mfma_f32_16x16x32_bf16 v[20:23], v[12:15], v[92:95], v[20:23]
	v_mfma_f32_16x16x32_bf16 v[24:27], v[72:75], v[92:95], v[24:27]
	v_mfma_f32_16x16x32_bf16 v[28:31], v[12:15], v[100:103], v[28:31]
	v_mfma_f32_16x16x32_bf16 v[32:35], v[72:75], v[100:103], v[32:35]
	v_mfma_f32_16x16x32_bf16 v[36:39], v[12:15], v[108:111], v[36:39]
	v_mfma_f32_16x16x32_bf16 v[40:43], v[72:75], v[108:111], v[40:43]
	s_setprio 0
	s_barrier
	s_mov_b32 m0, s97
	v_lshl_add_u64 v[76:77], v[150:151], 0, s[40:41]
	global_load_lds_dwordx4 v[76:77], off
	v_lshl_add_u64 v[76:77], v[152:153], 0, s[40:41]
	s_mov_b32 m0, s18
	s_nop 0
	global_load_lds_dwordx4 v[76:77], off
	s_barrier
	s_waitcnt lgkmcnt(0)
	s_setprio 1
	s_setprio 0
	s_mov_b32 m0, s29
	v_lshl_add_u64 v[150:151], v[158:159], 0, s[40:41]
	s_barrier
	ds_read_b128 v[76:79], v155 offset:49152
	ds_read_b128 v[84:87], v155 offset:50176
	ds_read_b128 v[88:91], v155 offset:51200
	ds_read_b128 v[92:95], v155 offset:52224
	ds_read_b128 v[96:99], v155 offset:53248
	ds_read_b128 v[100:103], v155 offset:54272
	ds_read_b128 v[104:107], v155 offset:55296
	ds_read_b128 v[108:111], v155 offset:56320
	global_load_lds_dwordx4 v[150:151], off
	v_lshl_add_u64 v[150:151], v[162:163], 0, s[40:41]
	s_mov_b32 m0, s30
	s_nop 0
	global_load_lds_dwordx4 v[150:151], off
	s_barrier
	s_waitcnt lgkmcnt(0)
	s_setprio 1
	v_mfma_f32_16x16x32_bf16 v[80:83], v[8:11], v[76:79], v[80:83]
	v_mfma_f32_16x16x32_bf16 v[44:47], v[68:71], v[76:79], v[44:47]
	v_mfma_f32_16x16x32_bf16 v[52:55], v[8:11], v[88:91], v[52:55]
	v_mfma_f32_16x16x32_bf16 v[56:59], v[68:71], v[88:91], v[56:59]
	v_mfma_f32_16x16x32_bf16 v[60:63], v[8:11], v[96:99], v[60:63]
	v_mfma_f32_16x16x32_bf16 v[64:67], v[68:71], v[96:99], v[64:67]
	v_mfma_f32_16x16x32_bf16 v[0:3], v[8:11], v[104:107], v[0:3]
	v_mfma_f32_16x16x32_bf16 v[4:7], v[68:71], v[104:107], v[4:7]
	v_mfma_f32_16x16x32_bf16 v[80:83], v[12:15], v[84:87], v[80:83]
	v_mfma_f32_16x16x32_bf16 v[44:47], v[72:75], v[84:87], v[44:47]
	v_mfma_f32_16x16x32_bf16 v[52:55], v[12:15], v[92:95], v[52:55]
	v_mfma_f32_16x16x32_bf16 v[56:59], v[72:75], v[92:95], v[56:59]
	v_mfma_f32_16x16x32_bf16 v[60:63], v[12:15], v[100:103], v[60:63]
	v_mfma_f32_16x16x32_bf16 v[64:67], v[72:75], v[100:103], v[64:67]
	v_mfma_f32_16x16x32_bf16 v[0:3], v[12:15], v[108:111], v[0:3]
	v_mfma_f32_16x16x32_bf16 v[4:7], v[72:75], v[108:111], v[4:7]
	s_setprio 0
	s_barrier
	s_add_u32 s10, s10, 0x10180
	s_addc_u32 s11, s11, 0
	s_mov_b32 m0, s31
	v_lshl_add_u64 v[8:9], s[10:11], 0, v[114:115]
	global_load_lds_dwordx4 v[8:9], off
	v_lshl_add_u64 v[8:9], s[10:11], 0, v[118:119]
	s_mov_b32 m0, s33
	s_nop 0
	global_load_lds_dwordx4 v[8:9], off
	s_waitcnt vmcnt(6)
	s_barrier
	s_setprio 1
	s_setprio 0
	s_barrier
	ds_read_b128 v[8:11], v157
	ds_read_b128 v[12:15], v157 offset:1024
	ds_read_b128 v[68:71], v157 offset:2048
	ds_read_b128 v[72:75], v157 offset:3072
	s_add_u32 s6, s6, 0x10180
	s_addc_u32 s7, s7, 0
	s_mov_b32 m0, s14
	v_lshl_add_u64 v[150:151], s[6:7], 0, v[112:113]
	ds_read_b128 v[76:79], v155
	ds_read_b128 v[84:87], v155 offset:1024
	ds_read_b128 v[88:91], v155 offset:2048
	ds_read_b128 v[92:95], v155 offset:3072
	ds_read_b128 v[96:99], v155 offset:4096
	ds_read_b128 v[100:103], v155 offset:5120
	ds_read_b128 v[104:107], v155 offset:6144
	ds_read_b128 v[108:111], v155 offset:7168
	global_load_lds_dwordx4 v[150:151], off
	v_lshl_add_u64 v[150:151], s[6:7], 0, v[116:117]
	s_mov_b32 m0, s92
	s_nop 0
	global_load_lds_dwordx4 v[150:151], off
	s_waitcnt lgkmcnt(8)
	s_barrier
	s_waitcnt lgkmcnt(0)
	s_setprio 1
	v_mfma_f32_16x16x32_bf16 v[48:51], v[8:11], v[76:79], v[48:51]
	v_mfma_f32_16x16x32_bf16 v[16:19], v[68:71], v[76:79], v[16:19]
	v_mfma_f32_16x16x32_bf16 v[20:23], v[8:11], v[88:91], v[20:23]
	v_mfma_f32_16x16x32_bf16 v[24:27], v[68:71], v[88:91], v[24:27]
	v_mfma_f32_16x16x32_bf16 v[28:31], v[8:11], v[96:99], v[28:31]
	v_mfma_f32_16x16x32_bf16 v[32:35], v[68:71], v[96:99], v[32:35]
	v_mfma_f32_16x16x32_bf16 v[36:39], v[8:11], v[104:107], v[36:39]
	v_mfma_f32_16x16x32_bf16 v[40:43], v[68:71], v[104:107], v[40:43]
	v_mfma_f32_16x16x32_bf16 v[48:51], v[12:15], v[84:87], v[48:51]
	v_mfma_f32_16x16x32_bf16 v[16:19], v[72:75], v[84:87], v[16:19]
	v_mfma_f32_16x16x32_bf16 v[20:23], v[12:15], v[92:95], v[20:23]
	v_mfma_f32_16x16x32_bf16 v[24:27], v[72:75], v[92:95], v[24:27]
	v_mfma_f32_16x16x32_bf16 v[28:31], v[12:15], v[100:103], v[28:31]
	v_mfma_f32_16x16x32_bf16 v[32:35], v[72:75], v[100:103], v[32:35]
	v_mfma_f32_16x16x32_bf16 v[36:39], v[12:15], v[108:111], v[36:39]
	v_mfma_f32_16x16x32_bf16 v[40:43], v[72:75], v[108:111], v[40:43]
	s_setprio 0
	s_barrier
	s_mov_b32 m0, s93
	v_lshl_add_u64 v[158:159], s[60:61], 0, v[114:115]
	global_load_lds_dwordx4 v[158:159], off
	v_lshl_add_u64 v[170:171], s[60:61], 0, v[118:119]
	s_mov_b32 m0, s94
	s_nop 0
	global_load_lds_dwordx4 v[170:171], off
	s_barrier
	s_waitcnt lgkmcnt(0)
	s_setprio 1
	s_setprio 0
	s_mov_b32 m0, s19
	v_lshl_add_u64 v[172:173], s[62:63], 0, v[112:113]
	s_barrier
	ds_read_b128 v[76:79], v155 offset:16384
	ds_read_b128 v[84:87], v155 offset:17408
	ds_read_b128 v[88:91], v155 offset:18432
	ds_read_b128 v[92:95], v155 offset:19456
	ds_read_b128 v[96:99], v155 offset:20480
	ds_read_b128 v[100:103], v155 offset:21504
	ds_read_b128 v[104:107], v155 offset:22528
	ds_read_b128 v[108:111], v155 offset:23552
	global_load_lds_dwordx4 v[172:173], off
	v_lshl_add_u64 v[176:177], s[62:63], 0, v[116:117]
	s_mov_b32 m0, s20
	s_nop 0
	global_load_lds_dwordx4 v[176:177], off
	s_barrier
	s_waitcnt lgkmcnt(0)
	s_setprio 1
	v_mfma_f32_16x16x32_bf16 v[52:55], v[8:11], v[88:91], v[52:55]
	v_mfma_f32_16x16x32_bf16 v[80:83], v[8:11], v[76:79], v[80:83]
	v_mfma_f32_16x16x32_bf16 v[44:47], v[68:71], v[76:79], v[44:47]
	v_mfma_f32_16x16x32_bf16 v[76:79], v[12:15], v[92:95], v[52:55]
	v_mfma_f32_16x16x32_bf16 v[52:55], v[68:71], v[88:91], v[56:59]
	v_mfma_f32_16x16x32_bf16 v[56:59], v[72:75], v[92:95], v[52:55]
	v_mfma_f32_16x16x32_bf16 v[52:55], v[8:11], v[96:99], v[60:63]
	v_mfma_f32_16x16x32_bf16 v[60:63], v[12:15], v[100:103], v[52:55]
	v_mfma_f32_16x16x32_bf16 v[52:55], v[68:71], v[96:99], v[64:67]
	v_mfma_f32_16x16x32_bf16 v[0:3], v[8:11], v[104:107], v[0:3]
	v_mfma_f32_16x16x32_bf16 v[4:7], v[68:71], v[104:107], v[4:7]
	v_mfma_f32_16x16x32_bf16 v[80:83], v[12:15], v[84:87], v[80:83]
	v_mfma_f32_16x16x32_bf16 v[44:47], v[72:75], v[84:87], v[44:47]
	v_mfma_f32_16x16x32_bf16 v[64:67], v[72:75], v[100:103], v[52:55]
	v_mfma_f32_16x16x32_bf16 v[0:3], v[12:15], v[108:111], v[0:3]
	v_mfma_f32_16x16x32_bf16 v[4:7], v[72:75], v[108:111], v[4:7]
	s_setprio 0
	s_barrier
	s_add_u32 s6, s60, 0x10000
	s_addc_u32 s7, s61, 0
	s_mov_b32 m0, s21
	v_lshl_add_u64 v[8:9], s[6:7], 0, v[114:115]
	global_load_lds_dwordx4 v[8:9], off
	v_lshl_add_u64 v[8:9], s[6:7], 0, v[118:119]
	s_mov_b32 m0, s26
	s_nop 0
	global_load_lds_dwordx4 v[8:9], off
	s_waitcnt vmcnt(6)
	s_barrier
	s_setprio 1
	s_setprio 0
	s_barrier
	ds_read_b128 v[84:87], v161
	ds_read_b128 v[88:91], v161 offset:1024
	ds_read_b128 v[100:103], v161 offset:2048
	ds_read_b128 v[104:107], v161 offset:3072
	s_add_u32 s6, s62, 0x10000
	s_addc_u32 s7, s63, 0
	s_mov_b32 m0, s27
	v_lshl_add_u64 v[68:69], s[6:7], 0, v[112:113]
	ds_read_b128 v[8:11], v155 offset:32768
	ds_read_b128 v[12:15], v155 offset:33792
	ds_read_b128 v[52:55], v155 offset:34816
	ds_read_b128 v[72:75], v155 offset:35840
	ds_read_b128 v[108:111], v155 offset:36864
	ds_read_b128 v[150:153], v155 offset:37888
	ds_read_b128 v[162:165], v155 offset:38912
	ds_read_b128 v[166:169], v155 offset:39936
	global_load_lds_dwordx4 v[68:69], off
	v_lshl_add_u64 v[68:69], s[6:7], 0, v[116:117]
	s_mov_b32 m0, s28
	s_nop 0
	global_load_lds_dwordx4 v[68:69], off
	s_waitcnt lgkmcnt(8)
	s_barrier
	s_waitcnt lgkmcnt(0)
	s_setprio 1
	v_mfma_f32_16x16x32_bf16 v[48:51], v[84:87], v[8:11], v[48:51]
	v_mfma_f32_16x16x32_bf16 v[8:11], v[100:103], v[8:11], v[16:19]
	v_mfma_f32_16x16x32_bf16 v[96:99], v[104:107], v[12:15], v[8:11]
	v_mfma_f32_16x16x32_bf16 v[8:11], v[84:87], v[52:55], v[20:23]
	v_mfma_f32_16x16x32_bf16 v[68:71], v[88:91], v[72:75], v[8:11]
	v_mfma_f32_16x16x32_bf16 v[8:11], v[100:103], v[52:55], v[24:27]
	v_mfma_f32_16x16x32_bf16 v[72:75], v[104:107], v[72:75], v[8:11]
	v_mfma_f32_16x16x32_bf16 v[8:11], v[84:87], v[108:111], v[28:31]
	v_mfma_f32_16x16x32_bf16 v[92:95], v[88:91], v[12:15], v[48:51]
	v_mfma_f32_16x16x32_bf16 v[48:51], v[88:91], v[150:153], v[8:11]
	v_mfma_f32_16x16x32_bf16 v[8:11], v[100:103], v[108:111], v[32:35]
	v_mfma_f32_16x16x32_bf16 v[52:55], v[104:107], v[150:153], v[8:11]
	v_mfma_f32_16x16x32_bf16 v[8:11], v[84:87], v[162:165], v[36:39]
	v_mfma_f32_16x16x32_bf16 v[32:35], v[88:91], v[166:169], v[8:11]
	v_mfma_f32_16x16x32_bf16 v[8:11], v[100:103], v[162:165], v[40:43]
	v_mfma_f32_16x16x32_bf16 v[36:39], v[104:107], v[166:169], v[8:11]
	s_setprio 0
	s_barrier
	s_mov_b32 m0, s97
	s_nop 3
	v_lshl_add_u64 v[8:9], v[158:159], 0, s[16:17]
	global_load_lds_dwordx4 v[8:9], off
	v_lshl_add_u64 v[8:9], v[170:171], 0, s[16:17]
	s_mov_b32 m0, s18
	s_nop 0
	global_load_lds_dwordx4 v[8:9], off
	s_barrier
	s_waitcnt lgkmcnt(0)
	s_setprio 1
	s_setprio 0
	s_mov_b32 m0, s29
	v_lshl_add_u64 v[16:17], v[172:173], 0, s[16:17]
	s_barrier
	ds_read_b128 v[8:11], v155 offset:49152
	ds_read_b128 v[12:15], v155 offset:50176
	ds_read_b128 v[20:23], v155 offset:51200
	ds_read_b128 v[40:43], v155 offset:52224
	ds_read_b128 v[108:111], v155 offset:53248
	ds_read_b128 v[150:153], v155 offset:54272
	ds_read_b128 v[162:165], v155 offset:55296
	ds_read_b128 v[166:169], v155 offset:56320
	global_load_lds_dwordx4 v[16:17], off
	v_lshl_add_u64 v[16:17], v[176:177], 0, s[16:17]
	s_mov_b32 m0, s30
	s_nop 0
	global_load_lds_dwordx4 v[16:17], off
	s_barrier
	s_waitcnt lgkmcnt(0)
	s_setprio 1
	v_mfma_f32_16x16x32_bf16 v[16:19], v[84:87], v[8:11], v[80:83]
	v_mfma_f32_16x16x32_bf16 v[8:11], v[100:103], v[8:11], v[44:47]
	v_mfma_f32_16x16x32_bf16 v[28:31], v[104:107], v[12:15], v[8:11]
	v_mfma_f32_16x16x32_bf16 v[8:11], v[84:87], v[20:23], v[76:79]
	v_mfma_f32_16x16x32_bf16 v[24:27], v[88:91], v[12:15], v[16:19]
	v_mfma_f32_16x16x32_bf16 v[16:19], v[88:91], v[40:43], v[8:11]
	v_mfma_f32_16x16x32_bf16 v[8:11], v[100:103], v[20:23], v[56:59]
	v_mfma_f32_16x16x32_bf16 v[20:23], v[104:107], v[40:43], v[8:11]
	v_mfma_f32_16x16x32_bf16 v[8:11], v[84:87], v[108:111], v[60:63]
	v_mfma_f32_16x16x32_bf16 v[12:15], v[100:103], v[108:111], v[64:67]
	v_mfma_f32_16x16x32_bf16 v[0:3], v[84:87], v[162:165], v[0:3]
	v_mfma_f32_16x16x32_bf16 v[4:7], v[100:103], v[162:165], v[4:7]
	v_mfma_f32_16x16x32_bf16 v[8:11], v[88:91], v[150:153], v[8:11]
	v_mfma_f32_16x16x32_bf16 v[12:15], v[104:107], v[150:153], v[12:15]
	v_mfma_f32_16x16x32_bf16 v[0:3], v[88:91], v[166:169], v[0:3]
	v_mfma_f32_16x16x32_bf16 v[4:7], v[104:107], v[166:169], v[4:7]
	s_setprio 0
	s_barrier
	s_add_u32 s6, s60, 0x10080
	s_addc_u32 s7, s61, 0
	s_mov_b32 m0, s31
	v_lshl_add_u64 v[40:41], s[6:7], 0, v[114:115]
	global_load_lds_dwordx4 v[40:41], off
	v_lshl_add_u64 v[40:41], s[6:7], 0, v[118:119]
	s_mov_b32 m0, s33
	s_nop 0
	global_load_lds_dwordx4 v[40:41], off
	s_waitcnt vmcnt(6)
	s_barrier
	s_setprio 1
	s_setprio 0
	s_barrier
	global_load_dwordx4 v[88:91], v[136:137], off offset:48
	global_load_dwordx4 v[100:103], v[136:137], off offset:32
	global_load_dwordx4 v[104:107], v[136:137], off offset:16
	global_load_dwordx4 v[108:111], v[136:137], off
	global_load_dwordx4 v[64:67], v[138:139], off offset:48
	global_load_dwordx4 v[76:79], v[138:139], off offset:32
	global_load_dwordx4 v[80:83], v[138:139], off offset:16
	global_load_dwordx4 v[84:87], v[138:139], off
	global_load_dwordx4 v[40:43], v[140:141], off offset:48
	global_load_dwordx4 v[44:47], v[140:141], off offset:32
	global_load_dwordx4 v[56:59], v[140:141], off offset:16
	global_load_dwordx4 v[60:63], v[140:141], off
	s_cmp_lt_u32 s8, 16
	s_cselect_b64 s[10:11], -1, 0
	s_and_b64 s[60:61], s[22:23], s[10:11]
	v_cndmask_b32_e64 v150, 0, 1, s[60:61]
	v_cmp_ne_u32_e64 s[6:7], 1, v150
	s_andn2_b64 vcc, exec, s[60:61]
	s_cbranch_vccnz .LBB0_734
	v_and_b32_e32 v151, 64, v156
	v_xor_b32_e32 v150, 16, v156
	v_add_u32_e32 v151, 64, v151
	v_cmp_lt_i32_e32 vcc, v150, v151
	s_nop 1
	v_cndmask_b32_e32 v150, v156, v150, vcc
	v_lshlrev_b32_e32 v157, 2, v150
	ds_bpermute_b32 v152, v157, v92
	ds_bpermute_b32 v150, v157, v96
	ds_bpermute_b32 v153, v157, v93
	ds_bpermute_b32 v151, v157, v97
	ds_bpermute_b32 v161, v157, v94
	ds_bpermute_b32 v158, v157, v98
	ds_bpermute_b32 v159, v157, v95
	ds_bpermute_b32 v157, v157, v99
	s_and_saveexec_b64 s[60:61], s[0:1]
	s_cbranch_execz .LBB0_733
	global_load_dwordx4 v[162:165], v[134:135], off offset:48
	global_load_dwordx4 v[166:169], v[134:135], off offset:32
	global_load_dwordx4 v[170:173], v[134:135], off offset:16
	global_load_dwordx4 v[180:183], v[134:135], off
	s_waitcnt lgkmcnt(0)
	v_pk_mul_f32 v[152:153], v[124:125], v[152:153]
	v_mul_f32_e32 v158, v124, v158
	v_mul_f32_e32 v161, v124, v161
	v_pk_mul_f32 v[150:151], v[124:125], v[150:151]
	s_waitcnt vmcnt(0)
	v_mul_f32_e32 v98, v98, v162
	v_mul_f32_e32 v158, v163, v158
	v_mul_f32_e32 v163, v124, v157
	v_mov_b32_e32 v177, v182
	v_mov_b32_e32 v182, v181
	v_mov_b32_e32 v176, v180
	v_pk_mul_f32 v[152:153], v[182:183], v[152:153]
	v_mul_f32_e32 v181, v124, v159
	v_mov_b32_e32 v180, v95
	v_mov_b32_e32 v162, v99
	v_pk_mul_f32 v[172:173], v[172:173], v[180:181]
	v_pk_fma_f32 v[92:93], v[92:93], v[176:177], v[152:153]
	v_mov_b32_e32 v153, v168
	v_mov_b32_e32 v168, v167
	v_pk_mul_f32 v[162:163], v[164:165], v[162:163]
	v_mul_f32_e32 v94, v94, v170
	v_mul_f32_e32 v170, v171, v161
	v_mov_b32_e32 v95, v172
	v_mov_b32_e32 v171, v173
	v_mov_b32_e32 v152, v166
	v_pk_mul_f32 v[150:151], v[168:169], v[150:151]
	v_mov_b32_e32 v99, v162
	v_mov_b32_e32 v159, v163
	v_pk_add_f32 v[94:95], v[94:95], v[170:171]
	v_pk_fma_f32 v[96:97], v[96:97], v[152:153], v[150:151]
	v_pk_add_f32 v[98:99], v[98:99], v[158:159]

.LBB0_1268:
	ds_read_b128 v[140:143], v149
	ds_read_b128 v[152:155], v149 offset:1024
	ds_read_b128 v[156:159], v149 offset:2048
	ds_read_b128 v[160:163], v149 offset:3072
	s_add_u32 s22, s10, 0xfffe0080
	s_addc_u32 s23, s11, -1
	s_cmp_eq_u32 s44, 4
	s_cselect_b32 s25, s13, s23
	s_cselect_b32 s24, s40, s22
	s_cselect_b32 s23, s15, s43
	s_cselect_b32 s22, s41, s42
	v_lshl_add_u64 v[144:145], s[10:11], 0, v[136:137]
	s_add_i32 m0, s1, 0xc000
	ds_read_b128 v[164:167], v150
	ds_read_b128 v[168:171], v150 offset:1024
	ds_read_b128 v[172:175], v150 offset:2048
	ds_read_b128 v[180:183], v150 offset:3072
	ds_read_b128 v[184:187], v150 offset:4096
	ds_read_b128 v[188:191], v150 offset:5120
	ds_read_b128 v[192:195], v150 offset:6144
	ds_read_b128 v[196:199], v150 offset:7168
	global_load_lds_dwordx4 v[144:145], off
	v_lshl_add_u64 v[144:145], s[10:11], 0, v[138:139]
	s_add_i32 m0, s1, 0xe000
	s_nop 0
	global_load_lds_dwordx4 v[144:145], off
	s_waitcnt lgkmcnt(8)
	s_barrier
	s_waitcnt lgkmcnt(0)
	s_setprio 1
	v_mfma_f32_16x16x32_bf16 v[124:127], v[140:143], v[164:167], v[124:127]
	v_mfma_f32_16x16x32_bf16 v[120:123], v[156:159], v[164:167], v[120:123]
	v_mfma_f32_16x16x32_bf16 v[112:115], v[140:143], v[172:175], v[112:115]
	v_mfma_f32_16x16x32_bf16 v[104:107], v[156:159], v[172:175], v[104:107]
	v_mfma_f32_16x16x32_bf16 v[96:99], v[140:143], v[184:187], v[96:99]
	v_mfma_f32_16x16x32_bf16 v[88:91], v[156:159], v[184:187], v[88:91]
	v_mfma_f32_16x16x32_bf16 v[80:83], v[140:143], v[192:195], v[80:83]
	v_mfma_f32_16x16x32_bf16 v[72:75], v[156:159], v[192:195], v[72:75]
	v_mfma_f32_16x16x32_bf16 v[124:127], v[152:155], v[168:171], v[124:127]
	v_mfma_f32_16x16x32_bf16 v[120:123], v[160:163], v[168:171], v[120:123]
	v_mfma_f32_16x16x32_bf16 v[112:115], v[152:155], v[180:183], v[112:115]
	v_mfma_f32_16x16x32_bf16 v[104:107], v[160:163], v[180:183], v[104:107]
	v_mfma_f32_16x16x32_bf16 v[96:99], v[152:155], v[188:191], v[96:99]
	v_mfma_f32_16x16x32_bf16 v[88:91], v[160:163], v[188:191], v[88:91]
	v_mfma_f32_16x16x32_bf16 v[80:83], v[152:155], v[196:199], v[80:83]
	v_mfma_f32_16x16x32_bf16 v[72:75], v[160:163], v[196:199], v[72:75]
	s_setprio 0
	s_barrier
	s_add_i32 s45, s35, s27
	v_lshl_add_u64 v[144:145], s[22:23], 0, v[132:133]
	s_mov_b32 m0, s45
	ds_read_b128 v[200:203], v151
	ds_read_b128 v[204:207], v151 offset:1024
	ds_read_b128 v[208:211], v151 offset:2048
	ds_read_b128 v[212:215], v151 offset:3072
	global_load_lds_dwordx4 v[144:145], off
	v_lshl_add_u64 v[176:177], s[22:23], 0, v[128:129]
	s_add_i32 m0, s45, 0x2000
	s_nop 0
	global_load_lds_dwordx4 v[176:177], off
	s_barrier
	s_waitcnt lgkmcnt(0)
	s_setprio 1
	v_mfma_f32_16x16x32_bf16 v[116:119], v[200:203], v[164:167], v[116:119]
	v_mfma_f32_16x16x32_bf16 v[108:111], v[208:211], v[164:167], v[108:111]
	v_mfma_f32_16x16x32_bf16 v[100:103], v[200:203], v[172:175], v[100:103]
	v_mfma_f32_16x16x32_bf16 v[92:95], v[208:211], v[172:175], v[92:95]
	v_mfma_f32_16x16x32_bf16 v[84:87], v[200:203], v[184:187], v[84:87]
	v_mfma_f32_16x16x32_bf16 v[76:79], v[208:211], v[184:187], v[76:79]
	v_mfma_f32_16x16x32_bf16 v[68:71], v[200:203], v[192:195], v[68:71]
	v_mfma_f32_16x16x32_bf16 v[64:67], v[208:211], v[192:195], v[64:67]
	v_mfma_f32_16x16x32_bf16 v[116:119], v[204:207], v[168:171], v[116:119]
	v_mfma_f32_16x16x32_bf16 v[108:111], v[212:215], v[168:171], v[108:111]
	v_mfma_f32_16x16x32_bf16 v[100:103], v[204:207], v[180:183], v[100:103]
	v_mfma_f32_16x16x32_bf16 v[92:95], v[212:215], v[180:183], v[92:95]
	v_mfma_f32_16x16x32_bf16 v[84:87], v[204:207], v[188:191], v[84:87]
	v_mfma_f32_16x16x32_bf16 v[76:79], v[212:215], v[188:191], v[76:79]
	v_mfma_f32_16x16x32_bf16 v[68:71], v[204:207], v[196:199], v[68:71]
	v_mfma_f32_16x16x32_bf16 v[64:67], v[212:215], v[196:199], v[64:67]
	s_setprio 0
	s_mov_b32 m0, s1
	v_lshl_add_u64 v[216:217], s[24:25], 0, v[134:135]
	s_barrier
	ds_read_b128 v[164:167], v150 offset:16384
	ds_read_b128 v[168:171], v150 offset:17408
	ds_read_b128 v[172:175], v150 offset:18432
	ds_read_b128 v[180:183], v150 offset:19456
	ds_read_b128 v[184:187], v150 offset:20480
	ds_read_b128 v[188:191], v150 offset:21504
	ds_read_b128 v[192:195], v150 offset:22528
	ds_read_b128 v[196:199], v150 offset:23552
	global_load_lds_dwordx4 v[216:217], off
	v_lshl_add_u64 v[218:219], s[24:25], 0, v[130:131]
	s_mov_b32 m0, s7
	s_nop 0
	global_load_lds_dwordx4 v[218:219], off
	s_barrier
	s_waitcnt lgkmcnt(0)
	s_setprio 1
	v_mfma_f32_16x16x32_bf16 v[60:63], v[140:143], v[164:167], v[60:63]
	v_mfma_f32_16x16x32_bf16 v[56:59], v[156:159], v[164:167], v[56:59]
	v_mfma_f32_16x16x32_bf16 v[48:51], v[140:143], v[172:175], v[48:51]
	v_mfma_f32_16x16x32_bf16 v[40:43], v[156:159], v[172:175], v[40:43]
	v_mfma_f32_16x16x32_bf16 v[32:35], v[140:143], v[184:187], v[32:35]
	v_mfma_f32_16x16x32_bf16 v[24:27], v[156:159], v[184:187], v[24:27]
	v_mfma_f32_16x16x32_bf16 v[16:19], v[140:143], v[192:195], v[16:19]
	v_mfma_f32_16x16x32_bf16 v[8:11], v[156:159], v[192:195], v[8:11]
	v_mfma_f32_16x16x32_bf16 v[60:63], v[152:155], v[168:171], v[60:63]
	v_mfma_f32_16x16x32_bf16 v[56:59], v[160:163], v[168:171], v[56:59]
	v_mfma_f32_16x16x32_bf16 v[48:51], v[152:155], v[180:183], v[48:51]
	v_mfma_f32_16x16x32_bf16 v[40:43], v[160:163], v[180:183], v[40:43]
	v_mfma_f32_16x16x32_bf16 v[32:35], v[152:155], v[188:191], v[32:35]
	v_mfma_f32_16x16x32_bf16 v[24:27], v[160:163], v[188:191], v[24:27]
	v_mfma_f32_16x16x32_bf16 v[16:19], v[152:155], v[196:199], v[16:19]
	v_mfma_f32_16x16x32_bf16 v[8:11], v[160:163], v[196:199], v[8:11]
	s_setprio 0
	s_barrier
	s_add_u32 s46, s22, 0x20000
	s_addc_u32 s47, s23, 0
	s_add_i32 s45, s36, s27
	v_lshl_add_u64 v[140:141], s[46:47], 0, v[132:133]
	s_mov_b32 m0, s45
	s_nop 0
	global_load_lds_dwordx4 v[140:141], off
	v_lshl_add_u64 v[140:141], s[46:47], 0, v[128:129]
	s_add_i32 m0, s45, 0x2000
	s_nop 0
	global_load_lds_dwordx4 v[140:141], off
	s_waitcnt vmcnt(6)
	s_barrier
	s_setprio 1
	v_mfma_f32_16x16x32_bf16 v[52:55], v[200:203], v[164:167], v[52:55]
	v_mfma_f32_16x16x32_bf16 v[44:47], v[208:211], v[164:167], v[44:47]
	v_mfma_f32_16x16x32_bf16 v[36:39], v[200:203], v[172:175], v[36:39]
	v_mfma_f32_16x16x32_bf16 v[28:31], v[208:211], v[172:175], v[28:31]
	v_mfma_f32_16x16x32_bf16 v[20:23], v[200:203], v[184:187], v[20:23]
	v_mfma_f32_16x16x32_bf16 v[12:15], v[208:211], v[184:187], v[12:15]
	v_mfma_f32_16x16x32_bf16 v[4:7], v[200:203], v[192:195], v[4:7]
	v_mfma_f32_16x16x32_bf16 v[0:3], v[208:211], v[192:195], v[0:3]
	v_mfma_f32_16x16x32_bf16 v[52:55], v[204:207], v[168:171], v[52:55]
	v_mfma_f32_16x16x32_bf16 v[44:47], v[212:215], v[168:171], v[44:47]
	v_mfma_f32_16x16x32_bf16 v[36:39], v[204:207], v[180:183], v[36:39]
	v_mfma_f32_16x16x32_bf16 v[28:31], v[212:215], v[180:183], v[28:31]
	v_mfma_f32_16x16x32_bf16 v[20:23], v[204:207], v[188:191], v[20:23]
	v_mfma_f32_16x16x32_bf16 v[12:15], v[212:215], v[188:191], v[12:15]
	v_mfma_f32_16x16x32_bf16 v[4:7], v[204:207], v[196:199], v[4:7]
	v_mfma_f32_16x16x32_bf16 v[0:3], v[212:215], v[196:199], v[0:3]
	s_setprio 0
	s_add_i32 s45, 0, 0x18000
	v_add_u32_e32 v160, s45, v147
	s_barrier
	ds_read_b128 v[140:143], v160
	ds_read_b128 v[152:155], v160 offset:1024
	ds_read_b128 v[156:159], v160 offset:2048
	ds_read_b128 v[160:163], v160 offset:3072
	s_add_u32 s24, s24, 0x20000
	s_addc_u32 s25, s25, 0
	s_mov_b32 m0, s28
	v_lshl_add_u64 v[200:201], s[24:25], 0, v[134:135]
	ds_read_b128 v[164:167], v150 offset:32768
	ds_read_b128 v[168:171], v150 offset:33792
	ds_read_b128 v[172:175], v150 offset:34816
	ds_read_b128 v[180:183], v150 offset:35840
	ds_read_b128 v[184:187], v150 offset:36864
	ds_read_b128 v[188:191], v150 offset:37888
	ds_read_b128 v[192:195], v150 offset:38912
	ds_read_b128 v[196:199], v150 offset:39936
	global_load_lds_dwordx4 v[200:201], off
	v_lshl_add_u64 v[200:201], s[24:25], 0, v[130:131]
	s_mov_b32 m0, s29
	s_nop 0
	global_load_lds_dwordx4 v[200:201], off
	s_waitcnt lgkmcnt(8)
	s_barrier
	s_waitcnt lgkmcnt(0)
	s_setprio 1
	v_mfma_f32_16x16x32_bf16 v[124:127], v[140:143], v[164:167], v[124:127]
	v_mfma_f32_16x16x32_bf16 v[120:123], v[156:159], v[164:167], v[120:123]
	v_mfma_f32_16x16x32_bf16 v[112:115], v[140:143], v[172:175], v[112:115]
	v_mfma_f32_16x16x32_bf16 v[104:107], v[156:159], v[172:175], v[104:107]
	v_mfma_f32_16x16x32_bf16 v[96:99], v[140:143], v[184:187], v[96:99]
	v_mfma_f32_16x16x32_bf16 v[88:91], v[156:159], v[184:187], v[88:91]
	v_mfma_f32_16x16x32_bf16 v[80:83], v[140:143], v[192:195], v[80:83]
	v_mfma_f32_16x16x32_bf16 v[72:75], v[156:159], v[192:195], v[72:75]
	v_mfma_f32_16x16x32_bf16 v[124:127], v[152:155], v[168:171], v[124:127]
	v_mfma_f32_16x16x32_bf16 v[120:123], v[160:163], v[168:171], v[120:123]
	v_mfma_f32_16x16x32_bf16 v[112:115], v[152:155], v[180:183], v[112:115]
	v_mfma_f32_16x16x32_bf16 v[104:107], v[160:163], v[180:183], v[104:107]
	v_mfma_f32_16x16x32_bf16 v[96:99], v[152:155], v[188:191], v[96:99]
	v_mfma_f32_16x16x32_bf16 v[88:91], v[160:163], v[188:191], v[88:91]
	v_mfma_f32_16x16x32_bf16 v[80:83], v[152:155], v[196:199], v[80:83]
	v_mfma_f32_16x16x32_bf16 v[72:75], v[160:163], v[196:199], v[72:75]
	s_setprio 0
	s_barrier
	s_add_i32 s24, 0, 0x1c000
	s_add_i32 s25, s45, s27
	v_add_u32_e32 v179, s24, v147
	v_lshl_add_u64 v[144:145], v[144:145], 0, s[2:3]
	s_mov_b32 m0, s25
	ds_read_b128 v[200:203], v179
	ds_read_b128 v[204:207], v179 offset:1024
	ds_read_b128 v[208:211], v179 offset:2048
	ds_read_b128 v[212:215], v179 offset:3072
	global_load_lds_dwordx4 v[144:145], off
	v_lshl_add_u64 v[144:145], v[176:177], 0, s[2:3]
	s_add_i32 m0, s25, 0x2000
	s_nop 0
	global_load_lds_dwordx4 v[144:145], off
	s_barrier
	s_waitcnt lgkmcnt(0)
	s_setprio 1
	v_mfma_f32_16x16x32_bf16 v[116:119], v[200:203], v[164:167], v[116:119]
	v_mfma_f32_16x16x32_bf16 v[108:111], v[208:211], v[164:167], v[108:111]
	v_mfma_f32_16x16x32_bf16 v[100:103], v[200:203], v[172:175], v[100:103]
	v_mfma_f32_16x16x32_bf16 v[92:95], v[208:211], v[172:175], v[92:95]
	v_mfma_f32_16x16x32_bf16 v[84:87], v[200:203], v[184:187], v[84:87]
	v_mfma_f32_16x16x32_bf16 v[76:79], v[208:211], v[184:187], v[76:79]
	v_mfma_f32_16x16x32_bf16 v[68:71], v[200:203], v[192:195], v[68:71]
	v_mfma_f32_16x16x32_bf16 v[64:67], v[208:211], v[192:195], v[64:67]
	v_mfma_f32_16x16x32_bf16 v[116:119], v[204:207], v[168:171], v[116:119]
	v_mfma_f32_16x16x32_bf16 v[108:111], v[212:215], v[168:171], v[108:111]
	v_mfma_f32_16x16x32_bf16 v[100:103], v[204:207], v[180:183], v[100:103]
	v_mfma_f32_16x16x32_bf16 v[92:95], v[212:215], v[180:183], v[92:95]
	v_mfma_f32_16x16x32_bf16 v[84:87], v[204:207], v[188:191], v[84:87]
	v_mfma_f32_16x16x32_bf16 v[76:79], v[212:215], v[188:191], v[76:79]
	v_mfma_f32_16x16x32_bf16 v[68:71], v[204:207], v[196:199], v[68:71]
	v_mfma_f32_16x16x32_bf16 v[64:67], v[212:215], v[196:199], v[64:67]
	s_setprio 0
	s_mov_b32 m0, s31
	v_lshl_add_u64 v[144:145], v[216:217], 0, s[2:3]
	s_barrier
	ds_read_b128 v[164:167], v150 offset:49152
	ds_read_b128 v[168:171], v150 offset:50176
	ds_read_b128 v[172:175], v150 offset:51200
	ds_read_b128 v[180:183], v150 offset:52224
	ds_read_b128 v[184:187], v150 offset:53248
	ds_read_b128 v[188:191], v150 offset:54272
	ds_read_b128 v[192:195], v150 offset:55296
	ds_read_b128 v[196:199], v150 offset:56320
	global_load_lds_dwordx4 v[144:145], off
	v_lshl_add_u64 v[144:145], v[218:219], 0, s[2:3]
	s_mov_b32 m0, s33
	s_nop 0
	global_load_lds_dwordx4 v[144:145], off
	s_barrier
	s_waitcnt lgkmcnt(0)
	s_setprio 1
	v_mfma_f32_16x16x32_bf16 v[60:63], v[140:143], v[164:167], v[60:63]
	v_mfma_f32_16x16x32_bf16 v[56:59], v[156:159], v[164:167], v[56:59]
	v_mfma_f32_16x16x32_bf16 v[48:51], v[140:143], v[172:175], v[48:51]
	v_mfma_f32_16x16x32_bf16 v[40:43], v[156:159], v[172:175], v[40:43]
	v_mfma_f32_16x16x32_bf16 v[32:35], v[140:143], v[184:187], v[32:35]
	v_mfma_f32_16x16x32_bf16 v[24:27], v[156:159], v[184:187], v[24:27]
	v_mfma_f32_16x16x32_bf16 v[16:19], v[140:143], v[192:195], v[16:19]
	v_mfma_f32_16x16x32_bf16 v[8:11], v[156:159], v[192:195], v[8:11]
	v_mfma_f32_16x16x32_bf16 v[60:63], v[152:155], v[168:171], v[60:63]
	v_mfma_f32_16x16x32_bf16 v[56:59], v[160:163], v[168:171], v[56:59]
	v_mfma_f32_16x16x32_bf16 v[48:51], v[152:155], v[180:183], v[48:51]
	v_mfma_f32_16x16x32_bf16 v[40:43], v[160:163], v[180:183], v[40:43]
	v_mfma_f32_16x16x32_bf16 v[32:35], v[152:155], v[188:191], v[32:35]
	v_mfma_f32_16x16x32_bf16 v[24:27], v[160:163], v[188:191], v[24:27]
	v_mfma_f32_16x16x32_bf16 v[16:19], v[152:155], v[196:199], v[16:19]
	v_mfma_f32_16x16x32_bf16 v[8:11], v[160:163], v[196:199], v[8:11]
	s_setprio 0
	s_barrier
	s_add_u32 s22, s22, 0x20080
	s_addc_u32 s23, s23, 0
	s_add_i32 s24, s24, s27
	v_lshl_add_u64 v[140:141], s[22:23], 0, v[132:133]
	s_mov_b32 m0, s24
	s_nop 0
	global_load_lds_dwordx4 v[140:141], off
	v_lshl_add_u64 v[140:141], s[22:23], 0, v[128:129]
	s_add_i32 m0, s24, 0x2000
	s_nop 0
	global_load_lds_dwordx4 v[140:141], off
	s_waitcnt vmcnt(6)
	s_barrier
	s_setprio 1
	v_mfma_f32_16x16x32_bf16 v[52:55], v[200:203], v[164:167], v[52:55]
	v_mfma_f32_16x16x32_bf16 v[44:47], v[208:211], v[164:167], v[44:47]
	v_mfma_f32_16x16x32_bf16 v[36:39], v[200:203], v[172:175], v[36:39]
	v_mfma_f32_16x16x32_bf16 v[28:31], v[208:211], v[172:175], v[28:31]
	v_mfma_f32_16x16x32_bf16 v[20:23], v[200:203], v[184:187], v[20:23]
	v_mfma_f32_16x16x32_bf16 v[12:15], v[208:211], v[184:187], v[12:15]
	v_mfma_f32_16x16x32_bf16 v[4:7], v[200:203], v[192:195], v[4:7]
	v_mfma_f32_16x16x32_bf16 v[0:3], v[208:211], v[192:195], v[0:3]
	v_mfma_f32_16x16x32_bf16 v[52:55], v[204:207], v[168:171], v[52:55]
	v_mfma_f32_16x16x32_bf16 v[44:47], v[212:215], v[168:171], v[44:47]
	v_mfma_f32_16x16x32_bf16 v[36:39], v[204:207], v[180:183], v[36:39]
	v_mfma_f32_16x16x32_bf16 v[28:31], v[212:215], v[180:183], v[28:31]
	v_mfma_f32_16x16x32_bf16 v[20:23], v[204:207], v[188:191], v[20:23]
	v_mfma_f32_16x16x32_bf16 v[12:15], v[212:215], v[188:191], v[12:15]
	v_mfma_f32_16x16x32_bf16 v[4:7], v[204:207], v[196:199], v[4:7]
	v_mfma_f32_16x16x32_bf16 v[0:3], v[212:215], v[196:199], v[0:3]
	s_setprio 0
	s_add_i32 s44, s44, 2
	s_add_u32 s10, s10, 0x100
	s_addc_u32 s11, s11, 0
	s_add_u32 s42, s42, 0x100
	s_addc_u32 s43, s43, 0
	s_cmp_gt_u32 s44, 5
	s_barrier
	s_cbranch_scc0 .LBB0_1268
	v_lshl_add_u32 v142, s39, 8, v146
	s_nop 0
	v_lshl_or_b32 v140, s38, 8, v148
	v_ashrrev_i32_e32 v143, 31, v142
	s_nop 1
	v_readlane_b32 s46, v252, 13
	v_readlane_b32 s47, v252, 14
	v_ashrrev_i32_e32 v141, 31, v140
	v_lshlrev_b64 v[144:145], 12, v[142:143]
	s_mov_b64 s[42:43], s[46:47]
	v_lshl_add_u64 v[144:145], s[42:43], 0, v[144:145]
	v_lshlrev_b64 v[140:141], 1, v[140:141]
	v_or_b32_e32 v172, 16, v142
	v_lshl_add_u64 v[144:145], v[144:145], 0, v[140:141]
	v_ashrrev_i32_e32 v173, 31, v172
	global_load_dwordx4 v[152:155], v[144:145], off
	global_load_dwordx4 v[156:159], v[144:145], off offset:256
	v_lshlrev_b64 v[144:145], 12, v[172:173]
	v_lshl_add_u64 v[144:145], s[42:43], 0, v[144:145]
	v_lshl_add_u64 v[144:145], v[144:145], 0, v[140:141]
	global_load_dwordx4 v[160:163], v[144:145], off
	global_load_dwordx4 v[164:167], v[144:145], off offset:256
	v_or_b32_e32 v176, 32, v142
	v_ashrrev_i32_e32 v177, 31, v176
	v_lshlrev_b64 v[168:169], 12, v[176:177]
	v_lshl_add_u64 v[168:169], s[42:43], 0, v[168:169]
	v_lshl_add_u64 v[182:183], v[168:169], 0, v[140:141]
	global_load_dwordx4 v[168:171], v[182:183], off
	v_or_b32_e32 v144, 48, v142
	v_ashrrev_i32_e32 v145, 31, v144
	v_lshlrev_b64 v[180:181], 12, v[144:145]
	v_lshlrev_b64 v[174:175], 11, v[142:143]
	v_lshlrev_b64 v[172:173], 11, v[172:173]
	v_lshl_add_u64 v[180:181], s[42:43], 0, v[180:181]
	v_lshl_add_u64 v[174:175], s[82:83], 0, v[174:175]
	v_lshl_add_u64 v[172:173], s[82:83], 0, v[172:173]
	v_lshl_add_u64 v[184:185], v[180:181], 0, v[140:141]
	v_lshl_add_u64 v[188:189], v[174:175], 0, v[140:141]
	v_lshl_add_u64 v[190:191], v[172:173], 0, v[140:141]
	global_load_dwordx4 v[172:175], v[182:183], off offset:256
	s_nop 0
	global_load_dwordx4 v[180:183], v[184:185], off
	s_nop 0
	global_load_dwordx4 v[184:187], v[184:185], off offset:256
	v_add_u32_e32 v234, 0x80, v142
	v_ashrrev_i32_e32 v235, 31, v234
	v_lshlrev_b64 v[236:237], 12, v[234:235]
	v_lshl_add_u64 v[236:237], s[42:43], 0, v[236:237]
	v_lshl_add_u64 v[236:237], v[236:237], 0, v[140:141]
	global_load_dwordx4 v[200:203], v[236:237], off
	global_load_dwordx4 v[204:207], v[236:237], off offset:256
	v_add_u32_e32 v234, 0x90, v142
	v_ashrrev_i32_e32 v235, 31, v234
	v_lshlrev_b64 v[236:237], 12, v[234:235]
	v_lshl_add_u64 v[236:237], s[42:43], 0, v[236:237]
	v_lshl_add_u64 v[236:237], v[236:237], 0, v[140:141]
	global_load_dwordx4 v[208:211], v[236:237], off
	global_load_dwordx4 v[212:215], v[236:237], off offset:256
	v_add_u32_e32 v234, 0xa0, v142
	v_ashrrev_i32_e32 v235, 31, v234
	v_lshlrev_b64 v[236:237], 12, v[234:235]
	v_lshl_add_u64 v[236:237], s[42:43], 0, v[236:237]
	v_lshl_add_u64 v[236:237], v[236:237], 0, v[140:141]
	global_load_dwordx4 v[216:219], v[236:237], off
	global_load_dwordx4 v[222:225], v[236:237], off offset:256
	v_add_u32_e32 v234, 0xb0, v142
	v_ashrrev_i32_e32 v235, 31, v234
	v_lshlrev_b64 v[236:237], 12, v[234:235]
	v_lshl_add_u64 v[236:237], s[42:43], 0, v[236:237]
	v_lshl_add_u64 v[236:237], v[236:237], 0, v[140:141]
	global_load_dwordx4 v[226:229], v[236:237], off
	global_load_dwordx4 v[230:233], v[236:237], off offset:256
	s_and_b64 vcc, exec, s[18:19]
	s_mov_b32 s38, s14
	s_mov_b32 s39, s12
	s_mov_b32 s15, s14
	s_mov_b32 s18, s12
	s_mov_b64 s[22:23], s[20:21]
	s_mov_b64 s[10:11], s[16:17]
	s_mov_b32 s13, s37
	s_nop 7
	s_nop 2
	s_waitcnt vmcnt(8)
	v_lshlrev_b32_e32 v194, 16, v154
	v_and_b32_e32 v195, 0xffff0000, v154
	v_lshlrev_b32_e32 v154, 16, v155
	v_and_b32_e32 v155, 0xffff0000, v155
	v_lshlrev_b32_e32 v196, 16, v156
	v_and_b32_e32 v197, 0xffff0000, v156
	v_lshlrev_b32_e32 v156, 16, v157
	v_and_b32_e32 v157, 0xffff0000, v157
	v_lshlrev_b32_e32 v198, 16, v158
	v_and_b32_e32 v199, 0xffff0000, v158
	v_lshlrev_b32_e32 v158, 16, v159
	v_and_b32_e32 v159, 0xffff0000, v159
	v_lshlrev_b32_e32 v192, 16, v152
	v_and_b32_e32 v193, 0xffff0000, v152
	v_lshlrev_b32_e32 v152, 16, v153
	v_and_b32_e32 v153, 0xffff0000, v153
	v_pk_mul_f32 v[120:121], v[120:121], v[194:195]
	v_pk_mul_f32 v[122:123], v[122:123], v[154:155]
	v_pk_mul_f32 v[118:119], v[118:119], v[156:157]
	v_pk_mul_f32 v[154:155], v[110:111], v[158:159]
	v_lshlrev_b32_e32 v156, 16, v160
	v_and_b32_e32 v157, 0xffff0000, v160
	v_lshlrev_b32_e32 v158, 16, v161
	v_and_b32_e32 v159, 0xffff0000, v161
	v_lshlrev_b32_e32 v160, 16, v162
	v_and_b32_e32 v161, 0xffff0000, v162
	v_lshlrev_b32_e32 v162, 16, v163
	v_and_b32_e32 v163, 0xffff0000, v163
	v_pk_mul_f32 v[124:125], v[124:125], v[192:193]
	v_pk_mul_f32 v[126:127], v[126:127], v[152:153]
	v_cvt_pk_bf16_f32 v110, v120, v121
	v_cvt_pk_bf16_f32 v111, v122, v123
	v_pk_mul_f32 v[112:113], v[112:113], v[156:157]
	v_pk_mul_f32 v[114:115], v[114:115], v[158:159]
	v_pk_mul_f32 v[120:121], v[104:105], v[160:161]
	v_pk_mul_f32 v[122:123], v[106:107], v[162:163]
	v_pk_mul_f32 v[116:117], v[116:117], v[196:197]
	v_pk_mul_f32 v[152:153], v[108:109], v[198:199]
	v_cvt_pk_bf16_f32 v108, v124, v125
	v_cvt_pk_bf16_f32 v109, v126, v127
	v_cvt_pk_bf16_f32 v104, v112, v113
	v_cvt_pk_bf16_f32 v105, v114, v115
	v_cvt_pk_bf16_f32 v106, v120, v121
	v_cvt_pk_bf16_f32 v107, v122, v123
	v_cvt_pk_bf16_f32 v116, v116, v117
	v_cvt_pk_bf16_f32 v117, v118, v119
	v_cvt_pk_bf16_f32 v118, v152, v153
	v_cvt_pk_bf16_f32 v119, v154, v155
	global_store_dwordx4 v[188:189], v[108:111], off
	global_store_dwordx4 v[188:189], v[116:119], off offset:256
	global_store_dwordx4 v[190:191], v[104:107], off
	v_lshlrev_b32_e32 v192, 16, v164
	v_and_b32_e32 v193, 0xffff0000, v164
	v_lshlrev_b32_e32 v104, 16, v165
	v_and_b32_e32 v105, 0xffff0000, v165
	v_pk_mul_f32 v[102:103], v[102:103], v[104:105]
	v_lshlrev_b32_e32 v104, 16, v166
	v_and_b32_e32 v105, 0xffff0000, v166
	v_pk_mul_f32 v[104:105], v[92:93], v[104:105]
	v_lshlrev_b32_e32 v92, 16, v167
	v_and_b32_e32 v93, 0xffff0000, v167
	v_pk_mul_f32 v[100:101], v[100:101], v[192:193]
	v_pk_mul_f32 v[106:107], v[94:95], v[92:93]
	v_cvt_pk_bf16_f32 v92, v100, v101
	v_cvt_pk_bf16_f32 v93, v102, v103
	v_cvt_pk_bf16_f32 v94, v104, v105
	v_cvt_pk_bf16_f32 v95, v106, v107
	global_store_dwordx4 v[190:191], v[92:95], off offset:256
	v_add_u32_e32 v102, 0xb0, v142
	v_ashrrev_i32_e32 v103, 31, v102
	v_lshlrev_b32_e32 v94, 16, v168
	v_and_b32_e32 v95, 0xffff0000, v168
	v_pk_mul_f32 v[94:95], v[96:97], v[94:95]
	v_lshlrev_b32_e32 v96, 16, v169
	v_and_b32_e32 v97, 0xffff0000, v169
	v_pk_mul_f32 v[96:97], v[98:99], v[96:97]
	v_lshlrev_b32_e32 v98, 16, v170
	v_and_b32_e32 v99, 0xffff0000, v170
	v_lshlrev_b64 v[92:93], 11, v[176:177]
	v_pk_mul_f32 v[98:99], v[88:89], v[98:99]
	v_lshlrev_b32_e32 v88, 16, v171
	v_and_b32_e32 v89, 0xffff0000, v171
	v_pk_mul_f32 v[100:101], v[90:91], v[88:89]
	v_lshl_add_u64 v[92:93], s[82:83], 0, v[92:93]
	v_cvt_pk_bf16_f32 v88, v94, v95
	v_cvt_pk_bf16_f32 v89, v96, v97
	v_cvt_pk_bf16_f32 v90, v98, v99
	v_cvt_pk_bf16_f32 v91, v100, v101
	v_lshl_add_u64 v[92:93], v[92:93], 0, v[140:141]
	global_store_dwordx4 v[92:93], v[88:91], off
	v_add_u32_e32 v96, 0x80, v142
	v_ashrrev_i32_e32 v97, 31, v96
	v_lshlrev_b32_e32 v88, 16, v172
	v_and_b32_e32 v89, 0xffff0000, v172
	v_pk_mul_f32 v[84:85], v[84:85], v[88:89]
	v_lshlrev_b32_e32 v88, 16, v173
	v_and_b32_e32 v89, 0xffff0000, v173
	v_pk_mul_f32 v[86:87], v[86:87], v[88:89]
	v_lshlrev_b32_e32 v88, 16, v174
	v_and_b32_e32 v89, 0xffff0000, v174
	v_pk_mul_f32 v[88:89], v[76:77], v[88:89]
	v_lshlrev_b32_e32 v76, 16, v175
	v_and_b32_e32 v77, 0xffff0000, v175
	v_pk_mul_f32 v[90:91], v[78:79], v[76:77]
	v_cvt_pk_bf16_f32 v76, v84, v85
	v_cvt_pk_bf16_f32 v77, v86, v87
	v_cvt_pk_bf16_f32 v78, v88, v89
	v_cvt_pk_bf16_f32 v79, v90, v91
	global_store_dwordx4 v[92:93], v[76:79], off offset:256
	v_add_u32_e32 v98, 0x90, v142
	v_ashrrev_i32_e32 v99, 31, v98
	v_lshlrev_b32_e32 v78, 16, v180
	v_and_b32_e32 v79, 0xffff0000, v180
	v_pk_mul_f32 v[78:79], v[80:81], v[78:79]
	v_lshlrev_b32_e32 v80, 16, v181
	v_and_b32_e32 v81, 0xffff0000, v181
	v_pk_mul_f32 v[80:81], v[82:83], v[80:81]
	v_lshlrev_b32_e32 v82, 16, v182
	v_and_b32_e32 v83, 0xffff0000, v182
	v_lshlrev_b64 v[76:77], 11, v[144:145]
	v_pk_mul_f32 v[82:83], v[72:73], v[82:83]
	v_lshlrev_b32_e32 v72, 16, v183
	v_and_b32_e32 v73, 0xffff0000, v183
	v_pk_mul_f32 v[84:85], v[74:75], v[72:73]
	v_lshl_add_u64 v[76:77], s[82:83], 0, v[76:77]
	v_cvt_pk_bf16_f32 v72, v78, v79
	v_cvt_pk_bf16_f32 v73, v80, v81
	v_cvt_pk_bf16_f32 v74, v82, v83
	v_cvt_pk_bf16_f32 v75, v84, v85
	v_lshl_add_u64 v[76:77], v[76:77], 0, v[140:141]
	global_store_dwordx4 v[76:77], v[72:75], off
	v_add_u32_e32 v100, 0xa0, v142
	v_ashrrev_i32_e32 v101, 31, v100
	v_lshlrev_b32_e32 v72, 16, v184
	v_and_b32_e32 v73, 0xffff0000, v184
	v_pk_mul_f32 v[68:69], v[68:69], v[72:73]
	v_lshlrev_b32_e32 v72, 16, v185
	v_and_b32_e32 v73, 0xffff0000, v185
	v_pk_mul_f32 v[70:71], v[70:71], v[72:73]
	v_lshlrev_b32_e32 v72, 16, v186
	v_and_b32_e32 v73, 0xffff0000, v186
	v_pk_mul_f32 v[72:73], v[64:65], v[72:73]
	v_lshlrev_b32_e32 v64, 16, v187
	v_and_b32_e32 v65, 0xffff0000, v187
	v_pk_mul_f32 v[74:75], v[66:67], v[64:65]
	v_cvt_pk_bf16_f32 v64, v68, v69
	v_cvt_pk_bf16_f32 v65, v70, v71
	v_cvt_pk_bf16_f32 v66, v72, v73
	v_cvt_pk_bf16_f32 v67, v74, v75
	global_store_dwordx4 v[76:77], v[64:67], off offset:256
	s_nop 1
	v_lshlrev_b64 v[64:65], 12, v[96:97]
	v_lshl_add_u64 v[64:65], s[42:43], 0, v[64:65]
	v_lshl_add_u64 v[64:65], v[64:65], 0, v[140:141]
	v_lshlrev_b64 v[64:65], 12, v[98:99]
	v_lshl_add_u64 v[64:65], s[42:43], 0, v[64:65]
	v_lshl_add_u64 v[64:65], v[64:65], 0, v[140:141]
	v_lshlrev_b64 v[64:65], 12, v[100:101]
	v_lshl_add_u64 v[64:65], s[42:43], 0, v[64:65]
	v_lshl_add_u64 v[64:65], v[64:65], 0, v[140:141]
	v_lshlrev_b64 v[64:65], 12, v[102:103]
	v_lshl_add_u64 v[64:65], s[42:43], 0, v[64:65]
	v_lshl_add_u64 v[64:65], v[64:65], 0, v[140:141]
	s_nop 0
	v_lshlrev_b64 v[96:97], 11, v[96:97]
	s_waitcnt vmcnt(8)
	v_lshlrev_b32_e32 v104, 16, v200
	v_and_b32_e32 v105, 0xffff0000, v200
	v_lshlrev_b32_e32 v68, 16, v201
	v_and_b32_e32 v69, 0xffff0000, v201
	v_pk_mul_f32 v[62:63], v[62:63], v[68:69]
	v_lshlrev_b32_e32 v68, 16, v202
	v_and_b32_e32 v69, 0xffff0000, v202
	v_pk_mul_f32 v[60:61], v[60:61], v[104:105]
	v_pk_mul_f32 v[68:69], v[56:57], v[68:69]
	v_lshlrev_b32_e32 v56, 16, v203
	v_and_b32_e32 v57, 0xffff0000, v203
	v_pk_mul_f32 v[70:71], v[58:59], v[56:57]
	v_cvt_pk_bf16_f32 v56, v60, v61
	v_lshl_add_u64 v[60:61], s[82:83], 0, v[96:97]
	v_cvt_pk_bf16_f32 v57, v62, v63
	v_cvt_pk_bf16_f32 v58, v68, v69
	v_cvt_pk_bf16_f32 v59, v70, v71
	v_lshl_add_u64 v[60:61], v[60:61], 0, v[140:141]
	global_store_dwordx4 v[60:61], v[56:59], off
	s_nop 1
	v_lshlrev_b32_e32 v56, 16, v204
	v_and_b32_e32 v57, 0xffff0000, v204
	v_pk_mul_f32 v[52:53], v[52:53], v[56:57]
	v_lshlrev_b32_e32 v56, 16, v205
	v_and_b32_e32 v57, 0xffff0000, v205
	v_pk_mul_f32 v[54:55], v[54:55], v[56:57]
	v_lshlrev_b32_e32 v56, 16, v206
	v_and_b32_e32 v57, 0xffff0000, v206
	v_pk_mul_f32 v[56:57], v[44:45], v[56:57]
	v_lshlrev_b32_e32 v44, 16, v207
	v_and_b32_e32 v45, 0xffff0000, v207
	v_pk_mul_f32 v[58:59], v[46:47], v[44:45]
	v_cvt_pk_bf16_f32 v44, v52, v53
	v_cvt_pk_bf16_f32 v45, v54, v55
	v_cvt_pk_bf16_f32 v46, v56, v57
	v_cvt_pk_bf16_f32 v47, v58, v59
	global_store_dwordx4 v[60:61], v[44:47], off offset:256
	s_nop 1
	v_lshlrev_b32_e32 v46, 16, v208
	v_and_b32_e32 v47, 0xffff0000, v208
	v_pk_mul_f32 v[46:47], v[48:49], v[46:47]
	v_lshlrev_b32_e32 v48, 16, v209
	v_and_b32_e32 v49, 0xffff0000, v209
	v_pk_mul_f32 v[48:49], v[50:51], v[48:49]
	v_lshlrev_b32_e32 v50, 16, v210
	v_and_b32_e32 v51, 0xffff0000, v210
	v_lshlrev_b64 v[44:45], 11, v[98:99]
	v_pk_mul_f32 v[50:51], v[40:41], v[50:51]
	v_lshlrev_b32_e32 v40, 16, v211
	v_and_b32_e32 v41, 0xffff0000, v211
	v_pk_mul_f32 v[52:53], v[42:43], v[40:41]
	v_lshl_add_u64 v[44:45], s[82:83], 0, v[44:45]
	v_cvt_pk_bf16_f32 v40, v46, v47
	v_cvt_pk_bf16_f32 v41, v48, v49
	v_cvt_pk_bf16_f32 v42, v50, v51
	v_cvt_pk_bf16_f32 v43, v52, v53
	v_lshl_add_u64 v[44:45], v[44:45], 0, v[140:141]
	global_store_dwordx4 v[44:45], v[40:43], off
	s_nop 1
	v_lshlrev_b32_e32 v40, 16, v212
	v_and_b32_e32 v41, 0xffff0000, v212
	v_pk_mul_f32 v[36:37], v[36:37], v[40:41]
	v_lshlrev_b32_e32 v40, 16, v213
	v_and_b32_e32 v41, 0xffff0000, v213
	v_pk_mul_f32 v[38:39], v[38:39], v[40:41]
	v_lshlrev_b32_e32 v40, 16, v214
	v_and_b32_e32 v41, 0xffff0000, v214
	v_pk_mul_f32 v[40:41], v[28:29], v[40:41]
	v_lshlrev_b32_e32 v28, 16, v215
	v_and_b32_e32 v29, 0xffff0000, v215
	v_pk_mul_f32 v[42:43], v[30:31], v[28:29]
	v_cvt_pk_bf16_f32 v28, v36, v37
	v_cvt_pk_bf16_f32 v29, v38, v39
	v_cvt_pk_bf16_f32 v30, v40, v41
	v_cvt_pk_bf16_f32 v31, v42, v43
	global_store_dwordx4 v[44:45], v[28:31], off offset:256
	s_nop 1
	v_lshlrev_b32_e32 v30, 16, v216
	v_and_b32_e32 v31, 0xffff0000, v216
	v_pk_mul_f32 v[30:31], v[32:33], v[30:31]
	v_lshlrev_b32_e32 v32, 16, v217
	v_and_b32_e32 v33, 0xffff0000, v217
	v_pk_mul_f32 v[32:33], v[34:35], v[32:33]
	v_lshlrev_b32_e32 v34, 16, v218
	v_and_b32_e32 v35, 0xffff0000, v218
	v_lshlrev_b64 v[28:29], 11, v[100:101]
	v_pk_mul_f32 v[34:35], v[24:25], v[34:35]
	v_lshlrev_b32_e32 v24, 16, v219
	v_and_b32_e32 v25, 0xffff0000, v219
	v_pk_mul_f32 v[36:37], v[26:27], v[24:25]
	v_lshl_add_u64 v[28:29], s[82:83], 0, v[28:29]
	v_cvt_pk_bf16_f32 v24, v30, v31
	v_cvt_pk_bf16_f32 v25, v32, v33
	v_cvt_pk_bf16_f32 v26, v34, v35
	v_cvt_pk_bf16_f32 v27, v36, v37
	v_lshl_add_u64 v[28:29], v[28:29], 0, v[140:141]
	global_store_dwordx4 v[28:29], v[24:27], off
	s_nop 1
	v_lshlrev_b32_e32 v24, 16, v222
	v_and_b32_e32 v25, 0xffff0000, v222
	v_pk_mul_f32 v[20:21], v[20:21], v[24:25]
	v_lshlrev_b32_e32 v24, 16, v223
	v_and_b32_e32 v25, 0xffff0000, v223
	v_pk_mul_f32 v[22:23], v[22:23], v[24:25]
	v_lshlrev_b32_e32 v24, 16, v224
	v_and_b32_e32 v25, 0xffff0000, v224
	v_pk_mul_f32 v[24:25], v[12:13], v[24:25]
	v_lshlrev_b32_e32 v12, 16, v225
	v_and_b32_e32 v13, 0xffff0000, v225
	v_pk_mul_f32 v[26:27], v[14:15], v[12:13]
	v_cvt_pk_bf16_f32 v12, v20, v21
	v_cvt_pk_bf16_f32 v13, v22, v23
	v_cvt_pk_bf16_f32 v14, v24, v25
	v_cvt_pk_bf16_f32 v15, v26, v27
	global_store_dwordx4 v[28:29], v[12:15], off offset:256
	s_nop 1
	v_lshlrev_b32_e32 v14, 16, v226
	v_and_b32_e32 v15, 0xffff0000, v226
	v_pk_mul_f32 v[14:15], v[16:17], v[14:15]
	v_lshlrev_b32_e32 v16, 16, v227
	v_and_b32_e32 v17, 0xffff0000, v227
	v_pk_mul_f32 v[16:17], v[18:19], v[16:17]
	v_lshlrev_b32_e32 v18, 16, v228
	v_and_b32_e32 v19, 0xffff0000, v228
	v_lshlrev_b64 v[12:13], 11, v[102:103]
	v_pk_mul_f32 v[18:19], v[8:9], v[18:19]
	v_lshlrev_b32_e32 v8, 16, v229
	v_and_b32_e32 v9, 0xffff0000, v229
	v_pk_mul_f32 v[20:21], v[10:11], v[8:9]
	v_lshl_add_u64 v[12:13], s[82:83], 0, v[12:13]
	v_cvt_pk_bf16_f32 v8, v14, v15
	v_cvt_pk_bf16_f32 v9, v16, v17
	v_cvt_pk_bf16_f32 v10, v18, v19
	v_cvt_pk_bf16_f32 v11, v20, v21
	v_lshl_add_u64 v[12:13], v[12:13], 0, v[140:141]
	global_store_dwordx4 v[12:13], v[8:11], off
	s_nop 1
	v_lshlrev_b32_e32 v8, 16, v230
	v_and_b32_e32 v9, 0xffff0000, v230
	v_pk_mul_f32 v[4:5], v[4:5], v[8:9]
	v_lshlrev_b32_e32 v8, 16, v231
	v_and_b32_e32 v9, 0xffff0000, v231
	v_pk_mul_f32 v[6:7], v[6:7], v[8:9]
	v_lshlrev_b32_e32 v8, 16, v232
	v_and_b32_e32 v9, 0xffff0000, v232
	v_pk_mul_f32 v[8:9], v[0:1], v[8:9]
	v_lshlrev_b32_e32 v0, 16, v233
	v_and_b32_e32 v1, 0xffff0000, v233
	v_pk_mul_f32 v[10:11], v[2:3], v[0:1]
	v_cvt_pk_bf16_f32 v0, v4, v5
	v_cvt_pk_bf16_f32 v1, v6, v7
	v_cvt_pk_bf16_f32 v2, v8, v9
	v_cvt_pk_bf16_f32 v3, v10, v11
	global_store_dwordx4 v[12:13], v[0:3], off offset:256
	s_cbranch_vccz .LBB0_1260
	s_waitcnt vmcnt(0)
	s_cmpk_gt_u32 s26, 0xff
	s_cbranch_scc1 .LBB0_1272
	s_barrier

.LBB0_1285:
	ds_read_b128 v[128:131], v175
	ds_read_b128 v[132:135], v175 offset:1024
	ds_read_b128 v[136:139], v175 offset:2048
	ds_read_b128 v[140:143], v175 offset:3072
	s_add_u32 s22, s10, 0xfffe0080
	s_addc_u32 s23, s11, -1
	s_cmp_eq_u32 s43, 4
	s_cselect_b32 s25, s13, s23
	s_cselect_b32 s24, s39, s22
	s_cselect_b32 s23, s15, s42
	s_cselect_b32 s22, s40, s41
	v_lshl_add_u64 v[196:197], s[10:11], 0, v[160:161]
	s_add_i32 m0, s1, 0xc000
	ds_read_b128 v[144:147], v176
	ds_read_b128 v[148:151], v176 offset:1024
	ds_read_b128 v[164:167], v176 offset:2048
	ds_read_b128 v[168:171], v176 offset:3072
	ds_read_b128 v[180:183], v176 offset:4096
	ds_read_b128 v[184:187], v176 offset:5120
	ds_read_b128 v[188:191], v176 offset:6144
	ds_read_b128 v[192:195], v176 offset:7168
	global_load_lds_dwordx4 v[196:197], off
	v_lshl_add_u64 v[196:197], s[10:11], 0, v[162:163]
	s_add_i32 m0, s1, 0xe000
	s_nop 0
	global_load_lds_dwordx4 v[196:197], off
	s_waitcnt lgkmcnt(8)
	s_barrier
	s_waitcnt lgkmcnt(0)
	s_setprio 1
	v_mfma_f32_16x16x32_bf16 v[124:127], v[128:131], v[144:147], v[124:127]
	v_mfma_f32_16x16x32_bf16 v[120:123], v[136:139], v[144:147], v[120:123]
	v_mfma_f32_16x16x32_bf16 v[108:111], v[128:131], v[164:167], v[108:111]
	v_mfma_f32_16x16x32_bf16 v[104:107], v[136:139], v[164:167], v[104:107]
	v_mfma_f32_16x16x32_bf16 v[92:95], v[128:131], v[180:183], v[92:95]
	v_mfma_f32_16x16x32_bf16 v[88:91], v[136:139], v[180:183], v[88:91]
	v_mfma_f32_16x16x32_bf16 v[76:79], v[128:131], v[188:191], v[76:79]
	v_mfma_f32_16x16x32_bf16 v[72:75], v[136:139], v[188:191], v[72:75]
	v_mfma_f32_16x16x32_bf16 v[124:127], v[132:135], v[148:151], v[124:127]
	v_mfma_f32_16x16x32_bf16 v[120:123], v[140:143], v[148:151], v[120:123]
	v_mfma_f32_16x16x32_bf16 v[108:111], v[132:135], v[168:171], v[108:111]
	v_mfma_f32_16x16x32_bf16 v[104:107], v[140:143], v[168:171], v[104:107]
	v_mfma_f32_16x16x32_bf16 v[92:95], v[132:135], v[184:187], v[92:95]
	v_mfma_f32_16x16x32_bf16 v[88:91], v[140:143], v[184:187], v[88:91]
	v_mfma_f32_16x16x32_bf16 v[76:79], v[132:135], v[192:195], v[76:79]
	v_mfma_f32_16x16x32_bf16 v[72:75], v[140:143], v[192:195], v[72:75]
	s_setprio 0
	s_barrier
	s_add_i32 s44, s35, s27
	v_lshl_add_u64 v[212:213], s[22:23], 0, v[156:157]
	s_mov_b32 m0, s44
	ds_read_b128 v[196:199], v177
	ds_read_b128 v[200:203], v177 offset:1024
	ds_read_b128 v[204:207], v177 offset:2048
	ds_read_b128 v[208:211], v177 offset:3072
	global_load_lds_dwordx4 v[212:213], off
	v_lshl_add_u64 v[214:215], s[22:23], 0, v[152:153]
	s_add_i32 m0, s44, 0x2000
	s_nop 0
	global_load_lds_dwordx4 v[214:215], off
	s_barrier
	s_waitcnt lgkmcnt(0)
	s_setprio 1
	v_mfma_f32_16x16x32_bf16 v[116:119], v[196:199], v[144:147], v[116:119]
	v_mfma_f32_16x16x32_bf16 v[112:115], v[204:207], v[144:147], v[112:115]
	v_mfma_f32_16x16x32_bf16 v[100:103], v[196:199], v[164:167], v[100:103]
	v_mfma_f32_16x16x32_bf16 v[96:99], v[204:207], v[164:167], v[96:99]
	v_mfma_f32_16x16x32_bf16 v[84:87], v[196:199], v[180:183], v[84:87]
	v_mfma_f32_16x16x32_bf16 v[80:83], v[204:207], v[180:183], v[80:83]
	v_mfma_f32_16x16x32_bf16 v[68:71], v[196:199], v[188:191], v[68:71]
	v_mfma_f32_16x16x32_bf16 v[64:67], v[204:207], v[188:191], v[64:67]
	v_mfma_f32_16x16x32_bf16 v[116:119], v[200:203], v[148:151], v[116:119]
	v_mfma_f32_16x16x32_bf16 v[112:115], v[208:211], v[148:151], v[112:115]
	v_mfma_f32_16x16x32_bf16 v[100:103], v[200:203], v[168:171], v[100:103]
	v_mfma_f32_16x16x32_bf16 v[96:99], v[208:211], v[168:171], v[96:99]
	v_mfma_f32_16x16x32_bf16 v[84:87], v[200:203], v[184:187], v[84:87]
	v_mfma_f32_16x16x32_bf16 v[80:83], v[208:211], v[184:187], v[80:83]
	v_mfma_f32_16x16x32_bf16 v[68:71], v[200:203], v[192:195], v[68:71]
	v_mfma_f32_16x16x32_bf16 v[64:67], v[208:211], v[192:195], v[64:67]
	s_setprio 0
	s_mov_b32 m0, s1
	v_lshl_add_u64 v[216:217], s[24:25], 0, v[158:159]
	s_barrier
	ds_read_b128 v[144:147], v176 offset:16384
	ds_read_b128 v[148:151], v176 offset:17408
	ds_read_b128 v[164:167], v176 offset:18432
	ds_read_b128 v[168:171], v176 offset:19456
	ds_read_b128 v[180:183], v176 offset:20480
	ds_read_b128 v[184:187], v176 offset:21504
	ds_read_b128 v[188:191], v176 offset:22528
	ds_read_b128 v[192:195], v176 offset:23552
	global_load_lds_dwordx4 v[216:217], off
	v_lshl_add_u64 v[218:219], s[24:25], 0, v[154:155]
	s_mov_b32 m0, s7
	s_nop 0
	global_load_lds_dwordx4 v[218:219], off
	s_barrier
	s_waitcnt lgkmcnt(0)
	s_setprio 1
	v_mfma_f32_16x16x32_bf16 v[60:63], v[128:131], v[144:147], v[60:63]
	v_mfma_f32_16x16x32_bf16 v[56:59], v[136:139], v[144:147], v[56:59]
	v_mfma_f32_16x16x32_bf16 v[44:47], v[128:131], v[164:167], v[44:47]
	v_mfma_f32_16x16x32_bf16 v[40:43], v[136:139], v[164:167], v[40:43]
	v_mfma_f32_16x16x32_bf16 v[28:31], v[128:131], v[180:183], v[28:31]
	v_mfma_f32_16x16x32_bf16 v[24:27], v[136:139], v[180:183], v[24:27]
	v_mfma_f32_16x16x32_bf16 v[12:15], v[128:131], v[188:191], v[12:15]
	v_mfma_f32_16x16x32_bf16 v[8:11], v[136:139], v[188:191], v[8:11]
	v_mfma_f32_16x16x32_bf16 v[60:63], v[132:135], v[148:151], v[60:63]
	v_mfma_f32_16x16x32_bf16 v[56:59], v[140:143], v[148:151], v[56:59]
	v_mfma_f32_16x16x32_bf16 v[44:47], v[132:135], v[168:171], v[44:47]
	v_mfma_f32_16x16x32_bf16 v[40:43], v[140:143], v[168:171], v[40:43]
	v_mfma_f32_16x16x32_bf16 v[28:31], v[132:135], v[184:187], v[28:31]
	v_mfma_f32_16x16x32_bf16 v[24:27], v[140:143], v[184:187], v[24:27]
	v_mfma_f32_16x16x32_bf16 v[12:15], v[132:135], v[192:195], v[12:15]
	v_mfma_f32_16x16x32_bf16 v[8:11], v[140:143], v[192:195], v[8:11]
	s_setprio 0
	s_barrier
	s_add_u32 s44, s22, 0x20000
	s_addc_u32 s45, s23, 0
	s_add_i32 s46, s36, s27
	v_lshl_add_u64 v[128:129], s[44:45], 0, v[156:157]
	s_mov_b32 m0, s46
	s_nop 0
	global_load_lds_dwordx4 v[128:129], off
	v_lshl_add_u64 v[128:129], s[44:45], 0, v[152:153]
	s_add_i32 m0, s46, 0x2000
	s_nop 0
	global_load_lds_dwordx4 v[128:129], off
	s_waitcnt vmcnt(6)
	s_barrier
	s_setprio 1
	v_mfma_f32_16x16x32_bf16 v[52:55], v[196:199], v[144:147], v[52:55]
	v_mfma_f32_16x16x32_bf16 v[48:51], v[204:207], v[144:147], v[48:51]
	v_mfma_f32_16x16x32_bf16 v[36:39], v[196:199], v[164:167], v[36:39]
	v_mfma_f32_16x16x32_bf16 v[32:35], v[204:207], v[164:167], v[32:35]
	v_mfma_f32_16x16x32_bf16 v[20:23], v[196:199], v[180:183], v[20:23]
	v_mfma_f32_16x16x32_bf16 v[16:19], v[204:207], v[180:183], v[16:19]
	v_mfma_f32_16x16x32_bf16 v[4:7], v[196:199], v[188:191], v[4:7]
	v_mfma_f32_16x16x32_bf16 v[0:3], v[204:207], v[188:191], v[0:3]
	v_mfma_f32_16x16x32_bf16 v[52:55], v[200:203], v[148:151], v[52:55]
	v_mfma_f32_16x16x32_bf16 v[48:51], v[208:211], v[148:151], v[48:51]
	v_mfma_f32_16x16x32_bf16 v[36:39], v[200:203], v[168:171], v[36:39]
	v_mfma_f32_16x16x32_bf16 v[32:35], v[208:211], v[168:171], v[32:35]
	v_mfma_f32_16x16x32_bf16 v[20:23], v[200:203], v[184:187], v[20:23]
	v_mfma_f32_16x16x32_bf16 v[16:19], v[208:211], v[184:187], v[16:19]
	v_mfma_f32_16x16x32_bf16 v[4:7], v[200:203], v[192:195], v[4:7]
	v_mfma_f32_16x16x32_bf16 v[0:3], v[208:211], v[192:195], v[0:3]
	s_setprio 0
	s_add_i32 s44, 0, 0x18000
	v_add_u32_e32 v140, s44, v173
	s_barrier
	ds_read_b128 v[128:131], v140
	ds_read_b128 v[132:135], v140 offset:1024
	ds_read_b128 v[136:139], v140 offset:2048
	ds_read_b128 v[140:143], v140 offset:3072
	s_add_u32 s24, s24, 0x20000
	s_addc_u32 s25, s25, 0
	s_mov_b32 m0, s28
	v_lshl_add_u64 v[196:197], s[24:25], 0, v[158:159]
	ds_read_b128 v[144:147], v176 offset:32768
	ds_read_b128 v[148:151], v176 offset:33792
	ds_read_b128 v[164:167], v176 offset:34816
	ds_read_b128 v[168:171], v176 offset:35840
	ds_read_b128 v[180:183], v176 offset:36864
	ds_read_b128 v[184:187], v176 offset:37888
	ds_read_b128 v[188:191], v176 offset:38912
	ds_read_b128 v[192:195], v176 offset:39936
	global_load_lds_dwordx4 v[196:197], off
	v_lshl_add_u64 v[196:197], s[24:25], 0, v[154:155]
	s_mov_b32 m0, s29
	s_nop 0
	global_load_lds_dwordx4 v[196:197], off
	s_waitcnt lgkmcnt(8)
	s_barrier
	s_waitcnt lgkmcnt(0)
	s_setprio 1
	v_mfma_f32_16x16x32_bf16 v[124:127], v[128:131], v[144:147], v[124:127]
	v_mfma_f32_16x16x32_bf16 v[120:123], v[136:139], v[144:147], v[120:123]
	v_mfma_f32_16x16x32_bf16 v[108:111], v[128:131], v[164:167], v[108:111]
	v_mfma_f32_16x16x32_bf16 v[104:107], v[136:139], v[164:167], v[104:107]
	v_mfma_f32_16x16x32_bf16 v[92:95], v[128:131], v[180:183], v[92:95]
	v_mfma_f32_16x16x32_bf16 v[88:91], v[136:139], v[180:183], v[88:91]
	v_mfma_f32_16x16x32_bf16 v[76:79], v[128:131], v[188:191], v[76:79]
	v_mfma_f32_16x16x32_bf16 v[72:75], v[136:139], v[188:191], v[72:75]
	v_mfma_f32_16x16x32_bf16 v[124:127], v[132:135], v[148:151], v[124:127]
	v_mfma_f32_16x16x32_bf16 v[120:123], v[140:143], v[148:151], v[120:123]
	v_mfma_f32_16x16x32_bf16 v[108:111], v[132:135], v[168:171], v[108:111]
	v_mfma_f32_16x16x32_bf16 v[104:107], v[140:143], v[168:171], v[104:107]
	v_mfma_f32_16x16x32_bf16 v[92:95], v[132:135], v[184:187], v[92:95]
	v_mfma_f32_16x16x32_bf16 v[88:91], v[140:143], v[184:187], v[88:91]
	v_mfma_f32_16x16x32_bf16 v[76:79], v[132:135], v[192:195], v[76:79]
	v_mfma_f32_16x16x32_bf16 v[72:75], v[140:143], v[192:195], v[72:75]
	s_setprio 0
	s_barrier
	s_add_i32 s24, 0, 0x1c000
	s_add_i32 s25, s44, s27
	v_add_u32_e32 v179, s24, v173
	v_lshl_add_u64 v[212:213], v[212:213], 0, s[4:5]
	s_mov_b32 m0, s25
	ds_read_b128 v[196:199], v179
	ds_read_b128 v[200:203], v179 offset:1024
	ds_read_b128 v[204:207], v179 offset:2048
	ds_read_b128 v[208:211], v179 offset:3072
	global_load_lds_dwordx4 v[212:213], off
	v_lshl_add_u64 v[212:213], v[214:215], 0, s[4:5]
	s_add_i32 m0, s25, 0x2000
	s_nop 0
	global_load_lds_dwordx4 v[212:213], off
	s_barrier
	s_waitcnt lgkmcnt(0)
	s_setprio 1
	v_mfma_f32_16x16x32_bf16 v[116:119], v[196:199], v[144:147], v[116:119]
	v_mfma_f32_16x16x32_bf16 v[112:115], v[204:207], v[144:147], v[112:115]
	v_mfma_f32_16x16x32_bf16 v[100:103], v[196:199], v[164:167], v[100:103]
	v_mfma_f32_16x16x32_bf16 v[96:99], v[204:207], v[164:167], v[96:99]
	v_mfma_f32_16x16x32_bf16 v[84:87], v[196:199], v[180:183], v[84:87]
	v_mfma_f32_16x16x32_bf16 v[80:83], v[204:207], v[180:183], v[80:83]
	v_mfma_f32_16x16x32_bf16 v[68:71], v[196:199], v[188:191], v[68:71]
	v_mfma_f32_16x16x32_bf16 v[64:67], v[204:207], v[188:191], v[64:67]
	v_mfma_f32_16x16x32_bf16 v[116:119], v[200:203], v[148:151], v[116:119]
	v_mfma_f32_16x16x32_bf16 v[112:115], v[208:211], v[148:151], v[112:115]
	v_mfma_f32_16x16x32_bf16 v[100:103], v[200:203], v[168:171], v[100:103]
	v_mfma_f32_16x16x32_bf16 v[96:99], v[208:211], v[168:171], v[96:99]
	v_mfma_f32_16x16x32_bf16 v[84:87], v[200:203], v[184:187], v[84:87]
	v_mfma_f32_16x16x32_bf16 v[80:83], v[208:211], v[184:187], v[80:83]
	v_mfma_f32_16x16x32_bf16 v[68:71], v[200:203], v[192:195], v[68:71]
	v_mfma_f32_16x16x32_bf16 v[64:67], v[208:211], v[192:195], v[64:67]
	s_setprio 0
	s_mov_b32 m0, s31
	v_lshl_add_u64 v[212:213], v[216:217], 0, s[4:5]
	s_barrier
	ds_read_b128 v[144:147], v176 offset:49152
	ds_read_b128 v[148:151], v176 offset:50176
	ds_read_b128 v[164:167], v176 offset:51200
	ds_read_b128 v[168:171], v176 offset:52224
	ds_read_b128 v[180:183], v176 offset:53248
	ds_read_b128 v[184:187], v176 offset:54272
	ds_read_b128 v[188:191], v176 offset:55296
	ds_read_b128 v[192:195], v176 offset:56320
	global_load_lds_dwordx4 v[212:213], off
	v_lshl_add_u64 v[212:213], v[218:219], 0, s[4:5]
	s_mov_b32 m0, s33
	s_nop 0
	global_load_lds_dwordx4 v[212:213], off
	s_barrier
	s_waitcnt lgkmcnt(0)
	s_setprio 1
	v_mfma_f32_16x16x32_bf16 v[60:63], v[128:131], v[144:147], v[60:63]
	v_mfma_f32_16x16x32_bf16 v[56:59], v[136:139], v[144:147], v[56:59]
	v_mfma_f32_16x16x32_bf16 v[44:47], v[128:131], v[164:167], v[44:47]
	v_mfma_f32_16x16x32_bf16 v[40:43], v[136:139], v[164:167], v[40:43]
	v_mfma_f32_16x16x32_bf16 v[28:31], v[128:131], v[180:183], v[28:31]
	v_mfma_f32_16x16x32_bf16 v[24:27], v[136:139], v[180:183], v[24:27]
	v_mfma_f32_16x16x32_bf16 v[12:15], v[128:131], v[188:191], v[12:15]
	v_mfma_f32_16x16x32_bf16 v[8:11], v[136:139], v[188:191], v[8:11]
	v_mfma_f32_16x16x32_bf16 v[60:63], v[132:135], v[148:151], v[60:63]
	v_mfma_f32_16x16x32_bf16 v[56:59], v[140:143], v[148:151], v[56:59]
	v_mfma_f32_16x16x32_bf16 v[44:47], v[132:135], v[168:171], v[44:47]
	v_mfma_f32_16x16x32_bf16 v[40:43], v[140:143], v[168:171], v[40:43]
	v_mfma_f32_16x16x32_bf16 v[28:31], v[132:135], v[184:187], v[28:31]
	v_mfma_f32_16x16x32_bf16 v[24:27], v[140:143], v[184:187], v[24:27]
	v_mfma_f32_16x16x32_bf16 v[12:15], v[132:135], v[192:195], v[12:15]
	v_mfma_f32_16x16x32_bf16 v[8:11], v[140:143], v[192:195], v[8:11]
	s_setprio 0
	s_barrier
	s_add_u32 s22, s22, 0x20080
	s_addc_u32 s23, s23, 0
	s_add_i32 s24, s24, s27
	v_lshl_add_u64 v[128:129], s[22:23], 0, v[156:157]
	s_mov_b32 m0, s24
	s_nop 0
	global_load_lds_dwordx4 v[128:129], off
	v_lshl_add_u64 v[128:129], s[22:23], 0, v[152:153]
	s_add_i32 m0, s24, 0x2000
	s_nop 0
	global_load_lds_dwordx4 v[128:129], off
	s_waitcnt vmcnt(6)
	s_barrier
	s_setprio 1
	v_mfma_f32_16x16x32_bf16 v[52:55], v[196:199], v[144:147], v[52:55]
	v_mfma_f32_16x16x32_bf16 v[48:51], v[204:207], v[144:147], v[48:51]
	v_mfma_f32_16x16x32_bf16 v[36:39], v[196:199], v[164:167], v[36:39]
	v_mfma_f32_16x16x32_bf16 v[32:35], v[204:207], v[164:167], v[32:35]
	v_mfma_f32_16x16x32_bf16 v[20:23], v[196:199], v[180:183], v[20:23]
	v_mfma_f32_16x16x32_bf16 v[16:19], v[204:207], v[180:183], v[16:19]
	v_mfma_f32_16x16x32_bf16 v[4:7], v[196:199], v[188:191], v[4:7]
	v_mfma_f32_16x16x32_bf16 v[0:3], v[204:207], v[188:191], v[0:3]
	v_mfma_f32_16x16x32_bf16 v[52:55], v[200:203], v[148:151], v[52:55]
	v_mfma_f32_16x16x32_bf16 v[48:51], v[208:211], v[148:151], v[48:51]
	v_mfma_f32_16x16x32_bf16 v[36:39], v[200:203], v[168:171], v[36:39]
	v_mfma_f32_16x16x32_bf16 v[32:35], v[208:211], v[168:171], v[32:35]
	v_mfma_f32_16x16x32_bf16 v[20:23], v[200:203], v[184:187], v[20:23]
	v_mfma_f32_16x16x32_bf16 v[16:19], v[208:211], v[184:187], v[16:19]
	v_mfma_f32_16x16x32_bf16 v[4:7], v[200:203], v[192:195], v[4:7]
	v_mfma_f32_16x16x32_bf16 v[0:3], v[208:211], v[192:195], v[0:3]
	s_setprio 0
	s_add_i32 s43, s43, 2
	s_add_u32 s10, s10, 0x100
	s_addc_u32 s11, s11, 0
	s_add_u32 s41, s41, 0x100
	s_addc_u32 s42, s42, 0
	s_cmp_gt_u32 s43, 5
	s_barrier
	s_cbranch_scc0 .LBB0_1285
	v_lshl_add_u32 v164, s38, 8, v172
	s_nop 0
	v_lshl_or_b32 v128, s0, 8, v174
	v_ashrrev_i32_e32 v165, 31, v164
	s_nop 1
	v_readlane_b32 s46, v252, 13
	v_readlane_b32 s47, v252, 14
	v_ashrrev_i32_e32 v129, 31, v128
	v_lshlrev_b64 v[130:131], 12, v[164:165]
	s_mov_b64 s[42:43], s[46:47]
	v_lshl_add_u64 v[130:131], s[42:43], 0, v[130:131]
	v_lshlrev_b64 v[132:133], 11, v[164:165]
	v_lshlrev_b64 v[166:167], 1, v[128:129]
	v_lshl_add_u64 v[132:133], s[82:83], 0, v[132:133]
	v_lshl_add_u64 v[128:129], v[130:131], 0, v[166:167]
	global_load_dwordx4 v[180:183], v[128:129], off offset:2048
	v_lshl_add_u64 v[222:223], v[132:133], 0, v[166:167]
	global_load_dwordx4 v[184:187], v[222:223], off
	global_load_dwordx4 v[188:191], v[128:129], off offset:2304
	global_load_dwordx4 v[192:195], v[222:223], off offset:256
	v_or_b32_e32 v128, 16, v164
	v_ashrrev_i32_e32 v129, 31, v128
	v_lshlrev_b64 v[130:131], 12, v[128:129]
	v_lshlrev_b64 v[128:129], 11, v[128:129]
	v_lshl_add_u64 v[130:131], s[42:43], 0, v[130:131]
	v_lshl_add_u64 v[128:129], s[82:83], 0, v[128:129]
	v_lshl_add_u64 v[130:131], v[130:131], 0, v[166:167]
	v_lshl_add_u64 v[224:225], v[128:129], 0, v[166:167]
	global_load_dwordx4 v[196:199], v[130:131], off offset:2048
	global_load_dwordx4 v[200:203], v[224:225], off
	v_or_b32_e32 v128, 32, v164
	v_or_b32_e32 v132, 48, v164
	v_ashrrev_i32_e32 v129, 31, v128
	v_ashrrev_i32_e32 v133, 31, v132
	v_lshlrev_b64 v[134:135], 12, v[128:129]
	v_lshlrev_b64 v[128:129], 11, v[128:129]
	v_lshlrev_b64 v[136:137], 12, v[132:133]
	v_lshlrev_b64 v[132:133], 11, v[132:133]
	v_lshl_add_u64 v[134:135], s[42:43], 0, v[134:135]
	v_lshl_add_u64 v[128:129], s[82:83], 0, v[128:129]
	v_lshl_add_u64 v[136:137], s[42:43], 0, v[136:137]
	v_lshl_add_u64 v[132:133], s[82:83], 0, v[132:133]
	v_lshl_add_u64 v[134:135], v[134:135], 0, v[166:167]
	v_lshl_add_u64 v[170:171], v[128:129], 0, v[166:167]
	v_lshl_add_u64 v[128:129], v[136:137], 0, v[166:167]
	v_lshl_add_u64 v[168:169], v[132:133], 0, v[166:167]
	global_load_dwordx4 v[204:207], v[130:131], off offset:2304
	global_load_dwordx4 v[208:211], v[224:225], off offset:256
	global_load_dwordx4 v[212:215], v[134:135], off offset:2048
	global_load_dwordx4 v[148:151], v[134:135], off offset:2304
	global_load_dwordx4 v[216:219], v[170:171], off
	global_load_dwordx4 v[144:147], v[170:171], off offset:256
	global_load_dwordx4 v[140:143], v[128:129], off offset:2048
	s_nop 0
	global_load_dwordx4 v[132:135], v[128:129], off offset:2304
	global_load_dwordx4 v[136:139], v[168:169], off
	s_nop 0
	global_load_dwordx4 v[128:131], v[168:169], off offset:256
	s_and_b64 vcc, exec, s[18:19]
	s_mov_b32 s0, s14
	s_mov_b32 s38, s12
	s_mov_b32 s15, s14
	s_mov_b32 s18, s12
	s_mov_b64 s[22:23], s[20:21]
	s_mov_b64 s[10:11], s[16:17]
	s_mov_b32 s13, s37
	s_nop 7
	s_nop 2
	s_waitcnt vmcnt(0)
	v_lshlrev_b32_e32 v228, 16, v184
	v_lshlrev_b32_e32 v226, 16, v180
	v_and_b32_e32 v227, 0xffff0000, v180
	v_and_b32_e32 v229, 0xffff0000, v184
	v_lshlrev_b32_e32 v180, 16, v181
	v_and_b32_e32 v181, 0xffff0000, v181
	v_lshlrev_b32_e32 v184, 16, v185
	v_and_b32_e32 v185, 0xffff0000, v185
	v_lshlrev_b32_e32 v230, 16, v182
	v_and_b32_e32 v231, 0xffff0000, v182
	v_lshlrev_b32_e32 v232, 16, v186
	v_and_b32_e32 v233, 0xffff0000, v186
	v_lshlrev_b32_e32 v182, 16, v183
	v_and_b32_e32 v183, 0xffff0000, v183
	v_lshlrev_b32_e32 v186, 16, v187
	v_and_b32_e32 v187, 0xffff0000, v187
	v_lshlrev_b32_e32 v234, 16, v188
	v_and_b32_e32 v235, 0xffff0000, v188
	v_lshlrev_b32_e32 v236, 16, v192
	v_and_b32_e32 v237, 0xffff0000, v192
	v_lshlrev_b32_e32 v188, 16, v189
	v_and_b32_e32 v189, 0xffff0000, v189
	v_lshlrev_b32_e32 v192, 16, v193
	v_and_b32_e32 v193, 0xffff0000, v193
	v_pk_fma_f32 v[124:125], v[124:125], v[226:227], v[228:229]
	v_pk_fma_f32 v[126:127], v[126:127], v[180:181], v[184:185]
	v_pk_fma_f32 v[120:121], v[120:121], v[230:231], v[232:233]
	v_pk_fma_f32 v[122:123], v[122:123], v[182:183], v[186:187]
	v_lshlrev_b32_e32 v238, 16, v190
	v_and_b32_e32 v239, 0xffff0000, v190
	v_lshlrev_b32_e32 v240, 16, v194
	v_pk_fma_f32 v[180:181], v[116:117], v[234:235], v[236:237]
	v_pk_fma_f32 v[182:183], v[118:119], v[188:189], v[192:193]
	v_cvt_pk_bf16_f32 v116, v124, v125
	v_cvt_pk_bf16_f32 v117, v126, v127
	v_cvt_pk_bf16_f32 v118, v120, v121
	v_cvt_pk_bf16_f32 v119, v122, v123
	v_and_b32_e32 v241, 0xffff0000, v194
	global_store_dwordx4 v[222:223], v[116:119], off
	s_nop 1
	v_pk_fma_f32 v[116:117], v[112:113], v[238:239], v[240:241]
	v_lshlrev_b32_e32 v112, 16, v191
	v_and_b32_e32 v113, 0xffff0000, v191
	v_lshlrev_b32_e32 v118, 16, v195
	v_and_b32_e32 v119, 0xffff0000, v195
	v_pk_fma_f32 v[118:119], v[114:115], v[112:113], v[118:119]
	v_cvt_pk_bf16_f32 v112, v180, v181
	v_cvt_pk_bf16_f32 v113, v182, v183
	v_cvt_pk_bf16_f32 v114, v116, v117
	v_cvt_pk_bf16_f32 v115, v118, v119
	global_store_dwordx4 v[222:223], v[112:115], off offset:256
	s_nop 1
	v_lshlrev_b32_e32 v112, 16, v196
	v_and_b32_e32 v113, 0xffff0000, v196
	v_lshlrev_b32_e32 v114, 16, v200
	v_and_b32_e32 v115, 0xffff0000, v200
	v_pk_fma_f32 v[108:109], v[108:109], v[112:113], v[114:115]
	v_lshlrev_b32_e32 v112, 16, v197
	v_and_b32_e32 v113, 0xffff0000, v197
	v_lshlrev_b32_e32 v114, 16, v201
	v_and_b32_e32 v115, 0xffff0000, v201
	v_pk_fma_f32 v[110:111], v[110:111], v[112:113], v[114:115]
	v_lshlrev_b32_e32 v112, 16, v198
	v_and_b32_e32 v113, 0xffff0000, v198
	v_lshlrev_b32_e32 v114, 16, v202
	v_and_b32_e32 v115, 0xffff0000, v202
	v_pk_fma_f32 v[112:113], v[104:105], v[112:113], v[114:115]
	v_lshlrev_b32_e32 v104, 16, v199
	v_and_b32_e32 v105, 0xffff0000, v199
	v_lshlrev_b32_e32 v114, 16, v203
	v_and_b32_e32 v115, 0xffff0000, v203
	v_pk_fma_f32 v[114:115], v[106:107], v[104:105], v[114:115]
	v_cvt_pk_bf16_f32 v104, v108, v109
	v_cvt_pk_bf16_f32 v105, v110, v111
	v_cvt_pk_bf16_f32 v106, v112, v113
	v_cvt_pk_bf16_f32 v107, v114, v115
	global_store_dwordx4 v[224:225], v[104:107], off
	s_nop 1
	v_lshlrev_b32_e32 v104, 16, v204
	v_and_b32_e32 v105, 0xffff0000, v204
	v_lshlrev_b32_e32 v106, 16, v208
	v_and_b32_e32 v107, 0xffff0000, v208
	v_pk_fma_f32 v[100:101], v[100:101], v[104:105], v[106:107]
	v_lshlrev_b32_e32 v104, 16, v205
	v_and_b32_e32 v105, 0xffff0000, v205
	v_lshlrev_b32_e32 v106, 16, v209
	v_and_b32_e32 v107, 0xffff0000, v209
	v_pk_fma_f32 v[102:103], v[102:103], v[104:105], v[106:107]
	v_lshlrev_b32_e32 v104, 16, v206
	v_and_b32_e32 v105, 0xffff0000, v206
	v_lshlrev_b32_e32 v106, 16, v210
	v_and_b32_e32 v107, 0xffff0000, v210
	v_pk_fma_f32 v[104:105], v[96:97], v[104:105], v[106:107]
	v_lshlrev_b32_e32 v96, 16, v207
	v_and_b32_e32 v97, 0xffff0000, v207
	v_lshlrev_b32_e32 v106, 16, v211
	v_and_b32_e32 v107, 0xffff0000, v211
	v_pk_fma_f32 v[106:107], v[98:99], v[96:97], v[106:107]
	v_cvt_pk_bf16_f32 v96, v100, v101
	v_cvt_pk_bf16_f32 v97, v102, v103
	v_cvt_pk_bf16_f32 v98, v104, v105
	v_cvt_pk_bf16_f32 v99, v106, v107
	global_store_dwordx4 v[224:225], v[96:99], off offset:256
	s_nop 1
	v_lshlrev_b32_e32 v96, 16, v212
	v_and_b32_e32 v97, 0xffff0000, v212
	v_lshlrev_b32_e32 v98, 16, v216
	v_and_b32_e32 v99, 0xffff0000, v216
	v_pk_fma_f32 v[92:93], v[92:93], v[96:97], v[98:99]
	v_lshlrev_b32_e32 v96, 16, v213
	v_and_b32_e32 v97, 0xffff0000, v213
	v_lshlrev_b32_e32 v98, 16, v217
	v_and_b32_e32 v99, 0xffff0000, v217
	v_pk_fma_f32 v[94:95], v[94:95], v[96:97], v[98:99]
	v_lshlrev_b32_e32 v96, 16, v214
	v_and_b32_e32 v97, 0xffff0000, v214
	v_lshlrev_b32_e32 v98, 16, v218
	v_and_b32_e32 v99, 0xffff0000, v218
	v_pk_fma_f32 v[96:97], v[88:89], v[96:97], v[98:99]
	v_lshlrev_b32_e32 v88, 16, v215
	v_and_b32_e32 v89, 0xffff0000, v215
	v_lshlrev_b32_e32 v98, 16, v219
	v_and_b32_e32 v99, 0xffff0000, v219
	v_pk_fma_f32 v[98:99], v[90:91], v[88:89], v[98:99]
	v_cvt_pk_bf16_f32 v88, v92, v93
	v_cvt_pk_bf16_f32 v89, v94, v95
	v_cvt_pk_bf16_f32 v90, v96, v97
	v_cvt_pk_bf16_f32 v91, v98, v99
	global_store_dwordx4 v[170:171], v[88:91], off
	s_nop 1
	v_lshlrev_b32_e32 v88, 16, v148
	v_and_b32_e32 v89, 0xffff0000, v148
	v_lshlrev_b32_e32 v90, 16, v144
	v_and_b32_e32 v91, 0xffff0000, v144
	v_pk_fma_f32 v[84:85], v[84:85], v[88:89], v[90:91]
	v_lshlrev_b32_e32 v88, 16, v149
	v_and_b32_e32 v89, 0xffff0000, v149
	v_lshlrev_b32_e32 v90, 16, v145
	v_and_b32_e32 v91, 0xffff0000, v145
	v_pk_fma_f32 v[86:87], v[86:87], v[88:89], v[90:91]
	v_lshlrev_b32_e32 v88, 16, v150
	v_and_b32_e32 v89, 0xffff0000, v150
	v_lshlrev_b32_e32 v90, 16, v146
	v_and_b32_e32 v91, 0xffff0000, v146
	v_pk_fma_f32 v[88:89], v[80:81], v[88:89], v[90:91]
	v_lshlrev_b32_e32 v80, 16, v151
	v_and_b32_e32 v81, 0xffff0000, v151
	v_lshlrev_b32_e32 v90, 16, v147
	v_and_b32_e32 v91, 0xffff0000, v147
	v_pk_fma_f32 v[90:91], v[82:83], v[80:81], v[90:91]
	v_cvt_pk_bf16_f32 v80, v84, v85
	v_cvt_pk_bf16_f32 v81, v86, v87
	v_cvt_pk_bf16_f32 v82, v88, v89
	v_cvt_pk_bf16_f32 v83, v90, v91
	global_store_dwordx4 v[170:171], v[80:83], off offset:256
	s_nop 1
	v_lshlrev_b32_e32 v80, 16, v140
	v_and_b32_e32 v81, 0xffff0000, v140
	v_lshlrev_b32_e32 v82, 16, v136
	v_and_b32_e32 v83, 0xffff0000, v136
	v_pk_fma_f32 v[76:77], v[76:77], v[80:81], v[82:83]
	v_lshlrev_b32_e32 v80, 16, v141
	v_and_b32_e32 v81, 0xffff0000, v141
	v_lshlrev_b32_e32 v82, 16, v137
	v_and_b32_e32 v83, 0xffff0000, v137
	v_pk_fma_f32 v[78:79], v[78:79], v[80:81], v[82:83]
	v_lshlrev_b32_e32 v80, 16, v142
	v_and_b32_e32 v81, 0xffff0000, v142
	v_lshlrev_b32_e32 v82, 16, v138
	v_and_b32_e32 v83, 0xffff0000, v138
	v_pk_fma_f32 v[80:81], v[72:73], v[80:81], v[82:83]
	v_lshlrev_b32_e32 v72, 16, v143
	v_and_b32_e32 v73, 0xffff0000, v143
	v_lshlrev_b32_e32 v82, 16, v139
	v_and_b32_e32 v83, 0xffff0000, v139
	v_pk_fma_f32 v[82:83], v[74:75], v[72:73], v[82:83]
	v_cvt_pk_bf16_f32 v72, v76, v77
	v_cvt_pk_bf16_f32 v73, v78, v79
	v_cvt_pk_bf16_f32 v74, v80, v81
	v_cvt_pk_bf16_f32 v75, v82, v83
	global_store_dwordx4 v[168:169], v[72:75], off
	s_nop 1
	v_lshlrev_b32_e32 v72, 16, v132
	v_and_b32_e32 v73, 0xffff0000, v132
	v_lshlrev_b32_e32 v74, 16, v128
	v_and_b32_e32 v75, 0xffff0000, v128
	v_pk_fma_f32 v[68:69], v[68:69], v[72:73], v[74:75]
	v_lshlrev_b32_e32 v72, 16, v133
	v_and_b32_e32 v73, 0xffff0000, v133
	v_lshlrev_b32_e32 v74, 16, v129
	v_and_b32_e32 v75, 0xffff0000, v129
	v_pk_fma_f32 v[70:71], v[70:71], v[72:73], v[74:75]
	v_lshlrev_b32_e32 v72, 16, v134
	v_and_b32_e32 v73, 0xffff0000, v134
	v_lshlrev_b32_e32 v74, 16, v130
	v_and_b32_e32 v75, 0xffff0000, v130
	v_pk_fma_f32 v[72:73], v[64:65], v[72:73], v[74:75]
	v_lshlrev_b32_e32 v64, 16, v135
	v_and_b32_e32 v65, 0xffff0000, v135
	v_lshlrev_b32_e32 v74, 16, v131
	v_and_b32_e32 v75, 0xffff0000, v131
	v_pk_fma_f32 v[74:75], v[66:67], v[64:65], v[74:75]
	v_cvt_pk_bf16_f32 v64, v68, v69
	v_cvt_pk_bf16_f32 v65, v70, v71
	v_cvt_pk_bf16_f32 v66, v72, v73
	v_cvt_pk_bf16_f32 v67, v74, v75
	global_store_dwordx4 v[168:169], v[64:67], off offset:256
	s_nop 1
	v_add_u32_e32 v64, 0x80, v164
	v_ashrrev_i32_e32 v65, 31, v64
	v_lshlrev_b64 v[66:67], 12, v[64:65]
	v_lshl_add_u64 v[66:67], s[42:43], 0, v[66:67]
	v_lshlrev_b64 v[64:65], 11, v[64:65]
	v_lshl_add_u64 v[66:67], v[66:67], 0, v[166:167]
	v_lshl_add_u64 v[64:65], s[82:83], 0, v[64:65]
	global_load_dwordx4 v[92:95], v[66:67], off offset:2048
	v_lshl_add_u64 v[132:133], v[64:65], 0, v[166:167]
	global_load_dwordx4 v[96:99], v[132:133], off
	global_load_dwordx4 v[100:103], v[66:67], off offset:2304
	global_load_dwordx4 v[104:107], v[132:133], off offset:256
	v_add_u32_e32 v64, 0x90, v164
	v_ashrrev_i32_e32 v65, 31, v64
	v_lshlrev_b64 v[66:67], 12, v[64:65]
	v_lshl_add_u64 v[66:67], s[42:43], 0, v[66:67]
	v_lshlrev_b64 v[64:65], 11, v[64:65]
	v_lshl_add_u64 v[66:67], v[66:67], 0, v[166:167]
	v_lshl_add_u64 v[64:65], s[82:83], 0, v[64:65]
	global_load_dwordx4 v[108:111], v[66:67], off offset:2048
	v_lshl_add_u64 v[134:135], v[64:65], 0, v[166:167]
	global_load_dwordx4 v[112:115], v[134:135], off
	global_load_dwordx4 v[116:119], v[66:67], off offset:2304
	global_load_dwordx4 v[120:123], v[134:135], off offset:256
	v_add_u32_e32 v64, 0xa0, v164
	v_ashrrev_i32_e32 v65, 31, v64
	v_lshlrev_b64 v[66:67], 12, v[64:65]
	v_lshl_add_u64 v[66:67], s[42:43], 0, v[66:67]
	v_lshlrev_b64 v[64:65], 11, v[64:65]
	v_lshl_add_u64 v[64:65], s[82:83], 0, v[64:65]
	v_lshl_add_u64 v[66:67], v[66:67], 0, v[166:167]
	v_lshl_add_u64 v[90:91], v[64:65], 0, v[166:167]
	global_load_dwordx4 v[124:127], v[66:67], off offset:2048
	global_load_dwordx4 v[84:87], v[66:67], off offset:2304
	global_load_dwordx4 v[128:131], v[90:91], off
	global_load_dwordx4 v[80:83], v[90:91], off offset:256
	v_add_u32_e32 v64, 0xb0, v164
	v_ashrrev_i32_e32 v65, 31, v64
	v_lshlrev_b64 v[66:67], 12, v[64:65]
	v_lshl_add_u64 v[66:67], s[42:43], 0, v[66:67]
	v_lshlrev_b64 v[64:65], 11, v[64:65]
	v_lshl_add_u64 v[64:65], s[82:83], 0, v[64:65]
	v_lshl_add_u64 v[66:67], v[66:67], 0, v[166:167]
	v_lshl_add_u64 v[88:89], v[64:65], 0, v[166:167]
	global_load_dwordx4 v[76:79], v[66:67], off offset:2048
	global_load_dwordx4 v[68:71], v[66:67], off offset:2304
	global_load_dwordx4 v[72:75], v[88:89], off
	s_nop 0
	global_load_dwordx4 v[64:67], v[88:89], off offset:256
	s_waitcnt vmcnt(0)
	v_lshlrev_b32_e32 v136, 16, v92
	v_and_b32_e32 v137, 0xffff0000, v92
	v_lshlrev_b32_e32 v138, 16, v96
	v_and_b32_e32 v139, 0xffff0000, v96
	v_lshlrev_b32_e32 v92, 16, v93
	v_and_b32_e32 v93, 0xffff0000, v93
	v_lshlrev_b32_e32 v96, 16, v97
	v_and_b32_e32 v97, 0xffff0000, v97
	v_pk_fma_f32 v[62:63], v[62:63], v[92:93], v[96:97]
	v_lshlrev_b32_e32 v92, 16, v94
	v_and_b32_e32 v93, 0xffff0000, v94
	v_lshlrev_b32_e32 v96, 16, v98
	v_and_b32_e32 v97, 0xffff0000, v98
	v_pk_fma_f32 v[92:93], v[56:57], v[92:93], v[96:97]
	v_lshlrev_b32_e32 v56, 16, v95
	v_and_b32_e32 v57, 0xffff0000, v95
	v_lshlrev_b32_e32 v94, 16, v99
	v_and_b32_e32 v95, 0xffff0000, v99
	v_pk_fma_f32 v[60:61], v[60:61], v[136:137], v[138:139]
	v_pk_fma_f32 v[94:95], v[58:59], v[56:57], v[94:95]
	v_cvt_pk_bf16_f32 v56, v60, v61
	v_cvt_pk_bf16_f32 v57, v62, v63
	v_cvt_pk_bf16_f32 v58, v92, v93
	v_cvt_pk_bf16_f32 v59, v94, v95
	global_store_dwordx4 v[132:133], v[56:59], off
	s_nop 1
	v_lshlrev_b32_e32 v56, 16, v100
	v_and_b32_e32 v57, 0xffff0000, v100
	v_lshlrev_b32_e32 v58, 16, v104
	v_and_b32_e32 v59, 0xffff0000, v104
	v_pk_fma_f32 v[52:53], v[52:53], v[56:57], v[58:59]
	v_lshlrev_b32_e32 v56, 16, v101
	v_and_b32_e32 v57, 0xffff0000, v101
	v_lshlrev_b32_e32 v58, 16, v105
	v_and_b32_e32 v59, 0xffff0000, v105
	v_pk_fma_f32 v[54:55], v[54:55], v[56:57], v[58:59]
	v_lshlrev_b32_e32 v56, 16, v102
	v_and_b32_e32 v57, 0xffff0000, v102
	v_lshlrev_b32_e32 v58, 16, v106
	v_and_b32_e32 v59, 0xffff0000, v106
	v_pk_fma_f32 v[56:57], v[48:49], v[56:57], v[58:59]
	v_lshlrev_b32_e32 v48, 16, v103
	v_and_b32_e32 v49, 0xffff0000, v103
	v_lshlrev_b32_e32 v58, 16, v107
	v_and_b32_e32 v59, 0xffff0000, v107
	v_pk_fma_f32 v[58:59], v[50:51], v[48:49], v[58:59]
	v_cvt_pk_bf16_f32 v48, v52, v53
	v_cvt_pk_bf16_f32 v49, v54, v55
	v_cvt_pk_bf16_f32 v50, v56, v57
	v_cvt_pk_bf16_f32 v51, v58, v59
	global_store_dwordx4 v[132:133], v[48:51], off offset:256
	s_nop 1
	v_lshlrev_b32_e32 v48, 16, v108
	v_and_b32_e32 v49, 0xffff0000, v108
	v_lshlrev_b32_e32 v50, 16, v112
	v_and_b32_e32 v51, 0xffff0000, v112
	v_pk_fma_f32 v[44:45], v[44:45], v[48:49], v[50:51]
	v_lshlrev_b32_e32 v48, 16, v109
	v_and_b32_e32 v49, 0xffff0000, v109
	v_lshlrev_b32_e32 v50, 16, v113
	v_and_b32_e32 v51, 0xffff0000, v113
	v_pk_fma_f32 v[46:47], v[46:47], v[48:49], v[50:51]
	v_lshlrev_b32_e32 v48, 16, v110
	v_and_b32_e32 v49, 0xffff0000, v110
	v_lshlrev_b32_e32 v50, 16, v114
	v_and_b32_e32 v51, 0xffff0000, v114
	v_pk_fma_f32 v[48:49], v[40:41], v[48:49], v[50:51]
	v_lshlrev_b32_e32 v40, 16, v111
	v_and_b32_e32 v41, 0xffff0000, v111
	v_lshlrev_b32_e32 v50, 16, v115
	v_and_b32_e32 v51, 0xffff0000, v115
	v_pk_fma_f32 v[50:51], v[42:43], v[40:41], v[50:51]
	v_cvt_pk_bf16_f32 v40, v44, v45
	v_cvt_pk_bf16_f32 v41, v46, v47
	v_cvt_pk_bf16_f32 v42, v48, v49
	v_cvt_pk_bf16_f32 v43, v50, v51
	global_store_dwordx4 v[134:135], v[40:43], off
	s_nop 1
	v_lshlrev_b32_e32 v40, 16, v116
	v_and_b32_e32 v41, 0xffff0000, v116
	v_lshlrev_b32_e32 v42, 16, v120
	v_and_b32_e32 v43, 0xffff0000, v120
	v_pk_fma_f32 v[36:37], v[36:37], v[40:41], v[42:43]
	v_lshlrev_b32_e32 v40, 16, v117
	v_and_b32_e32 v41, 0xffff0000, v117
	v_lshlrev_b32_e32 v42, 16, v121
	v_and_b32_e32 v43, 0xffff0000, v121
	v_pk_fma_f32 v[38:39], v[38:39], v[40:41], v[42:43]
	v_lshlrev_b32_e32 v40, 16, v118
	v_and_b32_e32 v41, 0xffff0000, v118
	v_lshlrev_b32_e32 v42, 16, v122
	v_and_b32_e32 v43, 0xffff0000, v122
	v_pk_fma_f32 v[40:41], v[32:33], v[40:41], v[42:43]
	v_lshlrev_b32_e32 v32, 16, v119
	v_and_b32_e32 v33, 0xffff0000, v119
	v_lshlrev_b32_e32 v42, 16, v123
	v_and_b32_e32 v43, 0xffff0000, v123
	v_pk_fma_f32 v[42:43], v[34:35], v[32:33], v[42:43]
	v_cvt_pk_bf16_f32 v32, v36, v37
	v_cvt_pk_bf16_f32 v33, v38, v39
	v_cvt_pk_bf16_f32 v34, v40, v41
	v_cvt_pk_bf16_f32 v35, v42, v43
	global_store_dwordx4 v[134:135], v[32:35], off offset:256
	s_nop 1
	v_lshlrev_b32_e32 v32, 16, v124
	v_and_b32_e32 v33, 0xffff0000, v124
	v_lshlrev_b32_e32 v34, 16, v128
	v_and_b32_e32 v35, 0xffff0000, v128
	v_pk_fma_f32 v[28:29], v[28:29], v[32:33], v[34:35]
	v_lshlrev_b32_e32 v32, 16, v125
	v_and_b32_e32 v33, 0xffff0000, v125
	v_lshlrev_b32_e32 v34, 16, v129
	v_and_b32_e32 v35, 0xffff0000, v129
	v_pk_fma_f32 v[30:31], v[30:31], v[32:33], v[34:35]
	v_lshlrev_b32_e32 v32, 16, v126
	v_and_b32_e32 v33, 0xffff0000, v126
	v_lshlrev_b32_e32 v34, 16, v130
	v_and_b32_e32 v35, 0xffff0000, v130
	v_pk_fma_f32 v[32:33], v[24:25], v[32:33], v[34:35]
	v_lshlrev_b32_e32 v24, 16, v127
	v_and_b32_e32 v25, 0xffff0000, v127
	v_lshlrev_b32_e32 v34, 16, v131
	v_and_b32_e32 v35, 0xffff0000, v131
	v_pk_fma_f32 v[34:35], v[26:27], v[24:25], v[34:35]
	v_cvt_pk_bf16_f32 v24, v28, v29
	v_cvt_pk_bf16_f32 v25, v30, v31
	v_cvt_pk_bf16_f32 v26, v32, v33
	v_cvt_pk_bf16_f32 v27, v34, v35
	global_store_dwordx4 v[90:91], v[24:27], off
	s_nop 1
	v_lshlrev_b32_e32 v24, 16, v84
	v_and_b32_e32 v25, 0xffff0000, v84
	v_lshlrev_b32_e32 v26, 16, v80
	v_and_b32_e32 v27, 0xffff0000, v80
	v_pk_fma_f32 v[20:21], v[20:21], v[24:25], v[26:27]
	v_lshlrev_b32_e32 v24, 16, v85
	v_and_b32_e32 v25, 0xffff0000, v85
	v_lshlrev_b32_e32 v26, 16, v81
	v_and_b32_e32 v27, 0xffff0000, v81
	v_pk_fma_f32 v[22:23], v[22:23], v[24:25], v[26:27]
	v_lshlrev_b32_e32 v24, 16, v86
	v_and_b32_e32 v25, 0xffff0000, v86
	v_lshlrev_b32_e32 v26, 16, v82
	v_and_b32_e32 v27, 0xffff0000, v82
	v_pk_fma_f32 v[24:25], v[16:17], v[24:25], v[26:27]
	v_lshlrev_b32_e32 v16, 16, v87
	v_and_b32_e32 v17, 0xffff0000, v87
	v_lshlrev_b32_e32 v26, 16, v83
	v_and_b32_e32 v27, 0xffff0000, v83
	v_pk_fma_f32 v[26:27], v[18:19], v[16:17], v[26:27]
	v_cvt_pk_bf16_f32 v16, v20, v21
	v_cvt_pk_bf16_f32 v17, v22, v23
	v_cvt_pk_bf16_f32 v18, v24, v25
	v_cvt_pk_bf16_f32 v19, v26, v27
	global_store_dwordx4 v[90:91], v[16:19], off offset:256
	s_nop 1
	v_lshlrev_b32_e32 v16, 16, v76
	v_and_b32_e32 v17, 0xffff0000, v76
	v_lshlrev_b32_e32 v18, 16, v72
	v_and_b32_e32 v19, 0xffff0000, v72
	v_pk_fma_f32 v[12:13], v[12:13], v[16:17], v[18:19]
	v_lshlrev_b32_e32 v16, 16, v77
	v_and_b32_e32 v17, 0xffff0000, v77
	v_lshlrev_b32_e32 v18, 16, v73
	v_and_b32_e32 v19, 0xffff0000, v73
	v_pk_fma_f32 v[14:15], v[14:15], v[16:17], v[18:19]
	v_lshlrev_b32_e32 v16, 16, v78
	v_and_b32_e32 v17, 0xffff0000, v78
	v_lshlrev_b32_e32 v18, 16, v74
	v_and_b32_e32 v19, 0xffff0000, v74
	v_pk_fma_f32 v[16:17], v[8:9], v[16:17], v[18:19]
	v_lshlrev_b32_e32 v8, 16, v79
	v_and_b32_e32 v9, 0xffff0000, v79
	v_lshlrev_b32_e32 v18, 16, v75
	v_and_b32_e32 v19, 0xffff0000, v75
	v_pk_fma_f32 v[18:19], v[10:11], v[8:9], v[18:19]
	v_cvt_pk_bf16_f32 v8, v12, v13
	v_cvt_pk_bf16_f32 v9, v14, v15
	v_cvt_pk_bf16_f32 v10, v16, v17
	v_cvt_pk_bf16_f32 v11, v18, v19
	global_store_dwordx4 v[88:89], v[8:11], off
	s_nop 1
	v_lshlrev_b32_e32 v8, 16, v68
	v_and_b32_e32 v9, 0xffff0000, v68
	v_lshlrev_b32_e32 v10, 16, v64
	v_and_b32_e32 v11, 0xffff0000, v64
	v_pk_fma_f32 v[4:5], v[4:5], v[8:9], v[10:11]
	v_lshlrev_b32_e32 v8, 16, v69
	v_and_b32_e32 v9, 0xffff0000, v69
	v_lshlrev_b32_e32 v10, 16, v65
	v_and_b32_e32 v11, 0xffff0000, v65
	v_pk_fma_f32 v[6:7], v[6:7], v[8:9], v[10:11]
	v_lshlrev_b32_e32 v8, 16, v70
	v_and_b32_e32 v9, 0xffff0000, v70
	v_lshlrev_b32_e32 v10, 16, v66
	v_and_b32_e32 v11, 0xffff0000, v66
	v_pk_fma_f32 v[8:9], v[0:1], v[8:9], v[10:11]
	v_lshlrev_b32_e32 v0, 16, v71
	v_and_b32_e32 v1, 0xffff0000, v71
	v_lshlrev_b32_e32 v10, 16, v67
	v_and_b32_e32 v11, 0xffff0000, v67
	v_pk_fma_f32 v[10:11], v[2:3], v[0:1], v[10:11]
	v_cvt_pk_bf16_f32 v0, v4, v5
	v_cvt_pk_bf16_f32 v1, v6, v7
	v_cvt_pk_bf16_f32 v2, v8, v9
	v_cvt_pk_bf16_f32 v3, v10, v11
	global_store_dwordx4 v[88:89], v[0:3], off offset:256
	s_cbranch_vccz .LBB0_1277
	s_waitcnt vmcnt(0)
	s_cmpk_gt_u32 s26, 0xff
	s_cbranch_scc1 .LBB0_1289
	s_barrier

.LBB0_1356:
	ds_read_b128 v[128:131], v189
	ds_read_b128 v[132:135], v189 offset:1024
	ds_read_b128 v[136:139], v189 offset:2048
	ds_read_b128 v[140:143], v189 offset:3072
	s_add_u32 s24, s10, 0xfffc0080
	s_addc_u32 s25, s11, -1
	s_cmp_eq_u32 s47, 12
	s_cselect_b32 s27, s15, s25
	s_cselect_b32 s26, s29, s24
	s_cselect_b32 s25, s17, s46
	s_cselect_b32 s24, s44, s45
	v_lshl_add_u64 v[198:199], s[10:11], 0, v[162:163]
	s_add_i32 m0, s7, 0xc000
	ds_read_b128 v[144:147], v190
	ds_read_b128 v[148:151], v190 offset:1024
	ds_read_b128 v[166:169], v190 offset:2048
	ds_read_b128 v[170:173], v190 offset:3072
	ds_read_b128 v[174:177], v190 offset:4096
	ds_read_b128 v[180:183], v190 offset:5120
	ds_read_b128 v[184:187], v190 offset:6144
	ds_read_b128 v[194:197], v190 offset:7168
	global_load_lds_dwordx4 v[198:199], off
	v_lshl_add_u64 v[198:199], s[10:11], 0, v[164:165]
	s_add_i32 m0, s7, 0xe000
	s_nop 0
	global_load_lds_dwordx4 v[198:199], off
	s_waitcnt lgkmcnt(8)
	s_barrier
	s_waitcnt lgkmcnt(0)
	s_setprio 1
	v_mfma_f32_16x16x32_bf16 v[124:127], v[128:131], v[144:147], v[124:127]
	v_mfma_f32_16x16x32_bf16 v[120:123], v[136:139], v[144:147], v[120:123]
	v_mfma_f32_16x16x32_bf16 v[108:111], v[128:131], v[166:169], v[108:111]
	v_mfma_f32_16x16x32_bf16 v[104:107], v[136:139], v[166:169], v[104:107]
	v_mfma_f32_16x16x32_bf16 v[92:95], v[128:131], v[174:177], v[92:95]
	v_mfma_f32_16x16x32_bf16 v[88:91], v[136:139], v[174:177], v[88:91]
	v_mfma_f32_16x16x32_bf16 v[76:79], v[128:131], v[184:187], v[76:79]
	v_mfma_f32_16x16x32_bf16 v[72:75], v[136:139], v[184:187], v[72:75]
	v_mfma_f32_16x16x32_bf16 v[124:127], v[132:135], v[148:151], v[124:127]
	v_mfma_f32_16x16x32_bf16 v[120:123], v[140:143], v[148:151], v[120:123]
	v_mfma_f32_16x16x32_bf16 v[108:111], v[132:135], v[170:173], v[108:111]
	v_mfma_f32_16x16x32_bf16 v[104:107], v[140:143], v[170:173], v[104:107]
	v_mfma_f32_16x16x32_bf16 v[92:95], v[132:135], v[180:183], v[92:95]
	v_mfma_f32_16x16x32_bf16 v[88:91], v[140:143], v[180:183], v[88:91]
	v_mfma_f32_16x16x32_bf16 v[76:79], v[132:135], v[194:197], v[76:79]
	v_mfma_f32_16x16x32_bf16 v[72:75], v[140:143], v[194:197], v[72:75]
	s_setprio 0
	s_barrier
	s_add_i32 s48, s41, s33
	v_lshl_add_u64 v[214:215], s[24:25], 0, v[156:157]
	s_mov_b32 m0, s48
	ds_read_b128 v[198:201], v191
	ds_read_b128 v[202:205], v191 offset:1024
	ds_read_b128 v[206:209], v191 offset:2048
	ds_read_b128 v[210:213], v191 offset:3072
	global_load_lds_dwordx4 v[214:215], off
	v_lshl_add_u64 v[216:217], s[24:25], 0, v[152:153]
	s_add_i32 m0, s48, 0x2000
	s_nop 0
	global_load_lds_dwordx4 v[216:217], off
	s_barrier
	s_waitcnt lgkmcnt(0)
	s_setprio 1
	v_mfma_f32_16x16x32_bf16 v[116:119], v[198:201], v[144:147], v[116:119]
	v_mfma_f32_16x16x32_bf16 v[112:115], v[206:209], v[144:147], v[112:115]
	v_mfma_f32_16x16x32_bf16 v[100:103], v[198:201], v[166:169], v[100:103]
	v_mfma_f32_16x16x32_bf16 v[96:99], v[206:209], v[166:169], v[96:99]
	v_mfma_f32_16x16x32_bf16 v[84:87], v[198:201], v[174:177], v[84:87]
	v_mfma_f32_16x16x32_bf16 v[80:83], v[206:209], v[174:177], v[80:83]
	v_mfma_f32_16x16x32_bf16 v[68:71], v[198:201], v[184:187], v[68:71]
	v_mfma_f32_16x16x32_bf16 v[64:67], v[206:209], v[184:187], v[64:67]
	v_mfma_f32_16x16x32_bf16 v[116:119], v[202:205], v[148:151], v[116:119]
	v_mfma_f32_16x16x32_bf16 v[112:115], v[210:213], v[148:151], v[112:115]
	v_mfma_f32_16x16x32_bf16 v[100:103], v[202:205], v[170:173], v[100:103]
	v_mfma_f32_16x16x32_bf16 v[96:99], v[210:213], v[170:173], v[96:99]
	v_mfma_f32_16x16x32_bf16 v[84:87], v[202:205], v[180:183], v[84:87]
	v_mfma_f32_16x16x32_bf16 v[80:83], v[210:213], v[180:183], v[80:83]
	v_mfma_f32_16x16x32_bf16 v[68:71], v[202:205], v[194:197], v[68:71]
	v_mfma_f32_16x16x32_bf16 v[64:67], v[210:213], v[194:197], v[64:67]
	s_setprio 0
	s_mov_b32 m0, s7
	v_lshl_add_u64 v[218:219], s[26:27], 0, v[158:159]
	s_barrier
	ds_read_b128 v[144:147], v190 offset:16384
	ds_read_b128 v[148:151], v190 offset:17408
	ds_read_b128 v[166:169], v190 offset:18432
	ds_read_b128 v[170:173], v190 offset:19456
	ds_read_b128 v[174:177], v190 offset:20480
	ds_read_b128 v[180:183], v190 offset:21504
	ds_read_b128 v[184:187], v190 offset:22528
	ds_read_b128 v[194:197], v190 offset:23552
	global_load_lds_dwordx4 v[218:219], off
	v_lshl_add_u64 v[222:223], s[26:27], 0, v[154:155]
	s_mov_b32 m0, s35
	s_nop 0
	global_load_lds_dwordx4 v[222:223], off
	s_barrier
	s_waitcnt lgkmcnt(0)
	s_setprio 1
	v_mfma_f32_16x16x32_bf16 v[60:63], v[128:131], v[144:147], v[60:63]
	v_mfma_f32_16x16x32_bf16 v[56:59], v[136:139], v[144:147], v[56:59]
	v_mfma_f32_16x16x32_bf16 v[44:47], v[128:131], v[166:169], v[44:47]
	v_mfma_f32_16x16x32_bf16 v[40:43], v[136:139], v[166:169], v[40:43]
	v_mfma_f32_16x16x32_bf16 v[28:31], v[128:131], v[174:177], v[28:31]
	v_mfma_f32_16x16x32_bf16 v[24:27], v[136:139], v[174:177], v[24:27]
	v_mfma_f32_16x16x32_bf16 v[12:15], v[128:131], v[184:187], v[12:15]
	v_mfma_f32_16x16x32_bf16 v[8:11], v[136:139], v[184:187], v[8:11]
	v_mfma_f32_16x16x32_bf16 v[60:63], v[132:135], v[148:151], v[60:63]
	v_mfma_f32_16x16x32_bf16 v[56:59], v[140:143], v[148:151], v[56:59]
	v_mfma_f32_16x16x32_bf16 v[44:47], v[132:135], v[170:173], v[44:47]
	v_mfma_f32_16x16x32_bf16 v[40:43], v[140:143], v[170:173], v[40:43]
	v_mfma_f32_16x16x32_bf16 v[28:31], v[132:135], v[180:183], v[28:31]
	v_mfma_f32_16x16x32_bf16 v[24:27], v[140:143], v[180:183], v[24:27]
	v_mfma_f32_16x16x32_bf16 v[12:15], v[132:135], v[194:197], v[12:15]
	v_mfma_f32_16x16x32_bf16 v[8:11], v[140:143], v[194:197], v[8:11]
	s_setprio 0
	s_barrier
	s_add_u32 s48, s24, 0x40000
	s_addc_u32 s49, s25, 0
	s_add_i32 s50, s42, s33
	v_lshl_add_u64 v[128:129], s[48:49], 0, v[156:157]
	s_mov_b32 m0, s50
	s_nop 0
	global_load_lds_dwordx4 v[128:129], off
	v_lshl_add_u64 v[128:129], s[48:49], 0, v[152:153]
	s_add_i32 m0, s50, 0x2000
	s_nop 0
	global_load_lds_dwordx4 v[128:129], off
	s_waitcnt vmcnt(6)
	s_barrier
	s_setprio 1
	v_mfma_f32_16x16x32_bf16 v[52:55], v[198:201], v[144:147], v[52:55]
	v_mfma_f32_16x16x32_bf16 v[48:51], v[206:209], v[144:147], v[48:51]
	v_mfma_f32_16x16x32_bf16 v[36:39], v[198:201], v[166:169], v[36:39]
	v_mfma_f32_16x16x32_bf16 v[32:35], v[206:209], v[166:169], v[32:35]
	v_mfma_f32_16x16x32_bf16 v[20:23], v[198:201], v[174:177], v[20:23]
	v_mfma_f32_16x16x32_bf16 v[16:19], v[206:209], v[174:177], v[16:19]
	v_mfma_f32_16x16x32_bf16 v[4:7], v[198:201], v[184:187], v[4:7]
	v_mfma_f32_16x16x32_bf16 v[0:3], v[206:209], v[184:187], v[0:3]
	v_mfma_f32_16x16x32_bf16 v[52:55], v[202:205], v[148:151], v[52:55]
	v_mfma_f32_16x16x32_bf16 v[48:51], v[210:213], v[148:151], v[48:51]
	v_mfma_f32_16x16x32_bf16 v[36:39], v[202:205], v[170:173], v[36:39]
	v_mfma_f32_16x16x32_bf16 v[32:35], v[210:213], v[170:173], v[32:35]
	v_mfma_f32_16x16x32_bf16 v[20:23], v[202:205], v[180:183], v[20:23]
	v_mfma_f32_16x16x32_bf16 v[16:19], v[210:213], v[180:183], v[16:19]
	v_mfma_f32_16x16x32_bf16 v[4:7], v[202:205], v[194:197], v[4:7]
	v_mfma_f32_16x16x32_bf16 v[0:3], v[210:213], v[194:197], v[0:3]
	s_setprio 0
	s_add_i32 s48, 0, 0x18000
	v_add_u32_e32 v140, s48, v188
	s_barrier
	ds_read_b128 v[128:131], v140
	ds_read_b128 v[132:135], v140 offset:1024
	ds_read_b128 v[136:139], v140 offset:2048
	ds_read_b128 v[140:143], v140 offset:3072
	s_add_u32 s26, s26, 0x40000
	s_addc_u32 s27, s27, 0
	s_mov_b32 m0, s36
	v_lshl_add_u64 v[198:199], s[26:27], 0, v[158:159]
	ds_read_b128 v[144:147], v190 offset:32768
	ds_read_b128 v[148:151], v190 offset:33792
	ds_read_b128 v[166:169], v190 offset:34816
	ds_read_b128 v[170:173], v190 offset:35840
	ds_read_b128 v[174:177], v190 offset:36864
	ds_read_b128 v[180:183], v190 offset:37888
	ds_read_b128 v[184:187], v190 offset:38912
	ds_read_b128 v[194:197], v190 offset:39936
	global_load_lds_dwordx4 v[198:199], off
	v_lshl_add_u64 v[198:199], s[26:27], 0, v[154:155]
	s_mov_b32 m0, s37
	s_nop 0
	global_load_lds_dwordx4 v[198:199], off
	s_waitcnt lgkmcnt(8)
	s_barrier
	s_waitcnt lgkmcnt(0)
	s_setprio 1
	v_mfma_f32_16x16x32_bf16 v[124:127], v[128:131], v[144:147], v[124:127]
	v_mfma_f32_16x16x32_bf16 v[120:123], v[136:139], v[144:147], v[120:123]
	v_mfma_f32_16x16x32_bf16 v[108:111], v[128:131], v[166:169], v[108:111]
	v_mfma_f32_16x16x32_bf16 v[104:107], v[136:139], v[166:169], v[104:107]
	v_mfma_f32_16x16x32_bf16 v[92:95], v[128:131], v[174:177], v[92:95]
	v_mfma_f32_16x16x32_bf16 v[88:91], v[136:139], v[174:177], v[88:91]
	v_mfma_f32_16x16x32_bf16 v[76:79], v[128:131], v[184:187], v[76:79]
	v_mfma_f32_16x16x32_bf16 v[72:75], v[136:139], v[184:187], v[72:75]
	v_mfma_f32_16x16x32_bf16 v[124:127], v[132:135], v[148:151], v[124:127]
	v_mfma_f32_16x16x32_bf16 v[120:123], v[140:143], v[148:151], v[120:123]
	v_mfma_f32_16x16x32_bf16 v[108:111], v[132:135], v[170:173], v[108:111]
	v_mfma_f32_16x16x32_bf16 v[104:107], v[140:143], v[170:173], v[104:107]
	v_mfma_f32_16x16x32_bf16 v[92:95], v[132:135], v[180:183], v[92:95]
	v_mfma_f32_16x16x32_bf16 v[88:91], v[140:143], v[180:183], v[88:91]
	v_mfma_f32_16x16x32_bf16 v[76:79], v[132:135], v[194:197], v[76:79]
	v_mfma_f32_16x16x32_bf16 v[72:75], v[140:143], v[194:197], v[72:75]
	s_setprio 0
	s_barrier
	s_add_i32 s26, 0, 0x1c000
	s_add_i32 s27, s48, s33
	v_add_u32_e32 v193, s26, v188
	v_lshl_add_u64 v[214:215], v[214:215], 0, s[12:13]
	s_mov_b32 m0, s27
	ds_read_b128 v[198:201], v193
	ds_read_b128 v[202:205], v193 offset:1024
	ds_read_b128 v[206:209], v193 offset:2048
	ds_read_b128 v[210:213], v193 offset:3072
	global_load_lds_dwordx4 v[214:215], off
	v_lshl_add_u64 v[214:215], v[216:217], 0, s[12:13]
	s_add_i32 m0, s27, 0x2000
	s_nop 0
	global_load_lds_dwordx4 v[214:215], off
	s_barrier
	s_waitcnt lgkmcnt(0)
	s_setprio 1
	v_mfma_f32_16x16x32_bf16 v[116:119], v[198:201], v[144:147], v[116:119]
	v_mfma_f32_16x16x32_bf16 v[112:115], v[206:209], v[144:147], v[112:115]
	v_mfma_f32_16x16x32_bf16 v[100:103], v[198:201], v[166:169], v[100:103]
	v_mfma_f32_16x16x32_bf16 v[96:99], v[206:209], v[166:169], v[96:99]
	v_mfma_f32_16x16x32_bf16 v[84:87], v[198:201], v[174:177], v[84:87]
	v_mfma_f32_16x16x32_bf16 v[80:83], v[206:209], v[174:177], v[80:83]
	v_mfma_f32_16x16x32_bf16 v[68:71], v[198:201], v[184:187], v[68:71]
	v_mfma_f32_16x16x32_bf16 v[64:67], v[206:209], v[184:187], v[64:67]
	v_mfma_f32_16x16x32_bf16 v[116:119], v[202:205], v[148:151], v[116:119]
	v_mfma_f32_16x16x32_bf16 v[112:115], v[210:213], v[148:151], v[112:115]
	v_mfma_f32_16x16x32_bf16 v[100:103], v[202:205], v[170:173], v[100:103]
	v_mfma_f32_16x16x32_bf16 v[96:99], v[210:213], v[170:173], v[96:99]
	v_mfma_f32_16x16x32_bf16 v[84:87], v[202:205], v[180:183], v[84:87]
	v_mfma_f32_16x16x32_bf16 v[80:83], v[210:213], v[180:183], v[80:83]
	v_mfma_f32_16x16x32_bf16 v[68:71], v[202:205], v[194:197], v[68:71]
	v_mfma_f32_16x16x32_bf16 v[64:67], v[210:213], v[194:197], v[64:67]
	s_setprio 0
	s_mov_b32 m0, s39
	v_lshl_add_u64 v[214:215], v[218:219], 0, s[12:13]
	s_barrier
	ds_read_b128 v[144:147], v190 offset:49152
	ds_read_b128 v[148:151], v190 offset:50176
	ds_read_b128 v[166:169], v190 offset:51200
	ds_read_b128 v[170:173], v190 offset:52224
	ds_read_b128 v[174:177], v190 offset:53248
	ds_read_b128 v[180:183], v190 offset:54272
	ds_read_b128 v[184:187], v190 offset:55296
	ds_read_b128 v[194:197], v190 offset:56320
	global_load_lds_dwordx4 v[214:215], off
	v_lshl_add_u64 v[214:215], v[222:223], 0, s[12:13]
	s_mov_b32 m0, s40
	s_nop 0
	global_load_lds_dwordx4 v[214:215], off
	s_barrier
	s_waitcnt lgkmcnt(0)
	s_setprio 1
	v_mfma_f32_16x16x32_bf16 v[60:63], v[128:131], v[144:147], v[60:63]
	v_mfma_f32_16x16x32_bf16 v[56:59], v[136:139], v[144:147], v[56:59]
	v_mfma_f32_16x16x32_bf16 v[44:47], v[128:131], v[166:169], v[44:47]
	v_mfma_f32_16x16x32_bf16 v[40:43], v[136:139], v[166:169], v[40:43]
	v_mfma_f32_16x16x32_bf16 v[28:31], v[128:131], v[174:177], v[28:31]
	v_mfma_f32_16x16x32_bf16 v[24:27], v[136:139], v[174:177], v[24:27]
	v_mfma_f32_16x16x32_bf16 v[12:15], v[128:131], v[184:187], v[12:15]
	v_mfma_f32_16x16x32_bf16 v[8:11], v[136:139], v[184:187], v[8:11]
	v_mfma_f32_16x16x32_bf16 v[60:63], v[132:135], v[148:151], v[60:63]
	v_mfma_f32_16x16x32_bf16 v[56:59], v[140:143], v[148:151], v[56:59]
	v_mfma_f32_16x16x32_bf16 v[44:47], v[132:135], v[170:173], v[44:47]
	v_mfma_f32_16x16x32_bf16 v[40:43], v[140:143], v[170:173], v[40:43]
	v_mfma_f32_16x16x32_bf16 v[28:31], v[132:135], v[180:183], v[28:31]
	v_mfma_f32_16x16x32_bf16 v[24:27], v[140:143], v[180:183], v[24:27]
	v_mfma_f32_16x16x32_bf16 v[12:15], v[132:135], v[194:197], v[12:15]
	v_mfma_f32_16x16x32_bf16 v[8:11], v[140:143], v[194:197], v[8:11]
	s_setprio 0
	s_barrier
	s_add_u32 s24, s24, 0x40080
	s_addc_u32 s25, s25, 0
	s_add_i32 s26, s26, s33
	v_lshl_add_u64 v[128:129], s[24:25], 0, v[156:157]
	s_mov_b32 m0, s26
	s_nop 0
	global_load_lds_dwordx4 v[128:129], off
	v_lshl_add_u64 v[128:129], s[24:25], 0, v[152:153]
	s_add_i32 m0, s26, 0x2000
	s_nop 0
	global_load_lds_dwordx4 v[128:129], off
	s_waitcnt vmcnt(6)
	s_barrier
	s_setprio 1
	v_mfma_f32_16x16x32_bf16 v[52:55], v[198:201], v[144:147], v[52:55]
	v_mfma_f32_16x16x32_bf16 v[48:51], v[206:209], v[144:147], v[48:51]
	v_mfma_f32_16x16x32_bf16 v[36:39], v[198:201], v[166:169], v[36:39]
	v_mfma_f32_16x16x32_bf16 v[32:35], v[206:209], v[166:169], v[32:35]
	v_mfma_f32_16x16x32_bf16 v[20:23], v[198:201], v[174:177], v[20:23]
	v_mfma_f32_16x16x32_bf16 v[16:19], v[206:209], v[174:177], v[16:19]
	v_mfma_f32_16x16x32_bf16 v[4:7], v[198:201], v[184:187], v[4:7]
	v_mfma_f32_16x16x32_bf16 v[0:3], v[206:209], v[184:187], v[0:3]
	v_mfma_f32_16x16x32_bf16 v[52:55], v[202:205], v[148:151], v[52:55]
	v_mfma_f32_16x16x32_bf16 v[48:51], v[210:213], v[148:151], v[48:51]
	v_mfma_f32_16x16x32_bf16 v[36:39], v[202:205], v[170:173], v[36:39]
	v_mfma_f32_16x16x32_bf16 v[32:35], v[210:213], v[170:173], v[32:35]
	v_mfma_f32_16x16x32_bf16 v[20:23], v[202:205], v[180:183], v[20:23]
	v_mfma_f32_16x16x32_bf16 v[16:19], v[210:213], v[180:183], v[16:19]
	v_mfma_f32_16x16x32_bf16 v[4:7], v[202:205], v[194:197], v[4:7]
	v_mfma_f32_16x16x32_bf16 v[0:3], v[210:213], v[194:197], v[0:3]
	s_setprio 0
	s_add_i32 s47, s47, 2
	s_add_u32 s10, s10, 0x100
	s_addc_u32 s11, s11, 0
	s_add_u32 s45, s45, 0x100
	s_addc_u32 s46, s46, 0
	s_cmp_gt_u32 s47, 13
	s_barrier
	s_cbranch_scc0 .LBB0_1356
	s_lshl_b32 s24, s4, 8
	s_ashr_i32 s25, s24, 31
	s_lshl_b32 s10, s4, 2
	s_nop 0
	v_lshl_add_u32 v166, s28, 8, v179
	s_ashr_i32 s11, s10, 31
	s_lshl_b64 s[28:29], s[24:25], 1
	v_readlane_b32 s50, v253, 40
	v_readlane_b32 s51, v253, 41
	s_add_u32 s26, s50, s28
	v_ashrrev_i32_e32 v167, 31, v166
	s_addc_u32 s27, s51, s29
	v_lshlrev_b64 v[204:205], 11, v[166:167]
	v_lshl_add_u64 v[128:129], s[26:27], 0, v[204:205]
	v_lshl_add_u64 v[206:207], v[128:129], 0, v[160:161]
	global_load_dwordx4 v[196:199], v[206:207], off
	global_load_dwordx4 v[200:203], v[206:207], off offset:256
	v_or_b32_e32 v182, 16, v166
	v_or_b32_e32 v174, 32, v166
	v_or_b32_e32 v168, 48, v166
	v_ashrrev_i32_e32 v183, 31, v182
	v_ashrrev_i32_e32 v175, 31, v174
	v_ashrrev_i32_e32 v169, 31, v168
	v_lshlrev_b64 v[186:187], 11, v[182:183]
	v_lshlrev_b64 v[180:181], 11, v[174:175]
	v_lshlrev_b64 v[172:173], 11, v[168:169]
	v_lshl_add_u64 v[128:129], s[26:27], 0, v[186:187]
	v_lshl_add_u64 v[130:131], s[26:27], 0, v[180:181]
	v_lshl_add_u64 v[132:133], s[26:27], 0, v[172:173]
	v_lshl_add_u64 v[184:185], v[128:129], 0, v[160:161]
	v_lshl_add_u64 v[176:177], v[130:131], 0, v[160:161]
	v_lshl_add_u64 v[170:171], v[132:133], 0, v[160:161]
	global_load_dwordx4 v[148:151], v[184:185], off
	global_load_dwordx4 v[144:147], v[184:185], off offset:256
	global_load_dwordx4 v[140:143], v[176:177], off
	global_load_dwordx4 v[136:139], v[176:177], off offset:256
	global_load_dwordx4 v[132:135], v[170:171], off
	global_load_dwordx4 v[128:131], v[170:171], off offset:256
	v_and_b32_e32 v194, 64, v192
	v_xor_b32_e32 v193, 16, v192
	v_add_u32_e32 v194, 64, v194
	v_cmp_lt_i32_e32 vcc, v193, v194
	v_xor_b32_e32 v195, 32, v192
	v_lshl_add_u64 v[204:205], s[50:51], 0, v[204:205]
	v_cndmask_b32_e32 v193, v192, v193, vcc
	v_cmp_lt_i32_e32 vcc, v195, v194
	v_lshlrev_b32_e32 v194, 2, v193
	s_nop 0
	v_cndmask_b32_e32 v195, v192, v195, vcc
	v_lshlrev_b32_e32 v193, 2, v195
	s_nop 7
	s_nop 3
	s_waitcnt vmcnt(0)
	v_lshlrev_b32_e32 v210, 16, v198
	v_and_b32_e32 v211, 0xffff0000, v198
	v_lshlrev_b32_e32 v208, 16, v196
	v_and_b32_e32 v209, 0xffff0000, v196
	v_lshlrev_b32_e32 v198, 16, v199
	v_and_b32_e32 v199, 0xffff0000, v199
	v_lshlrev_b32_e32 v214, 16, v202
	v_and_b32_e32 v215, 0xffff0000, v202
	v_lshlrev_b32_e32 v202, 16, v203
	v_and_b32_e32 v203, 0xffff0000, v203
	v_pk_add_f32 v[120:121], v[120:121], v[210:211]
	v_lshlrev_b32_e32 v196, 16, v197
	v_and_b32_e32 v197, 0xffff0000, v197
	v_pk_add_f32 v[124:125], v[124:125], v[208:209]
	v_pk_add_f32 v[122:123], v[122:123], v[198:199]
	v_pk_add_f32 v[198:199], v[114:115], v[202:203]
	v_cvt_pk_bf16_f32 v114, v120, v121
	v_pk_mul_f32 v[120:121], v[120:121], v[120:121]
	v_pk_add_f32 v[126:127], v[126:127], v[196:197]
	v_cvt_pk_bf16_f32 v115, v122, v123
	v_pk_mul_f32 v[122:123], v[122:123], v[122:123]
	v_pk_fma_f32 v[120:121], v[124:125], v[124:125], v[120:121]
	v_lshlrev_b32_e32 v212, 16, v200
	v_and_b32_e32 v213, 0xffff0000, v200
	v_lshlrev_b32_e32 v200, 16, v201
	v_and_b32_e32 v201, 0xffff0000, v201
	v_pk_add_f32 v[196:197], v[112:113], v[214:215]
	v_pk_fma_f32 v[122:123], v[126:127], v[126:127], v[122:123]
	v_add_f32_e32 v120, v120, v121
	v_pk_add_f32 v[116:117], v[116:117], v[212:213]
	v_pk_add_f32 v[118:119], v[118:119], v[200:201]
	v_pk_mul_f32 v[200:201], v[196:197], v[196:197]
	v_add_f32_e32 v120, v122, v120
	v_cvt_pk_bf16_f32 v112, v124, v125
	v_pk_fma_f32 v[124:125], v[116:117], v[116:117], v[200:201]
	v_add_f32_e32 v120, v123, v120
	v_pk_mul_f32 v[202:203], v[198:199], v[198:199]
	v_add_f32_e32 v120, v124, v120
	v_cvt_pk_bf16_f32 v113, v126, v127
	v_pk_fma_f32 v[126:127], v[118:119], v[118:119], v[202:203]
	v_add_f32_e32 v120, v125, v120
	v_add_f32_e32 v120, v126, v120
	v_add_f32_e32 v122, v127, v120
	ds_bpermute_b32 v123, v194, v122
	global_store_dwordx4 v[206:207], v[112:115], off
	v_lshl_add_u64 v[120:121], v[204:205], 0, s[28:29]
	s_nop 0
	v_cvt_pk_bf16_f32 v114, v116, v117
	s_waitcnt lgkmcnt(0)
	v_add_f32_e32 v112, v122, v123
	ds_bpermute_b32 v113, v193, v112
	v_cvt_pk_bf16_f32 v115, v118, v119
	v_cvt_pk_bf16_f32 v116, v196, v197
	v_cvt_pk_bf16_f32 v117, v198, v199
	v_lshl_add_u64 v[118:119], v[120:121], 0, v[160:161]
	global_store_dwordx4 v[118:119], v[114:117], off offset:256
	s_and_saveexec_b64 s[28:29], s[0:1]
	s_cbranch_execz .LBB0_1359
	s_waitcnt lgkmcnt(0)
	v_add_f32_e32 v114, v112, v113
	v_lshlrev_b64 v[112:113], 6, v[166:167]
	v_lshl_add_u64 v[112:113], s[86:87], 0, v[112:113]
	v_lshl_add_u64 v[112:113], s[10:11], 2, v[112:113]
	s_lshl_b32 s4, s38, 2
	v_lshl_add_u64 v[112:113], v[112:113], 0, s[4:5]
	global_store_dword v[112:113], v114, off

.LBB0_1441:
	ds_read_b128 v[144:147], v161
	ds_read_b128 v[148:151], v161 offset:1024
	ds_read_b128 v[172:175], v161 offset:2048
	ds_read_b128 v[180:183], v161 offset:3072
	s_add_u32 s4, s0, 0xfffc0080
	s_addc_u32 s5, s1, -1
	s_cmp_eq_u32 s45, 12
	s_cselect_b32 s11, s19, s5
	s_cselect_b32 s10, s41, s4
	s_cselect_b32 s5, s21, s44
	s_cselect_b32 s4, s42, s43
	v_lshl_add_u64 v[154:155], s[0:1], 0, v[140:141]
	s_add_i32 m0, s17, 0xc000
	ds_read_b128 v[184:187], v165
	ds_read_b128 v[188:191], v165 offset:1024
	ds_read_b128 v[192:195], v165 offset:2048
	ds_read_b128 v[196:199], v165 offset:3072
	ds_read_b128 v[200:203], v165 offset:4096
	ds_read_b128 v[204:207], v165 offset:5120
	ds_read_b128 v[208:211], v165 offset:6144
	ds_read_b128 v[212:215], v165 offset:7168
	global_load_lds_dwordx4 v[154:155], off
	v_lshl_add_u64 v[154:155], s[0:1], 0, v[142:143]
	s_add_i32 m0, s17, 0xe000
	s_nop 0
	global_load_lds_dwordx4 v[154:155], off
	s_waitcnt lgkmcnt(8)
	s_barrier
	s_waitcnt lgkmcnt(0)
	s_setprio 1
	v_mfma_f32_16x16x32_bf16 v[124:127], v[144:147], v[184:187], v[124:127]
	v_mfma_f32_16x16x32_bf16 v[120:123], v[172:175], v[184:187], v[120:123]
	v_mfma_f32_16x16x32_bf16 v[108:111], v[144:147], v[192:195], v[108:111]
	v_mfma_f32_16x16x32_bf16 v[104:107], v[172:175], v[192:195], v[104:107]
	v_mfma_f32_16x16x32_bf16 v[92:95], v[144:147], v[200:203], v[92:95]
	v_mfma_f32_16x16x32_bf16 v[88:91], v[172:175], v[200:203], v[88:91]
	v_mfma_f32_16x16x32_bf16 v[76:79], v[144:147], v[208:211], v[76:79]
	v_mfma_f32_16x16x32_bf16 v[72:75], v[172:175], v[208:211], v[72:75]
	v_mfma_f32_16x16x32_bf16 v[124:127], v[148:151], v[188:191], v[124:127]
	v_mfma_f32_16x16x32_bf16 v[120:123], v[180:183], v[188:191], v[120:123]
	v_mfma_f32_16x16x32_bf16 v[108:111], v[148:151], v[196:199], v[108:111]
	v_mfma_f32_16x16x32_bf16 v[104:107], v[180:183], v[196:199], v[104:107]
	v_mfma_f32_16x16x32_bf16 v[92:95], v[148:151], v[204:207], v[92:95]
	v_mfma_f32_16x16x32_bf16 v[88:91], v[180:183], v[204:207], v[88:91]
	v_mfma_f32_16x16x32_bf16 v[76:79], v[148:151], v[212:215], v[76:79]
	v_mfma_f32_16x16x32_bf16 v[72:75], v[180:183], v[212:215], v[72:75]
	s_setprio 0
	s_barrier
	s_add_i32 s46, s37, s15
	v_lshl_add_u64 v[154:155], s[4:5], 0, v[132:133]
	s_mov_b32 m0, s46
	ds_read_b128 v[216:219], v167
	ds_read_b128 v[222:225], v167 offset:1024
	ds_read_b128 v[226:229], v167 offset:2048
	ds_read_b128 v[230:233], v167 offset:3072
	global_load_lds_dwordx4 v[154:155], off
	v_lshl_add_u64 v[158:159], s[4:5], 0, v[128:129]
	s_add_i32 m0, s46, 0x2000
	s_nop 0
	global_load_lds_dwordx4 v[158:159], off
	s_barrier
	s_waitcnt lgkmcnt(0)
	s_setprio 1
	v_mfma_f32_16x16x32_bf16 v[116:119], v[216:219], v[184:187], v[116:119]
	v_mfma_f32_16x16x32_bf16 v[112:115], v[226:229], v[184:187], v[112:115]
	v_mfma_f32_16x16x32_bf16 v[100:103], v[216:219], v[192:195], v[100:103]
	v_mfma_f32_16x16x32_bf16 v[96:99], v[226:229], v[192:195], v[96:99]
	v_mfma_f32_16x16x32_bf16 v[84:87], v[216:219], v[200:203], v[84:87]
	v_mfma_f32_16x16x32_bf16 v[80:83], v[226:229], v[200:203], v[80:83]
	v_mfma_f32_16x16x32_bf16 v[68:71], v[216:219], v[208:211], v[68:71]
	v_mfma_f32_16x16x32_bf16 v[64:67], v[226:229], v[208:211], v[64:67]
	v_mfma_f32_16x16x32_bf16 v[116:119], v[222:225], v[188:191], v[116:119]
	v_mfma_f32_16x16x32_bf16 v[112:115], v[230:233], v[188:191], v[112:115]
	v_mfma_f32_16x16x32_bf16 v[100:103], v[222:225], v[196:199], v[100:103]
	v_mfma_f32_16x16x32_bf16 v[96:99], v[230:233], v[196:199], v[96:99]
	v_mfma_f32_16x16x32_bf16 v[84:87], v[222:225], v[204:207], v[84:87]
	v_mfma_f32_16x16x32_bf16 v[80:83], v[230:233], v[204:207], v[80:83]
	v_mfma_f32_16x16x32_bf16 v[68:71], v[222:225], v[212:215], v[68:71]
	v_mfma_f32_16x16x32_bf16 v[64:67], v[230:233], v[212:215], v[64:67]
	s_setprio 0
	s_mov_b32 m0, s17
	v_lshl_add_u64 v[162:163], s[10:11], 0, v[134:135]
	s_barrier
	ds_read_b128 v[184:187], v165 offset:16384
	ds_read_b128 v[188:191], v165 offset:17408
	ds_read_b128 v[192:195], v165 offset:18432
	ds_read_b128 v[196:199], v165 offset:19456
	ds_read_b128 v[200:203], v165 offset:20480
	ds_read_b128 v[204:207], v165 offset:21504
	ds_read_b128 v[208:211], v165 offset:22528
	ds_read_b128 v[212:215], v165 offset:23552
	global_load_lds_dwordx4 v[162:163], off
	v_lshl_add_u64 v[168:169], s[10:11], 0, v[130:131]
	s_mov_b32 m0, s28
	s_nop 0
	global_load_lds_dwordx4 v[168:169], off
	s_barrier
	s_waitcnt lgkmcnt(0)
	s_setprio 1
	v_mfma_f32_16x16x32_bf16 v[60:63], v[144:147], v[184:187], v[60:63]
	v_mfma_f32_16x16x32_bf16 v[56:59], v[172:175], v[184:187], v[56:59]
	v_mfma_f32_16x16x32_bf16 v[44:47], v[144:147], v[192:195], v[44:47]
	v_mfma_f32_16x16x32_bf16 v[40:43], v[172:175], v[192:195], v[40:43]
	v_mfma_f32_16x16x32_bf16 v[28:31], v[144:147], v[200:203], v[28:31]
	v_mfma_f32_16x16x32_bf16 v[24:27], v[172:175], v[200:203], v[24:27]
	v_mfma_f32_16x16x32_bf16 v[12:15], v[144:147], v[208:211], v[12:15]
	v_mfma_f32_16x16x32_bf16 v[8:11], v[172:175], v[208:211], v[8:11]
	v_mfma_f32_16x16x32_bf16 v[60:63], v[148:151], v[188:191], v[60:63]
	v_mfma_f32_16x16x32_bf16 v[56:59], v[180:183], v[188:191], v[56:59]
	v_mfma_f32_16x16x32_bf16 v[44:47], v[148:151], v[196:199], v[44:47]
	v_mfma_f32_16x16x32_bf16 v[40:43], v[180:183], v[196:199], v[40:43]
	v_mfma_f32_16x16x32_bf16 v[28:31], v[148:151], v[204:207], v[28:31]
	v_mfma_f32_16x16x32_bf16 v[24:27], v[180:183], v[204:207], v[24:27]
	v_mfma_f32_16x16x32_bf16 v[12:15], v[148:151], v[212:215], v[12:15]
	v_mfma_f32_16x16x32_bf16 v[8:11], v[180:183], v[212:215], v[8:11]
	s_setprio 0
	s_barrier
	s_add_u32 s46, s4, 0x40000
	s_addc_u32 s47, s5, 0
	s_add_i32 s48, s38, s15
	v_lshl_add_u64 v[144:145], s[46:47], 0, v[132:133]
	s_mov_b32 m0, s48
	s_nop 0
	global_load_lds_dwordx4 v[144:145], off
	v_lshl_add_u64 v[144:145], s[46:47], 0, v[128:129]
	s_add_i32 m0, s48, 0x2000
	s_nop 0
	global_load_lds_dwordx4 v[144:145], off
	s_waitcnt vmcnt(6)
	s_barrier
	s_setprio 1
	v_mfma_f32_16x16x32_bf16 v[52:55], v[216:219], v[184:187], v[52:55]
	v_mfma_f32_16x16x32_bf16 v[48:51], v[226:229], v[184:187], v[48:51]
	v_mfma_f32_16x16x32_bf16 v[36:39], v[216:219], v[192:195], v[36:39]
	v_mfma_f32_16x16x32_bf16 v[32:35], v[226:229], v[192:195], v[32:35]
	v_mfma_f32_16x16x32_bf16 v[20:23], v[216:219], v[200:203], v[20:23]
	v_mfma_f32_16x16x32_bf16 v[16:19], v[226:229], v[200:203], v[16:19]
	v_mfma_f32_16x16x32_bf16 v[4:7], v[216:219], v[208:211], v[4:7]
	v_mfma_f32_16x16x32_bf16 v[0:3], v[226:229], v[208:211], v[0:3]
	v_mfma_f32_16x16x32_bf16 v[52:55], v[222:225], v[188:191], v[52:55]
	v_mfma_f32_16x16x32_bf16 v[48:51], v[230:233], v[188:191], v[48:51]
	v_mfma_f32_16x16x32_bf16 v[36:39], v[222:225], v[196:199], v[36:39]
	v_mfma_f32_16x16x32_bf16 v[32:35], v[230:233], v[196:199], v[32:35]
	v_mfma_f32_16x16x32_bf16 v[20:23], v[222:225], v[204:207], v[20:23]
	v_mfma_f32_16x16x32_bf16 v[16:19], v[230:233], v[204:207], v[16:19]
	v_mfma_f32_16x16x32_bf16 v[4:7], v[222:225], v[212:215], v[4:7]
	v_mfma_f32_16x16x32_bf16 v[0:3], v[230:233], v[212:215], v[0:3]
	s_setprio 0
	s_add_i32 s46, 0, 0x18000
	v_add_u32_e32 v152, s46, v157
	s_barrier
	ds_read_b128 v[144:147], v152
	ds_read_b128 v[148:151], v152 offset:1024
	ds_read_b128 v[172:175], v152 offset:2048
	ds_read_b128 v[180:183], v152 offset:3072
	s_add_u32 s10, s10, 0x40000
	s_addc_u32 s11, s11, 0
	s_mov_b32 m0, s29
	v_lshl_add_u64 v[176:177], s[10:11], 0, v[134:135]
	ds_read_b128 v[184:187], v165 offset:32768
	ds_read_b128 v[188:191], v165 offset:33792
	ds_read_b128 v[192:195], v165 offset:34816
	ds_read_b128 v[196:199], v165 offset:35840
	ds_read_b128 v[200:203], v165 offset:36864
	ds_read_b128 v[204:207], v165 offset:37888
	ds_read_b128 v[208:211], v165 offset:38912
	ds_read_b128 v[212:215], v165 offset:39936
	global_load_lds_dwordx4 v[176:177], off
	v_lshl_add_u64 v[176:177], s[10:11], 0, v[130:131]
	s_mov_b32 m0, s31
	s_nop 0
	global_load_lds_dwordx4 v[176:177], off
	s_waitcnt lgkmcnt(8)
	s_barrier
	s_waitcnt lgkmcnt(0)
	s_setprio 1
	v_mfma_f32_16x16x32_bf16 v[124:127], v[144:147], v[184:187], v[124:127]
	v_mfma_f32_16x16x32_bf16 v[120:123], v[172:175], v[184:187], v[120:123]
	v_mfma_f32_16x16x32_bf16 v[108:111], v[144:147], v[192:195], v[108:111]
	v_mfma_f32_16x16x32_bf16 v[104:107], v[172:175], v[192:195], v[104:107]
	v_mfma_f32_16x16x32_bf16 v[92:95], v[144:147], v[200:203], v[92:95]
	v_mfma_f32_16x16x32_bf16 v[88:91], v[172:175], v[200:203], v[88:91]
	v_mfma_f32_16x16x32_bf16 v[76:79], v[144:147], v[208:211], v[76:79]
	v_mfma_f32_16x16x32_bf16 v[72:75], v[172:175], v[208:211], v[72:75]
	v_mfma_f32_16x16x32_bf16 v[124:127], v[148:151], v[188:191], v[124:127]
	v_mfma_f32_16x16x32_bf16 v[120:123], v[180:183], v[188:191], v[120:123]
	v_mfma_f32_16x16x32_bf16 v[108:111], v[148:151], v[196:199], v[108:111]
	v_mfma_f32_16x16x32_bf16 v[104:107], v[180:183], v[196:199], v[104:107]
	v_mfma_f32_16x16x32_bf16 v[92:95], v[148:151], v[204:207], v[92:95]
	v_mfma_f32_16x16x32_bf16 v[88:91], v[180:183], v[204:207], v[88:91]
	v_mfma_f32_16x16x32_bf16 v[76:79], v[148:151], v[212:215], v[76:79]
	v_mfma_f32_16x16x32_bf16 v[72:75], v[180:183], v[212:215], v[72:75]
	s_setprio 0
	s_barrier
	s_add_i32 s10, 0, 0x1c000
	s_add_i32 s11, s46, s15
	v_add_u32_e32 v152, s10, v157
	v_lshl_add_u64 v[154:155], v[154:155], 0, s[12:13]
	s_mov_b32 m0, s11
	ds_read_b128 v[216:219], v152
	ds_read_b128 v[222:225], v152 offset:1024
	ds_read_b128 v[226:229], v152 offset:2048
	ds_read_b128 v[230:233], v152 offset:3072
	global_load_lds_dwordx4 v[154:155], off
	v_lshl_add_u64 v[154:155], v[158:159], 0, s[12:13]
	s_add_i32 m0, s11, 0x2000
	s_nop 0
	global_load_lds_dwordx4 v[154:155], off
	s_barrier
	s_waitcnt lgkmcnt(0)
	s_setprio 1
	v_mfma_f32_16x16x32_bf16 v[116:119], v[216:219], v[184:187], v[116:119]
	v_mfma_f32_16x16x32_bf16 v[112:115], v[226:229], v[184:187], v[112:115]
	v_mfma_f32_16x16x32_bf16 v[100:103], v[216:219], v[192:195], v[100:103]
	v_mfma_f32_16x16x32_bf16 v[96:99], v[226:229], v[192:195], v[96:99]
	v_mfma_f32_16x16x32_bf16 v[84:87], v[216:219], v[200:203], v[84:87]
	v_mfma_f32_16x16x32_bf16 v[80:83], v[226:229], v[200:203], v[80:83]
	v_mfma_f32_16x16x32_bf16 v[68:71], v[216:219], v[208:211], v[68:71]
	v_mfma_f32_16x16x32_bf16 v[64:67], v[226:229], v[208:211], v[64:67]
	v_mfma_f32_16x16x32_bf16 v[116:119], v[222:225], v[188:191], v[116:119]
	v_mfma_f32_16x16x32_bf16 v[112:115], v[230:233], v[188:191], v[112:115]
	v_mfma_f32_16x16x32_bf16 v[100:103], v[222:225], v[196:199], v[100:103]
	v_mfma_f32_16x16x32_bf16 v[96:99], v[230:233], v[196:199], v[96:99]
	v_mfma_f32_16x16x32_bf16 v[84:87], v[222:225], v[204:207], v[84:87]
	v_mfma_f32_16x16x32_bf16 v[80:83], v[230:233], v[204:207], v[80:83]
	v_mfma_f32_16x16x32_bf16 v[68:71], v[222:225], v[212:215], v[68:71]
	v_mfma_f32_16x16x32_bf16 v[64:67], v[230:233], v[212:215], v[64:67]
	s_setprio 0
	s_mov_b32 m0, s35
	v_lshl_add_u64 v[154:155], v[162:163], 0, s[12:13]
	s_barrier
	ds_read_b128 v[184:187], v165 offset:49152
	ds_read_b128 v[188:191], v165 offset:50176
	ds_read_b128 v[192:195], v165 offset:51200
	ds_read_b128 v[196:199], v165 offset:52224
	ds_read_b128 v[200:203], v165 offset:53248
	ds_read_b128 v[204:207], v165 offset:54272
	ds_read_b128 v[208:211], v165 offset:55296
	ds_read_b128 v[212:215], v165 offset:56320
	global_load_lds_dwordx4 v[154:155], off
	v_lshl_add_u64 v[154:155], v[168:169], 0, s[12:13]
	s_mov_b32 m0, s36
	s_nop 0
	global_load_lds_dwordx4 v[154:155], off
	s_barrier
	s_waitcnt lgkmcnt(0)
	s_setprio 1
	v_mfma_f32_16x16x32_bf16 v[60:63], v[144:147], v[184:187], v[60:63]
	v_mfma_f32_16x16x32_bf16 v[56:59], v[172:175], v[184:187], v[56:59]
	v_mfma_f32_16x16x32_bf16 v[44:47], v[144:147], v[192:195], v[44:47]
	v_mfma_f32_16x16x32_bf16 v[40:43], v[172:175], v[192:195], v[40:43]
	v_mfma_f32_16x16x32_bf16 v[28:31], v[144:147], v[200:203], v[28:31]
	v_mfma_f32_16x16x32_bf16 v[24:27], v[172:175], v[200:203], v[24:27]
	v_mfma_f32_16x16x32_bf16 v[12:15], v[144:147], v[208:211], v[12:15]
	v_mfma_f32_16x16x32_bf16 v[8:11], v[172:175], v[208:211], v[8:11]
	v_mfma_f32_16x16x32_bf16 v[60:63], v[148:151], v[188:191], v[60:63]
	v_mfma_f32_16x16x32_bf16 v[56:59], v[180:183], v[188:191], v[56:59]
	v_mfma_f32_16x16x32_bf16 v[44:47], v[148:151], v[196:199], v[44:47]
	v_mfma_f32_16x16x32_bf16 v[40:43], v[180:183], v[196:199], v[40:43]
	v_mfma_f32_16x16x32_bf16 v[28:31], v[148:151], v[204:207], v[28:31]
	v_mfma_f32_16x16x32_bf16 v[24:27], v[180:183], v[204:207], v[24:27]
	v_mfma_f32_16x16x32_bf16 v[12:15], v[148:151], v[212:215], v[12:15]
	v_mfma_f32_16x16x32_bf16 v[8:11], v[180:183], v[212:215], v[8:11]
	s_setprio 0
	s_barrier
	s_add_u32 s4, s4, 0x40080
	s_addc_u32 s5, s5, 0
	s_add_i32 s10, s10, s15
	v_lshl_add_u64 v[144:145], s[4:5], 0, v[132:133]
	s_mov_b32 m0, s10
	s_nop 0
	global_load_lds_dwordx4 v[144:145], off
	v_lshl_add_u64 v[144:145], s[4:5], 0, v[128:129]
	s_add_i32 m0, s10, 0x2000
	s_nop 0
	global_load_lds_dwordx4 v[144:145], off
	s_waitcnt vmcnt(6)
	s_barrier
	s_setprio 1
	v_mfma_f32_16x16x32_bf16 v[52:55], v[216:219], v[184:187], v[52:55]
	v_mfma_f32_16x16x32_bf16 v[48:51], v[226:229], v[184:187], v[48:51]
	v_mfma_f32_16x16x32_bf16 v[36:39], v[216:219], v[192:195], v[36:39]
	v_mfma_f32_16x16x32_bf16 v[32:35], v[226:229], v[192:195], v[32:35]
	v_mfma_f32_16x16x32_bf16 v[20:23], v[216:219], v[200:203], v[20:23]
	v_mfma_f32_16x16x32_bf16 v[16:19], v[226:229], v[200:203], v[16:19]
	v_mfma_f32_16x16x32_bf16 v[4:7], v[216:219], v[208:211], v[4:7]
	v_mfma_f32_16x16x32_bf16 v[0:3], v[226:229], v[208:211], v[0:3]
	v_mfma_f32_16x16x32_bf16 v[52:55], v[222:225], v[188:191], v[52:55]
	v_mfma_f32_16x16x32_bf16 v[48:51], v[230:233], v[188:191], v[48:51]
	v_mfma_f32_16x16x32_bf16 v[36:39], v[222:225], v[196:199], v[36:39]
	v_mfma_f32_16x16x32_bf16 v[32:35], v[230:233], v[196:199], v[32:35]
	v_mfma_f32_16x16x32_bf16 v[20:23], v[222:225], v[204:207], v[20:23]
	v_mfma_f32_16x16x32_bf16 v[16:19], v[230:233], v[204:207], v[16:19]
	v_mfma_f32_16x16x32_bf16 v[4:7], v[222:225], v[212:215], v[4:7]
	v_mfma_f32_16x16x32_bf16 v[0:3], v[230:233], v[212:215], v[0:3]
	s_setprio 0
	s_add_i32 s45, s45, 2
	s_add_u32 s0, s0, 0x100
	s_addc_u32 s1, s1, 0
	s_add_u32 s43, s43, 0x100
	s_addc_u32 s44, s44, 0
	s_cmp_gt_u32 s45, 13
	s_barrier
	s_cbranch_scc0 .LBB0_1441
	v_lshl_add_u32 v168, s72, 8, v153
	v_ashrrev_i32_e32 v169, 31, v168
	v_or_b32_e32 v162, 16, v168
	v_lshlrev_b64 v[144:145], 6, v[168:169]
	v_ashrrev_i32_e32 v163, 31, v162
	v_or_b32_e32 v158, 32, v168
	v_lshl_add_u64 v[144:145], v[138:139], 0, v[144:145]
	v_lshlrev_b64 v[146:147], 6, v[162:163]
	v_ashrrev_i32_e32 v159, 31, v158
	v_lshl_add_u64 v[146:147], v[138:139], 0, v[146:147]
	global_load_dwordx4 v[172:175], v[144:145], off
	global_load_dwordx4 v[180:183], v[146:147], off
	v_lshlrev_b64 v[144:145], 6, v[158:159]
	v_or_b32_e32 v154, 48, v168
	v_lshl_add_u64 v[144:145], v[138:139], 0, v[144:145]
	v_ashrrev_i32_e32 v155, 31, v154
	global_load_dwordx4 v[184:187], v[144:145], off
	v_lshlrev_b64 v[144:145], 6, v[154:155]
	v_lshl_add_u64 v[144:145], v[138:139], 0, v[144:145]
	global_load_dwordx4 v[188:191], v[144:145], off
	v_add_u32_e32 v150, 0x80, v168
	v_ashrrev_i32_e32 v151, 31, v150
	v_lshlrev_b64 v[144:145], 6, v[150:151]
	v_add_u32_e32 v148, 0x90, v168
	v_lshl_add_u64 v[144:145], v[138:139], 0, v[144:145]
	v_ashrrev_i32_e32 v149, 31, v148
	global_load_dwordx4 v[192:195], v[144:145], off
	v_lshlrev_b64 v[144:145], 6, v[148:149]
	v_lshl_add_u64 v[144:145], v[138:139], 0, v[144:145]
	global_load_dwordx4 v[196:199], v[144:145], off
	v_and_b32_e32 v145, 64, v171
	v_add_u32_e32 v146, 0xa0, v168
	v_add_u32_e32 v144, 0xb0, v168
	v_add_u32_e32 v160, 64, v145
	v_ashrrev_i32_e32 v147, 31, v146
	v_ashrrev_i32_e32 v145, 31, v144
	v_lshlrev_b64 v[200:201], 6, v[146:147]
	v_lshlrev_b64 v[202:203], 6, v[144:145]
	v_lshl_add_u64 v[200:201], v[138:139], 0, v[200:201]
	v_lshl_add_u64 v[204:205], v[138:139], 0, v[202:203]
	global_load_dwordx4 v[200:203], v[200:201], off
	s_nop 0
	global_load_dwordx4 v[204:207], v[204:205], off
	v_xor_b32_e32 v152, 16, v171
	v_cmp_lt_i32_e32 vcc, v152, v160
	v_xor_b32_e32 v156, 32, v171
	v_mov_b64_e32 v[176:177], s[16:17]
	v_cndmask_b32_e32 v152, v171, v152, vcc
	v_lshlrev_b32_e32 v152, 2, v152
	v_cmp_lt_i32_e32 vcc, v156, v160
	v_lshlrev_b64 v[168:169], 7, v[168:169]
	s_mov_b32 s72, s18
	v_cndmask_b32_e32 v156, v171, v156, vcc
	v_lshlrev_b32_e32 v156, 2, v156
	s_mov_b32 s21, s18
	s_mov_b32 s19, s40
	s_waitcnt vmcnt(0)
	v_mov_b32_e32 v208, v173
	v_mov_b32_e32 v209, v174
	v_mov_b32_e32 v173, v175
	v_mov_b32_e32 v174, v181
	v_mov_b32_e32 v175, v182
	v_mov_b32_e32 v181, v183
	v_pk_add_f32 v[172:173], v[208:209], v[172:173]
	v_pk_add_f32 v[174:175], v[174:175], v[180:181]
	v_mov_b32_e32 v181, v172
	v_mov_b32_e32 v180, v174
	v_mov_b32_e32 v172, v175
	v_mov_b32_e32 v182, v185
	v_mov_b32_e32 v183, v186
	v_mov_b32_e32 v185, v187
	v_mov_b32_e32 v186, v189
	v_mov_b32_e32 v187, v190
	v_mov_b32_e32 v189, v191
	v_pk_add_f32 v[172:173], v[180:181], v[172:173]
	v_pk_add_f32 v[182:183], v[182:183], v[184:185]
	v_pk_add_f32 v[184:185], v[186:187], v[188:189]
	ds_bpermute_b32 v181, v152, v173
	ds_bpermute_b32 v180, v152, v172
	v_mov_b32_e32 v174, v184
	v_mov_b32_e32 v175, v182
	v_mov_b32_e32 v182, v185
	v_pk_add_f32 v[174:175], v[174:175], v[182:183]
	ds_bpermute_b32 v183, v152, v175
	ds_bpermute_b32 v182, v152, v174
	s_waitcnt lgkmcnt(0)
	v_pk_add_f32 v[172:173], v[172:173], v[180:181]
	ds_bpermute_b32 v181, v156, v173
	ds_bpermute_b32 v180, v156, v172
	v_mov_b32_e32 v184, v193
	v_pk_add_f32 v[174:175], v[174:175], v[182:183]
	ds_bpermute_b32 v183, v156, v175
	ds_bpermute_b32 v182, v156, v174
	s_waitcnt lgkmcnt(2)
	v_pk_add_f32 v[172:173], v[172:173], v[180:181]
	v_mov_b32_e32 v185, v194
	v_mov_b32_e32 v193, v195
	v_mov_b32_e32 v186, v197
	v_mov_b32_e32 v187, v198
	v_pk_fma_f32 v[172:173], v[172:173], s[14:15], v[176:177] op_sel_hi:[1,0,0]
	v_mov_b32_e32 v197, v199
	v_pk_add_f32 v[184:185], v[184:185], v[192:193]
	v_mul_f32_e32 v160, 0x4b800000, v173
	v_cmp_gt_f32_e32 vcc, s39, v173
	v_pk_add_f32 v[180:181], v[186:187], v[196:197]
	s_waitcnt lgkmcnt(0)
	v_pk_add_f32 v[174:175], v[174:175], v[182:183]
	v_cndmask_b32_e32 v160, v173, v160, vcc
	v_mov_b32_e32 v182, v180
	v_mov_b32_e32 v183, v184
	v_mov_b32_e32 v184, v181
	v_rsq_f32_e32 v160, v160
	v_pk_add_f32 v[180:181], v[182:183], v[184:185]
	ds_bpermute_b32 v183, v152, v181
	ds_bpermute_b32 v182, v152, v180
	v_pk_fma_f32 v[174:175], v[174:175], s[14:15], v[176:177] op_sel_hi:[1,0,0]
	v_mul_f32_e32 v164, 0x4b800000, v172
	v_cmp_gt_f32_e64 s[0:1], s39, v172
	v_mul_f32_e32 v170, 0x45800000, v160
	v_mul_f32_e32 v166, 0x4b800000, v175
	v_cndmask_b32_e64 v164, v172, v164, s[0:1]
	v_cmp_gt_f32_e64 s[4:5], s39, v175
	v_cndmask_b32_e32 v172, v160, v170, vcc
	v_mul_f32_e32 v160, 0x4b800000, v174
	v_cmp_gt_f32_e32 vcc, s39, v174
	v_cndmask_b32_e64 v166, v175, v166, s[4:5]
	v_mov_b32_e32 v184, v205
	v_cndmask_b32_e32 v160, v174, v160, vcc
	s_waitcnt lgkmcnt(0)
	v_pk_add_f32 v[174:175], v[180:181], v[182:183]
	ds_bpermute_b32 v181, v156, v175
	ds_bpermute_b32 v180, v156, v174
	v_mov_b32_e32 v185, v206
	v_mov_b32_e32 v205, v207
	v_pk_add_f32 v[184:185], v[184:185], v[204:205]
	v_rsq_f32_e32 v164, v164
	s_waitcnt lgkmcnt(0)
	v_pk_add_f32 v[174:175], v[174:175], v[180:181]
	v_mov_b32_e32 v180, v201
	v_mov_b32_e32 v181, v202
	v_mov_b32_e32 v201, v203
	v_pk_add_f32 v[180:181], v[180:181], v[200:201]
	v_mov_b32_e32 v186, v184
	v_mov_b32_e32 v187, v180
	v_mov_b32_e32 v180, v185
	v_rsq_f32_e32 v166, v166
	v_pk_add_f32 v[180:181], v[186:187], v[180:181]
	ds_bpermute_b32 v185, v152, v181
	ds_bpermute_b32 v184, v152, v180
	v_mul_f32_e32 v173, 0x45800000, v164
	v_cndmask_b32_e64 v182, v164, v173, s[0:1]
	v_mul_f32_e32 v164, 0x45800000, v166
	v_pk_fma_f32 v[174:175], v[174:175], s[14:15], v[176:177] op_sel_hi:[1,0,0]
	v_cndmask_b32_e64 v170, v166, v164, s[4:5]
	v_mul_f32_e32 v166, 0x4b800000, v175
	v_cmp_gt_f32_e64 s[0:1], s39, v175
	v_mul_f32_e32 v152, 0x4b800000, v174
	v_cmp_gt_f32_e64 s[4:5], s39, v174
	v_cndmask_b32_e64 v166, v175, v166, s[0:1]
	v_rsq_f32_e32 v160, v160
	v_cndmask_b32_e64 v152, v174, v152, s[4:5]
	s_waitcnt lgkmcnt(0)
	v_pk_add_f32 v[174:175], v[180:181], v[184:185]
	ds_bpermute_b32 v181, v156, v175
	ds_bpermute_b32 v180, v156, v174
	v_rsq_f32_e32 v173, v166
	v_mul_f32_e32 v164, 0x45800000, v160
	v_cndmask_b32_e32 v166, v160, v164, vcc
	v_rsq_f32_e32 v152, v152
	s_waitcnt lgkmcnt(0)
	v_pk_add_f32 v[174:175], v[174:175], v[180:181]
	v_mul_f32_e32 v156, 0x45800000, v173
	v_pk_fma_f32 v[174:175], v[174:175], s[14:15], v[176:177] op_sel_hi:[1,0,0]
	v_cndmask_b32_e64 v164, v173, v156, s[0:1]
	v_mul_f32_e32 v160, 0x4b800000, v175
	v_cmp_gt_f32_e32 vcc, s39, v175
	v_cmp_gt_f32_e64 s[0:1], s39, v174
	v_mul_f32_e32 v156, 0x45800000, v152
	v_cndmask_b32_e32 v160, v175, v160, vcc
	v_rsq_f32_e32 v173, v160
	v_mul_f32_e32 v160, 0x4b800000, v174
	v_cndmask_b32_e64 v160, v174, v160, s[0:1]
	v_rsq_f32_e32 v174, v160
	v_cndmask_b32_e64 v160, v152, v156, s[4:5]
	v_mul_f32_e32 v152, 0x45800000, v173
	v_cndmask_b32_e32 v156, v173, v152, vcc
	v_mul_f32_e32 v152, 0x45800000, v174
	v_cndmask_b32_e64 v152, v174, v152, s[0:1]
	s_lshl_b32 s0, s70, 8
	s_or_b32 s0, s0, s33
	s_ashr_i32 s4, s0, 6
	s_ashr_i32 s5, s4, 31
	s_lshl_b64 s[0:1], s[4:5], 22
	v_pk_mul_f32 v[124:125], v[124:125], v[172:173] op_sel_hi:[1,0]
	v_pk_mul_f32 v[120:121], v[120:121], v[172:173] op_sel_hi:[1,0]
	s_add_u32 s0, s84, s0
	v_pk_mul_f32 v[126:127], v[126:127], v[172:173] op_sel_hi:[1,0]
	v_pk_mul_f32 v[122:123], v[122:123], v[172:173] op_sel_hi:[1,0]
	v_max_f32_e32 v124, 0, v124
	v_max_f32_e32 v120, 0, v120
	v_max_f32_e32 v125, 0, v125
	v_max_f32_e32 v121, 0, v121
	s_addc_u32 s1, s85, s1
	s_or_b32 s4, s4, 2
	v_pk_mul_f32 v[124:125], v[124:125], v[124:125]
	v_pk_mul_f32 v[174:175], v[120:121], v[120:121]
	v_max_f32_e32 v120, 0, v126
	v_max_f32_e32 v122, 0, v122
	v_max_f32_e32 v121, 0, v127
	v_max_f32_e32 v123, 0, v123
	s_ashr_i32 s5, s4, 31
	v_pk_mul_f32 v[126:127], v[120:121], v[120:121]
	v_pk_mul_f32 v[176:177], v[122:123], v[122:123]
	v_cvt_pk_bf16_f32 v120, v124, v125
	v_lshl_add_u64 v[124:125], s[0:1], 0, v[168:169]
	v_pk_mul_f32 v[116:117], v[116:117], v[172:173] op_sel_hi:[1,0]
	v_pk_mul_f32 v[112:113], v[112:113], v[172:173] op_sel_hi:[1,0]
	s_lshl_b64 s[4:5], s[4:5], 22
	v_cvt_pk_bf16_f32 v121, v126, v127
	v_cvt_pk_bf16_f32 v122, v174, v175
	v_cvt_pk_bf16_f32 v123, v176, v177
	v_lshl_add_u64 v[124:125], v[124:125], 0, v[136:137]
	v_pk_mul_f32 v[118:119], v[118:119], v[172:173] op_sel_hi:[1,0]
	v_pk_mul_f32 v[114:115], v[114:115], v[172:173] op_sel_hi:[1,0]
	v_max_f32_e32 v116, 0, v116
	v_max_f32_e32 v112, 0, v112
	v_max_f32_e32 v117, 0, v117
	v_max_f32_e32 v113, 0, v113
	s_add_u32 s4, s84, s4
	global_store_dwordx4 v[124:125], v[120:123], off nt
	v_pk_mul_f32 v[116:117], v[116:117], v[116:117]
	v_max_f32_e32 v114, 0, v114
	v_pk_mul_f32 v[120:121], v[112:113], v[112:113]
	v_max_f32_e32 v112, 0, v118
	v_max_f32_e32 v113, 0, v119
	v_max_f32_e32 v115, 0, v115
	s_addc_u32 s5, s85, s5
	v_pk_mul_f32 v[118:119], v[112:113], v[112:113]
	v_pk_mul_f32 v[122:123], v[114:115], v[114:115]
	v_cvt_pk_bf16_f32 v112, v116, v117
	v_lshl_add_u64 v[116:117], s[4:5], 0, v[168:169]
	v_pk_mul_f32 v[108:109], v[108:109], v[182:183] op_sel_hi:[1,0]
	v_pk_mul_f32 v[104:105], v[104:105], v[182:183] op_sel_hi:[1,0]
	v_cvt_pk_bf16_f32 v113, v118, v119
	v_cvt_pk_bf16_f32 v114, v120, v121
	v_cvt_pk_bf16_f32 v115, v122, v123
	v_lshl_add_u64 v[116:117], v[116:117], 0, v[136:137]
	v_pk_mul_f32 v[110:111], v[110:111], v[182:183] op_sel_hi:[1,0]
	v_pk_mul_f32 v[106:107], v[106:107], v[182:183] op_sel_hi:[1,0]
	v_max_f32_e32 v108, 0, v108
	v_max_f32_e32 v104, 0, v104
	v_max_f32_e32 v109, 0, v109
	v_max_f32_e32 v105, 0, v105
	global_store_dwordx4 v[116:117], v[112:115], off nt
	v_pk_mul_f32 v[108:109], v[108:109], v[108:109]
	v_max_f32_e32 v106, 0, v106
	v_lshlrev_b64 v[112:113], 7, v[162:163]
	v_pk_mul_f32 v[114:115], v[104:105], v[104:105]
	v_max_f32_e32 v104, 0, v110
	v_max_f32_e32 v105, 0, v111
	v_max_f32_e32 v107, 0, v107
	v_pk_mul_f32 v[110:111], v[104:105], v[104:105]
	v_pk_mul_f32 v[116:117], v[106:107], v[106:107]
	v_cvt_pk_bf16_f32 v104, v108, v109
	v_lshl_add_u64 v[108:109], s[0:1], 0, v[112:113]
	v_pk_mul_f32 v[100:101], v[100:101], v[182:183] op_sel_hi:[1,0]
	v_pk_mul_f32 v[96:97], v[96:97], v[182:183] op_sel_hi:[1,0]
	v_cvt_pk_bf16_f32 v105, v110, v111
	v_cvt_pk_bf16_f32 v106, v114, v115
	v_cvt_pk_bf16_f32 v107, v116, v117
	v_lshl_add_u64 v[108:109], v[108:109], 0, v[136:137]
	v_pk_mul_f32 v[102:103], v[102:103], v[182:183] op_sel_hi:[1,0]
	v_pk_mul_f32 v[98:99], v[98:99], v[182:183] op_sel_hi:[1,0]
	v_max_f32_e32 v100, 0, v100
	v_max_f32_e32 v96, 0, v96
	v_max_f32_e32 v101, 0, v101
	v_max_f32_e32 v97, 0, v97
	global_store_dwordx4 v[108:109], v[104:107], off nt
	v_pk_mul_f32 v[100:101], v[100:101], v[100:101]
	v_max_f32_e32 v98, 0, v98
	v_pk_mul_f32 v[104:105], v[96:97], v[96:97]
	v_max_f32_e32 v96, 0, v102
	v_max_f32_e32 v97, 0, v103
	v_max_f32_e32 v99, 0, v99
	v_pk_mul_f32 v[102:103], v[96:97], v[96:97]
	v_pk_mul_f32 v[106:107], v[98:99], v[98:99]
	v_cvt_pk_bf16_f32 v96, v100, v101
	v_lshl_add_u64 v[100:101], s[4:5], 0, v[112:113]
	v_pk_mul_f32 v[92:93], v[92:93], v[170:171] op_sel_hi:[1,0]
	v_pk_mul_f32 v[88:89], v[88:89], v[170:171] op_sel_hi:[1,0]
	v_cvt_pk_bf16_f32 v97, v102, v103
	v_cvt_pk_bf16_f32 v98, v104, v105
	v_cvt_pk_bf16_f32 v99, v106, v107
	v_lshl_add_u64 v[100:101], v[100:101], 0, v[136:137]
	v_pk_mul_f32 v[94:95], v[94:95], v[170:171] op_sel_hi:[1,0]
	v_pk_mul_f32 v[90:91], v[90:91], v[170:171] op_sel_hi:[1,0]
	v_max_f32_e32 v92, 0, v92
	v_max_f32_e32 v88, 0, v88
	v_max_f32_e32 v93, 0, v93
	v_max_f32_e32 v89, 0, v89
	global_store_dwordx4 v[100:101], v[96:99], off nt
	v_pk_mul_f32 v[92:93], v[92:93], v[92:93]
	v_max_f32_e32 v90, 0, v90
	v_lshlrev_b64 v[96:97], 7, v[158:159]
	v_pk_mul_f32 v[98:99], v[88:89], v[88:89]
	v_max_f32_e32 v88, 0, v94
	v_max_f32_e32 v89, 0, v95
	v_max_f32_e32 v91, 0, v91
	v_pk_mul_f32 v[94:95], v[88:89], v[88:89]
	v_pk_mul_f32 v[100:101], v[90:91], v[90:91]
	v_cvt_pk_bf16_f32 v88, v92, v93
	v_lshl_add_u64 v[92:93], s[0:1], 0, v[96:97]
	v_pk_mul_f32 v[84:85], v[84:85], v[170:171] op_sel_hi:[1,0]
	v_pk_mul_f32 v[80:81], v[80:81], v[170:171] op_sel_hi:[1,0]
	v_cvt_pk_bf16_f32 v89, v94, v95
	v_cvt_pk_bf16_f32 v90, v98, v99
	v_cvt_pk_bf16_f32 v91, v100, v101
	v_lshl_add_u64 v[92:93], v[92:93], 0, v[136:137]
	v_pk_mul_f32 v[86:87], v[86:87], v[170:171] op_sel_hi:[1,0]
	v_pk_mul_f32 v[82:83], v[82:83], v[170:171] op_sel_hi:[1,0]
	v_max_f32_e32 v84, 0, v84
	v_max_f32_e32 v80, 0, v80
	v_max_f32_e32 v85, 0, v85
	v_max_f32_e32 v81, 0, v81
	global_store_dwordx4 v[92:93], v[88:91], off nt
	v_pk_mul_f32 v[84:85], v[84:85], v[84:85]
	v_max_f32_e32 v82, 0, v82
	v_pk_mul_f32 v[88:89], v[80:81], v[80:81]
	v_max_f32_e32 v80, 0, v86
	v_max_f32_e32 v81, 0, v87
	v_max_f32_e32 v83, 0, v83
	v_pk_mul_f32 v[86:87], v[80:81], v[80:81]
	v_pk_mul_f32 v[90:91], v[82:83], v[82:83]
	v_cvt_pk_bf16_f32 v80, v84, v85
	v_lshl_add_u64 v[84:85], s[4:5], 0, v[96:97]
	v_pk_mul_f32 v[76:77], v[76:77], v[166:167] op_sel_hi:[1,0]
	v_pk_mul_f32 v[72:73], v[72:73], v[166:167] op_sel_hi:[1,0]
	v_cvt_pk_bf16_f32 v81, v86, v87
	v_cvt_pk_bf16_f32 v82, v88, v89
	v_cvt_pk_bf16_f32 v83, v90, v91
	v_lshl_add_u64 v[84:85], v[84:85], 0, v[136:137]
	v_pk_mul_f32 v[78:79], v[78:79], v[166:167] op_sel_hi:[1,0]
	v_pk_mul_f32 v[74:75], v[74:75], v[166:167] op_sel_hi:[1,0]
	v_max_f32_e32 v76, 0, v76
	v_max_f32_e32 v72, 0, v72
	v_max_f32_e32 v77, 0, v77
	v_max_f32_e32 v73, 0, v73
	global_store_dwordx4 v[84:85], v[80:83], off nt
	v_pk_mul_f32 v[76:77], v[76:77], v[76:77]
	v_max_f32_e32 v74, 0, v74
	v_lshlrev_b64 v[80:81], 7, v[154:155]
	v_pk_mul_f32 v[82:83], v[72:73], v[72:73]
	v_max_f32_e32 v72, 0, v78
	v_max_f32_e32 v73, 0, v79
	v_max_f32_e32 v75, 0, v75
	v_pk_mul_f32 v[78:79], v[72:73], v[72:73]
	v_pk_mul_f32 v[84:85], v[74:75], v[74:75]
	v_cvt_pk_bf16_f32 v72, v76, v77
	v_lshl_add_u64 v[76:77], s[0:1], 0, v[80:81]
	v_pk_mul_f32 v[68:69], v[68:69], v[166:167] op_sel_hi:[1,0]
	v_pk_mul_f32 v[64:65], v[64:65], v[166:167] op_sel_hi:[1,0]
	v_cvt_pk_bf16_f32 v73, v78, v79
	v_cvt_pk_bf16_f32 v74, v82, v83
	v_cvt_pk_bf16_f32 v75, v84, v85
	v_lshl_add_u64 v[76:77], v[76:77], 0, v[136:137]
	v_pk_mul_f32 v[70:71], v[70:71], v[166:167] op_sel_hi:[1,0]
	v_pk_mul_f32 v[66:67], v[66:67], v[166:167] op_sel_hi:[1,0]
	v_max_f32_e32 v68, 0, v68
	v_max_f32_e32 v64, 0, v64
	v_max_f32_e32 v69, 0, v69
	v_max_f32_e32 v65, 0, v65
	global_store_dwordx4 v[76:77], v[72:75], off nt
	v_pk_mul_f32 v[68:69], v[68:69], v[68:69]
	v_max_f32_e32 v66, 0, v66
	v_pk_mul_f32 v[72:73], v[64:65], v[64:65]
	v_max_f32_e32 v64, 0, v70
	v_max_f32_e32 v65, 0, v71
	v_max_f32_e32 v67, 0, v67
	v_pk_mul_f32 v[70:71], v[64:65], v[64:65]
	v_pk_mul_f32 v[74:75], v[66:67], v[66:67]
	v_cvt_pk_bf16_f32 v64, v68, v69
	v_lshl_add_u64 v[68:69], s[4:5], 0, v[80:81]
	v_pk_mul_f32 v[60:61], v[60:61], v[164:165] op_sel_hi:[1,0]
	v_pk_mul_f32 v[56:57], v[56:57], v[164:165] op_sel_hi:[1,0]
	v_cvt_pk_bf16_f32 v65, v70, v71
	v_cvt_pk_bf16_f32 v66, v72, v73
	v_cvt_pk_bf16_f32 v67, v74, v75
	v_lshl_add_u64 v[68:69], v[68:69], 0, v[136:137]
	v_pk_mul_f32 v[62:63], v[62:63], v[164:165] op_sel_hi:[1,0]
	v_pk_mul_f32 v[58:59], v[58:59], v[164:165] op_sel_hi:[1,0]
	v_max_f32_e32 v60, 0, v60
	v_max_f32_e32 v56, 0, v56
	v_max_f32_e32 v61, 0, v61
	v_max_f32_e32 v57, 0, v57
	global_store_dwordx4 v[68:69], v[64:67], off nt
	v_pk_mul_f32 v[60:61], v[60:61], v[60:61]
	v_max_f32_e32 v58, 0, v58
	v_lshlrev_b64 v[64:65], 7, v[150:151]
	v_pk_mul_f32 v[66:67], v[56:57], v[56:57]
	v_max_f32_e32 v56, 0, v62
	v_max_f32_e32 v57, 0, v63
	v_max_f32_e32 v59, 0, v59
	v_pk_mul_f32 v[62:63], v[56:57], v[56:57]
	v_pk_mul_f32 v[68:69], v[58:59], v[58:59]
	v_cvt_pk_bf16_f32 v56, v60, v61
	v_lshl_add_u64 v[60:61], s[0:1], 0, v[64:65]
	v_pk_mul_f32 v[52:53], v[52:53], v[164:165] op_sel_hi:[1,0]
	v_pk_mul_f32 v[48:49], v[48:49], v[164:165] op_sel_hi:[1,0]
	v_cvt_pk_bf16_f32 v57, v62, v63
	v_cvt_pk_bf16_f32 v58, v66, v67
	v_cvt_pk_bf16_f32 v59, v68, v69
	v_lshl_add_u64 v[60:61], v[60:61], 0, v[136:137]
	v_pk_mul_f32 v[54:55], v[54:55], v[164:165] op_sel_hi:[1,0]
	v_pk_mul_f32 v[50:51], v[50:51], v[164:165] op_sel_hi:[1,0]
	v_max_f32_e32 v52, 0, v52
	v_max_f32_e32 v48, 0, v48
	v_max_f32_e32 v53, 0, v53
	v_max_f32_e32 v49, 0, v49
	global_store_dwordx4 v[60:61], v[56:59], off nt
	v_pk_mul_f32 v[52:53], v[52:53], v[52:53]
	v_max_f32_e32 v50, 0, v50
	v_pk_mul_f32 v[56:57], v[48:49], v[48:49]
	v_max_f32_e32 v48, 0, v54
	v_max_f32_e32 v49, 0, v55
	v_max_f32_e32 v51, 0, v51
	v_pk_mul_f32 v[54:55], v[48:49], v[48:49]
	v_pk_mul_f32 v[58:59], v[50:51], v[50:51]
	v_cvt_pk_bf16_f32 v48, v52, v53
	v_lshl_add_u64 v[52:53], s[4:5], 0, v[64:65]
	v_pk_mul_f32 v[44:45], v[44:45], v[160:161] op_sel_hi:[1,0]
	v_pk_mul_f32 v[40:41], v[40:41], v[160:161] op_sel_hi:[1,0]
	v_cvt_pk_bf16_f32 v49, v54, v55
	v_cvt_pk_bf16_f32 v50, v56, v57
	v_cvt_pk_bf16_f32 v51, v58, v59
	v_lshl_add_u64 v[52:53], v[52:53], 0, v[136:137]
	v_pk_mul_f32 v[46:47], v[46:47], v[160:161] op_sel_hi:[1,0]
	v_pk_mul_f32 v[42:43], v[42:43], v[160:161] op_sel_hi:[1,0]
	v_max_f32_e32 v44, 0, v44
	v_max_f32_e32 v40, 0, v40
	v_max_f32_e32 v45, 0, v45
	v_max_f32_e32 v41, 0, v41
	global_store_dwordx4 v[52:53], v[48:51], off nt
	v_pk_mul_f32 v[44:45], v[44:45], v[44:45]
	v_max_f32_e32 v42, 0, v42
	v_lshlrev_b64 v[48:49], 7, v[148:149]
	v_pk_mul_f32 v[50:51], v[40:41], v[40:41]
	v_max_f32_e32 v40, 0, v46
	v_max_f32_e32 v41, 0, v47
	v_max_f32_e32 v43, 0, v43
	v_pk_mul_f32 v[46:47], v[40:41], v[40:41]
	v_pk_mul_f32 v[52:53], v[42:43], v[42:43]
	v_cvt_pk_bf16_f32 v40, v44, v45
	v_lshl_add_u64 v[44:45], s[0:1], 0, v[48:49]
	v_pk_mul_f32 v[36:37], v[36:37], v[160:161] op_sel_hi:[1,0]
	v_pk_mul_f32 v[32:33], v[32:33], v[160:161] op_sel_hi:[1,0]
	v_cvt_pk_bf16_f32 v41, v46, v47
	v_cvt_pk_bf16_f32 v42, v50, v51
	v_cvt_pk_bf16_f32 v43, v52, v53
	v_lshl_add_u64 v[44:45], v[44:45], 0, v[136:137]
	v_pk_mul_f32 v[38:39], v[38:39], v[160:161] op_sel_hi:[1,0]
	v_pk_mul_f32 v[34:35], v[34:35], v[160:161] op_sel_hi:[1,0]
	v_max_f32_e32 v36, 0, v36
	v_max_f32_e32 v32, 0, v32
	v_max_f32_e32 v37, 0, v37
	v_max_f32_e32 v33, 0, v33
	global_store_dwordx4 v[44:45], v[40:43], off nt
	v_pk_mul_f32 v[36:37], v[36:37], v[36:37]
	v_max_f32_e32 v34, 0, v34
	v_pk_mul_f32 v[40:41], v[32:33], v[32:33]
	v_max_f32_e32 v32, 0, v38
	v_max_f32_e32 v33, 0, v39
	v_max_f32_e32 v35, 0, v35
	v_pk_mul_f32 v[38:39], v[32:33], v[32:33]
	v_pk_mul_f32 v[42:43], v[34:35], v[34:35]
	v_cvt_pk_bf16_f32 v32, v36, v37
	v_lshl_add_u64 v[36:37], s[4:5], 0, v[48:49]
	v_pk_mul_f32 v[28:29], v[28:29], v[156:157] op_sel_hi:[1,0]
	v_pk_mul_f32 v[24:25], v[24:25], v[156:157] op_sel_hi:[1,0]
	v_cvt_pk_bf16_f32 v33, v38, v39
	v_cvt_pk_bf16_f32 v34, v40, v41
	v_cvt_pk_bf16_f32 v35, v42, v43
	v_lshl_add_u64 v[36:37], v[36:37], 0, v[136:137]
	v_pk_mul_f32 v[30:31], v[30:31], v[156:157] op_sel_hi:[1,0]
	v_pk_mul_f32 v[26:27], v[26:27], v[156:157] op_sel_hi:[1,0]
	v_max_f32_e32 v28, 0, v28
	v_max_f32_e32 v24, 0, v24
	v_max_f32_e32 v29, 0, v29
	v_max_f32_e32 v25, 0, v25
	global_store_dwordx4 v[36:37], v[32:35], off nt
	v_pk_mul_f32 v[28:29], v[28:29], v[28:29]
	v_max_f32_e32 v26, 0, v26
	v_lshlrev_b64 v[32:33], 7, v[146:147]
	v_pk_mul_f32 v[34:35], v[24:25], v[24:25]
	v_max_f32_e32 v24, 0, v30
	v_max_f32_e32 v25, 0, v31
	v_max_f32_e32 v27, 0, v27
	v_pk_mul_f32 v[30:31], v[24:25], v[24:25]
	v_pk_mul_f32 v[36:37], v[26:27], v[26:27]
	v_cvt_pk_bf16_f32 v24, v28, v29
	v_lshl_add_u64 v[28:29], s[0:1], 0, v[32:33]
	v_pk_mul_f32 v[20:21], v[20:21], v[156:157] op_sel_hi:[1,0]
	v_pk_mul_f32 v[16:17], v[16:17], v[156:157] op_sel_hi:[1,0]
	v_cvt_pk_bf16_f32 v25, v30, v31
	v_cvt_pk_bf16_f32 v26, v34, v35
	v_cvt_pk_bf16_f32 v27, v36, v37
	v_lshl_add_u64 v[28:29], v[28:29], 0, v[136:137]
	v_pk_mul_f32 v[22:23], v[22:23], v[156:157] op_sel_hi:[1,0]
	v_pk_mul_f32 v[18:19], v[18:19], v[156:157] op_sel_hi:[1,0]
	v_max_f32_e32 v20, 0, v20
	v_max_f32_e32 v16, 0, v16
	v_max_f32_e32 v21, 0, v21
	v_max_f32_e32 v17, 0, v17
	global_store_dwordx4 v[28:29], v[24:27], off nt
	v_pk_mul_f32 v[20:21], v[20:21], v[20:21]
	v_max_f32_e32 v18, 0, v18
	v_pk_mul_f32 v[24:25], v[16:17], v[16:17]
	v_max_f32_e32 v16, 0, v22
	v_max_f32_e32 v17, 0, v23
	v_max_f32_e32 v19, 0, v19
	v_pk_mul_f32 v[22:23], v[16:17], v[16:17]
	v_pk_mul_f32 v[26:27], v[18:19], v[18:19]
	v_cvt_pk_bf16_f32 v16, v20, v21
	v_lshl_add_u64 v[20:21], s[4:5], 0, v[32:33]
	v_pk_mul_f32 v[12:13], v[12:13], v[152:153] op_sel_hi:[1,0]
	v_pk_mul_f32 v[8:9], v[8:9], v[152:153] op_sel_hi:[1,0]
	v_cvt_pk_bf16_f32 v17, v22, v23
	v_cvt_pk_bf16_f32 v18, v24, v25
	v_cvt_pk_bf16_f32 v19, v26, v27
	v_lshl_add_u64 v[20:21], v[20:21], 0, v[136:137]
	v_pk_mul_f32 v[14:15], v[14:15], v[152:153] op_sel_hi:[1,0]
	v_pk_mul_f32 v[10:11], v[10:11], v[152:153] op_sel_hi:[1,0]
	v_max_f32_e32 v12, 0, v12
	v_max_f32_e32 v8, 0, v8
	v_max_f32_e32 v13, 0, v13
	v_max_f32_e32 v9, 0, v9
	global_store_dwordx4 v[20:21], v[16:19], off nt
	v_pk_mul_f32 v[12:13], v[12:13], v[12:13]
	v_max_f32_e32 v10, 0, v10
	v_lshlrev_b64 v[16:17], 7, v[144:145]
	v_pk_mul_f32 v[18:19], v[8:9], v[8:9]
	v_max_f32_e32 v8, 0, v14
	v_max_f32_e32 v9, 0, v15
	v_max_f32_e32 v11, 0, v11
	v_pk_mul_f32 v[14:15], v[8:9], v[8:9]
	v_pk_mul_f32 v[20:21], v[10:11], v[10:11]
	v_cvt_pk_bf16_f32 v8, v12, v13
	v_lshl_add_u64 v[12:13], s[0:1], 0, v[16:17]
	v_pk_mul_f32 v[4:5], v[4:5], v[152:153] op_sel_hi:[1,0]
	v_pk_mul_f32 v[0:1], v[0:1], v[152:153] op_sel_hi:[1,0]
	v_cvt_pk_bf16_f32 v9, v14, v15
	v_cvt_pk_bf16_f32 v10, v18, v19
	v_cvt_pk_bf16_f32 v11, v20, v21
	v_lshl_add_u64 v[12:13], v[12:13], 0, v[136:137]
	v_pk_mul_f32 v[6:7], v[6:7], v[152:153] op_sel_hi:[1,0]
	v_pk_mul_f32 v[2:3], v[2:3], v[152:153] op_sel_hi:[1,0]
	v_max_f32_e32 v4, 0, v4
	v_max_f32_e32 v0, 0, v0
	v_max_f32_e32 v5, 0, v5
	v_max_f32_e32 v1, 0, v1
	global_store_dwordx4 v[12:13], v[8:11], off nt
	v_pk_mul_f32 v[4:5], v[4:5], v[4:5]
	v_max_f32_e32 v2, 0, v2
	v_pk_mul_f32 v[8:9], v[0:1], v[0:1]
	v_max_f32_e32 v0, 0, v6
	v_max_f32_e32 v1, 0, v7
	v_max_f32_e32 v3, 0, v3
	v_pk_mul_f32 v[6:7], v[0:1], v[0:1]
	v_pk_mul_f32 v[10:11], v[2:3], v[2:3]
	v_cvt_pk_bf16_f32 v0, v4, v5
	v_lshl_add_u64 v[4:5], s[4:5], 0, v[16:17]
	v_cvt_pk_bf16_f32 v1, v6, v7
	v_cvt_pk_bf16_f32 v2, v8, v9
	v_cvt_pk_bf16_f32 v3, v10, v11
	v_lshl_add_u64 v[4:5], v[4:5], 0, v[136:137]
	s_and_b64 vcc, exec, s[24:25]
	s_mov_b32 s70, s20
	s_mov_b32 s24, s20
	s_mov_b64 s[4:5], s[26:27]
	s_mov_b64 s[0:1], s[22:23]
	global_store_dwordx4 v[4:5], v[0:3], off nt
	s_cbranch_vccz .LBB0_1433
	s_waitcnt vmcnt(0)
	s_cmpk_gt_u32 s7, 0xff
	s_cbranch_scc1 .LBB0_1445
	s_barrier

.LBB0_1512:
	ds_read_b128 v[128:131], v203
	ds_read_b128 v[132:135], v203 offset:1024
	ds_read_b128 v[136:139], v203 offset:2048
	ds_read_b128 v[140:143], v203 offset:3072
	s_add_u32 s26, s24, 0x3fc000
	s_addc_u32 s27, s25, 0
	s_cmp_eq_u32 s49, 60
	s_cselect_b32 s30, s7, s26
	s_cselect_b32 s31, s5, s27
	s_cselect_b32 s26, s15, s17
	s_cselect_b32 s27, s8, s48
	s_add_u32 s28, s30, 0x400000
	s_addc_u32 s29, s31, 0
	v_lshl_add_u64 v[196:197], s[24:25], 0, v[168:169]
	s_add_i32 m0, s33, 0xc000
	ds_read_b128 v[144:147], v204
	ds_read_b128 v[148:151], v204 offset:1024
	ds_read_b128 v[172:175], v204 offset:2048
	ds_read_b128 v[176:179], v204 offset:3072
	ds_read_b128 v[180:183], v204 offset:4096
	ds_read_b128 v[184:187], v204 offset:5120
	ds_read_b128 v[188:191], v204 offset:6144
	ds_read_b128 v[192:195], v204 offset:7168
	global_load_lds_dwordx4 v[196:197], off
	v_lshl_add_u64 v[196:197], s[24:25], 0, v[170:171]
	s_add_i32 m0, s33, 0xe000
	s_nop 0
	global_load_lds_dwordx4 v[196:197], off
	s_waitcnt lgkmcnt(8)
	s_barrier
	s_waitcnt lgkmcnt(0)
	s_setprio 1
	v_mfma_f32_16x16x32_bf16 v[124:127], v[128:131], v[144:147], v[124:127]
	v_mfma_f32_16x16x32_bf16 v[120:123], v[136:139], v[144:147], v[120:123]
	v_mfma_f32_16x16x32_bf16 v[108:111], v[128:131], v[172:175], v[108:111]
	v_mfma_f32_16x16x32_bf16 v[104:107], v[136:139], v[172:175], v[104:107]
	v_mfma_f32_16x16x32_bf16 v[92:95], v[128:131], v[180:183], v[92:95]
	v_mfma_f32_16x16x32_bf16 v[88:91], v[136:139], v[180:183], v[88:91]
	v_mfma_f32_16x16x32_bf16 v[76:79], v[128:131], v[188:191], v[76:79]
	v_mfma_f32_16x16x32_bf16 v[72:75], v[136:139], v[188:191], v[72:75]
	v_mfma_f32_16x16x32_bf16 v[124:127], v[132:135], v[148:151], v[124:127]
	v_mfma_f32_16x16x32_bf16 v[120:123], v[140:143], v[148:151], v[120:123]
	v_mfma_f32_16x16x32_bf16 v[108:111], v[132:135], v[176:179], v[108:111]
	v_mfma_f32_16x16x32_bf16 v[104:107], v[140:143], v[176:179], v[104:107]
	v_mfma_f32_16x16x32_bf16 v[92:95], v[132:135], v[184:187], v[92:95]
	v_mfma_f32_16x16x32_bf16 v[88:91], v[140:143], v[184:187], v[88:91]
	v_mfma_f32_16x16x32_bf16 v[76:79], v[132:135], v[192:195], v[76:79]
	v_mfma_f32_16x16x32_bf16 v[72:75], v[140:143], v[192:195], v[72:75]
	s_setprio 0
	s_barrier
	s_add_i32 s50, s44, s13
	v_lshl_add_u64 v[200:201], s[26:27], 0, v[156:157]
	s_mov_b32 m0, s50
	ds_read_b128 v[196:199], v205
	ds_read_b128 v[208:211], v205 offset:1024
	ds_read_b128 v[212:215], v205 offset:2048
	ds_read_b128 v[216:219], v205 offset:3072
	global_load_lds_dwordx4 v[200:201], off
	v_lshl_add_u64 v[200:201], s[26:27], 0, v[152:153]
	s_add_i32 m0, s50, 0x2000
	s_nop 0
	global_load_lds_dwordx4 v[200:201], off
	s_barrier
	s_waitcnt lgkmcnt(0)
	s_setprio 1
	v_mfma_f32_16x16x32_bf16 v[116:119], v[196:199], v[144:147], v[116:119]
	v_mfma_f32_16x16x32_bf16 v[112:115], v[212:215], v[144:147], v[112:115]
	v_mfma_f32_16x16x32_bf16 v[100:103], v[196:199], v[172:175], v[100:103]
	v_mfma_f32_16x16x32_bf16 v[96:99], v[212:215], v[172:175], v[96:99]
	v_mfma_f32_16x16x32_bf16 v[84:87], v[196:199], v[180:183], v[84:87]
	v_mfma_f32_16x16x32_bf16 v[80:83], v[212:215], v[180:183], v[80:83]
	v_mfma_f32_16x16x32_bf16 v[68:71], v[196:199], v[188:191], v[68:71]
	v_mfma_f32_16x16x32_bf16 v[64:67], v[212:215], v[188:191], v[64:67]
	v_mfma_f32_16x16x32_bf16 v[116:119], v[208:211], v[148:151], v[116:119]
	v_mfma_f32_16x16x32_bf16 v[112:115], v[216:219], v[148:151], v[112:115]
	v_mfma_f32_16x16x32_bf16 v[100:103], v[208:211], v[176:179], v[100:103]
	v_mfma_f32_16x16x32_bf16 v[96:99], v[216:219], v[176:179], v[96:99]
	v_mfma_f32_16x16x32_bf16 v[84:87], v[208:211], v[184:187], v[84:87]
	v_mfma_f32_16x16x32_bf16 v[80:83], v[216:219], v[184:187], v[80:83]
	v_mfma_f32_16x16x32_bf16 v[68:71], v[208:211], v[192:195], v[68:71]
	v_mfma_f32_16x16x32_bf16 v[64:67], v[216:219], v[192:195], v[64:67]
	s_setprio 0
	s_mov_b32 m0, s33
	v_lshl_add_u64 v[200:201], s[30:31], 0, v[158:159]
	s_barrier
	ds_read_b128 v[144:147], v204 offset:16384
	ds_read_b128 v[148:151], v204 offset:17408
	ds_read_b128 v[172:175], v204 offset:18432
	ds_read_b128 v[176:179], v204 offset:19456
	ds_read_b128 v[180:183], v204 offset:20480
	ds_read_b128 v[184:187], v204 offset:21504
	ds_read_b128 v[188:191], v204 offset:22528
	ds_read_b128 v[192:195], v204 offset:23552
	global_load_lds_dwordx4 v[200:201], off
	v_lshl_add_u64 v[200:201], s[30:31], 0, v[154:155]
	s_mov_b32 m0, s35
	s_nop 0
	global_load_lds_dwordx4 v[200:201], off
	s_barrier
	s_waitcnt lgkmcnt(0)
	s_setprio 1
	v_mfma_f32_16x16x32_bf16 v[60:63], v[128:131], v[144:147], v[60:63]
	v_mfma_f32_16x16x32_bf16 v[56:59], v[136:139], v[144:147], v[56:59]
	v_mfma_f32_16x16x32_bf16 v[44:47], v[128:131], v[172:175], v[44:47]
	v_mfma_f32_16x16x32_bf16 v[40:43], v[136:139], v[172:175], v[40:43]
	v_mfma_f32_16x16x32_bf16 v[28:31], v[128:131], v[180:183], v[28:31]
	v_mfma_f32_16x16x32_bf16 v[24:27], v[136:139], v[180:183], v[24:27]
	v_mfma_f32_16x16x32_bf16 v[12:15], v[128:131], v[188:191], v[12:15]
	v_mfma_f32_16x16x32_bf16 v[8:11], v[136:139], v[188:191], v[8:11]
	v_mfma_f32_16x16x32_bf16 v[60:63], v[132:135], v[148:151], v[60:63]
	v_mfma_f32_16x16x32_bf16 v[56:59], v[140:143], v[148:151], v[56:59]
	v_mfma_f32_16x16x32_bf16 v[44:47], v[132:135], v[176:179], v[44:47]
	v_mfma_f32_16x16x32_bf16 v[40:43], v[140:143], v[176:179], v[40:43]
	v_mfma_f32_16x16x32_bf16 v[28:31], v[132:135], v[184:187], v[28:31]
	v_mfma_f32_16x16x32_bf16 v[24:27], v[140:143], v[184:187], v[24:27]
	v_mfma_f32_16x16x32_bf16 v[12:15], v[132:135], v[192:195], v[12:15]
	v_mfma_f32_16x16x32_bf16 v[8:11], v[140:143], v[192:195], v[8:11]
	s_setprio 0
	s_barrier
	s_add_u32 s50, s26, 0x4000
	s_addc_u32 s51, s27, 0
	s_add_i32 s52, s45, s13
	v_lshl_add_u64 v[128:129], s[50:51], 0, v[156:157]
	s_mov_b32 m0, s52
	s_nop 0
	global_load_lds_dwordx4 v[128:129], off
	v_lshl_add_u64 v[128:129], s[50:51], 0, v[152:153]
	s_add_i32 m0, s52, 0x2000
	s_nop 0
	global_load_lds_dwordx4 v[128:129], off
	s_waitcnt vmcnt(6)
	s_barrier
	s_setprio 1
	v_mfma_f32_16x16x32_bf16 v[52:55], v[196:199], v[144:147], v[52:55]
	v_mfma_f32_16x16x32_bf16 v[48:51], v[212:215], v[144:147], v[48:51]
	v_mfma_f32_16x16x32_bf16 v[36:39], v[196:199], v[172:175], v[36:39]
	v_mfma_f32_16x16x32_bf16 v[32:35], v[212:215], v[172:175], v[32:35]
	v_mfma_f32_16x16x32_bf16 v[20:23], v[196:199], v[180:183], v[20:23]
	v_mfma_f32_16x16x32_bf16 v[16:19], v[212:215], v[180:183], v[16:19]
	v_mfma_f32_16x16x32_bf16 v[4:7], v[196:199], v[188:191], v[4:7]
	v_mfma_f32_16x16x32_bf16 v[0:3], v[212:215], v[188:191], v[0:3]
	v_mfma_f32_16x16x32_bf16 v[52:55], v[208:211], v[148:151], v[52:55]
	v_mfma_f32_16x16x32_bf16 v[48:51], v[216:219], v[148:151], v[48:51]
	v_mfma_f32_16x16x32_bf16 v[36:39], v[208:211], v[176:179], v[36:39]
	v_mfma_f32_16x16x32_bf16 v[32:35], v[216:219], v[176:179], v[32:35]
	v_mfma_f32_16x16x32_bf16 v[20:23], v[208:211], v[184:187], v[20:23]
	v_mfma_f32_16x16x32_bf16 v[16:19], v[216:219], v[184:187], v[16:19]
	v_mfma_f32_16x16x32_bf16 v[4:7], v[208:211], v[192:195], v[4:7]
	v_mfma_f32_16x16x32_bf16 v[0:3], v[216:219], v[192:195], v[0:3]
	s_setprio 0
	s_add_i32 s50, 0, 0x18000
	v_add_u32_e32 v140, s50, v202
	s_barrier
	ds_read_b128 v[128:131], v140
	ds_read_b128 v[132:135], v140 offset:1024
	ds_read_b128 v[136:139], v140 offset:2048
	ds_read_b128 v[140:143], v140 offset:3072
	s_add_u32 s30, s30, 0x4000
	s_addc_u32 s31, s31, 0
	s_mov_b32 m0, s36
	v_lshl_add_u64 v[196:197], s[30:31], 0, v[158:159]
	ds_read_b128 v[144:147], v204 offset:32768
	ds_read_b128 v[148:151], v204 offset:33792
	ds_read_b128 v[172:175], v204 offset:34816
	ds_read_b128 v[176:179], v204 offset:35840
	ds_read_b128 v[180:183], v204 offset:36864
	ds_read_b128 v[184:187], v204 offset:37888
	ds_read_b128 v[188:191], v204 offset:38912
	ds_read_b128 v[192:195], v204 offset:39936
	global_load_lds_dwordx4 v[196:197], off
	v_lshl_add_u64 v[196:197], s[30:31], 0, v[154:155]
	s_mov_b32 m0, s37
	s_nop 0
	global_load_lds_dwordx4 v[196:197], off
	s_waitcnt lgkmcnt(8)
	s_barrier
	s_waitcnt lgkmcnt(0)
	s_setprio 1
	v_mfma_f32_16x16x32_bf16 v[124:127], v[128:131], v[144:147], v[124:127]
	v_mfma_f32_16x16x32_bf16 v[120:123], v[136:139], v[144:147], v[120:123]
	v_mfma_f32_16x16x32_bf16 v[108:111], v[128:131], v[172:175], v[108:111]
	v_mfma_f32_16x16x32_bf16 v[104:107], v[136:139], v[172:175], v[104:107]
	v_mfma_f32_16x16x32_bf16 v[92:95], v[128:131], v[180:183], v[92:95]
	v_mfma_f32_16x16x32_bf16 v[88:91], v[136:139], v[180:183], v[88:91]
	v_mfma_f32_16x16x32_bf16 v[76:79], v[128:131], v[188:191], v[76:79]
	v_mfma_f32_16x16x32_bf16 v[72:75], v[136:139], v[188:191], v[72:75]
	v_mfma_f32_16x16x32_bf16 v[124:127], v[132:135], v[148:151], v[124:127]
	v_mfma_f32_16x16x32_bf16 v[120:123], v[140:143], v[148:151], v[120:123]
	v_mfma_f32_16x16x32_bf16 v[108:111], v[132:135], v[176:179], v[108:111]
	v_mfma_f32_16x16x32_bf16 v[104:107], v[140:143], v[176:179], v[104:107]
	v_mfma_f32_16x16x32_bf16 v[92:95], v[132:135], v[184:187], v[92:95]
	v_mfma_f32_16x16x32_bf16 v[88:91], v[140:143], v[184:187], v[88:91]
	v_mfma_f32_16x16x32_bf16 v[76:79], v[132:135], v[192:195], v[76:79]
	v_mfma_f32_16x16x32_bf16 v[72:75], v[140:143], v[192:195], v[72:75]
	s_setprio 0
	s_barrier
	s_add_i32 s51, 0, 0x1c000
	s_add_u32 s30, s26, 0x20000
	v_add_u32_e32 v200, s51, v202
	s_addc_u32 s31, s27, 0
	s_add_i32 s50, s50, s13
	ds_read_b128 v[196:199], v200
	ds_read_b128 v[208:211], v200 offset:1024
	ds_read_b128 v[212:215], v200 offset:2048
	ds_read_b128 v[216:219], v200 offset:3072
	v_lshl_add_u64 v[200:201], s[30:31], 0, v[156:157]
	s_mov_b32 m0, s50
	s_nop 0
	global_load_lds_dwordx4 v[200:201], off
	v_lshl_add_u64 v[200:201], s[30:31], 0, v[152:153]
	s_add_i32 m0, s50, 0x2000
	s_nop 0
	global_load_lds_dwordx4 v[200:201], off
	s_barrier
	s_waitcnt lgkmcnt(0)
	s_setprio 1
	v_mfma_f32_16x16x32_bf16 v[116:119], v[196:199], v[144:147], v[116:119]
	v_mfma_f32_16x16x32_bf16 v[112:115], v[212:215], v[144:147], v[112:115]
	v_mfma_f32_16x16x32_bf16 v[100:103], v[196:199], v[172:175], v[100:103]
	v_mfma_f32_16x16x32_bf16 v[96:99], v[212:215], v[172:175], v[96:99]
	v_mfma_f32_16x16x32_bf16 v[84:87], v[196:199], v[180:183], v[84:87]
	v_mfma_f32_16x16x32_bf16 v[80:83], v[212:215], v[180:183], v[80:83]
	v_mfma_f32_16x16x32_bf16 v[68:71], v[196:199], v[188:191], v[68:71]
	v_mfma_f32_16x16x32_bf16 v[64:67], v[212:215], v[188:191], v[64:67]
	v_mfma_f32_16x16x32_bf16 v[116:119], v[208:211], v[148:151], v[116:119]
	v_mfma_f32_16x16x32_bf16 v[112:115], v[216:219], v[148:151], v[112:115]
	v_mfma_f32_16x16x32_bf16 v[100:103], v[208:211], v[176:179], v[100:103]
	v_mfma_f32_16x16x32_bf16 v[96:99], v[216:219], v[176:179], v[96:99]
	v_mfma_f32_16x16x32_bf16 v[84:87], v[208:211], v[184:187], v[84:87]
	v_mfma_f32_16x16x32_bf16 v[80:83], v[216:219], v[184:187], v[80:83]
	v_mfma_f32_16x16x32_bf16 v[68:71], v[208:211], v[192:195], v[68:71]
	v_mfma_f32_16x16x32_bf16 v[64:67], v[216:219], v[192:195], v[64:67]
	s_setprio 0
	s_mov_b32 m0, s41
	v_lshl_add_u64 v[200:201], s[28:29], 0, v[158:159]
	s_barrier
	ds_read_b128 v[144:147], v204 offset:49152
	ds_read_b128 v[148:151], v204 offset:50176
	ds_read_b128 v[172:175], v204 offset:51200
	ds_read_b128 v[176:179], v204 offset:52224
	ds_read_b128 v[180:183], v204 offset:53248
	ds_read_b128 v[184:187], v204 offset:54272
	ds_read_b128 v[188:191], v204 offset:55296
	ds_read_b128 v[192:195], v204 offset:56320
	global_load_lds_dwordx4 v[200:201], off
	v_lshl_add_u64 v[200:201], s[28:29], 0, v[154:155]
	s_mov_b32 m0, s42
	s_nop 0
	global_load_lds_dwordx4 v[200:201], off
	s_barrier
	s_waitcnt lgkmcnt(0)
	s_setprio 1
	v_mfma_f32_16x16x32_bf16 v[60:63], v[128:131], v[144:147], v[60:63]
	v_mfma_f32_16x16x32_bf16 v[56:59], v[136:139], v[144:147], v[56:59]
	v_mfma_f32_16x16x32_bf16 v[44:47], v[128:131], v[172:175], v[44:47]
	v_mfma_f32_16x16x32_bf16 v[40:43], v[136:139], v[172:175], v[40:43]
	v_mfma_f32_16x16x32_bf16 v[28:31], v[128:131], v[180:183], v[28:31]
	v_mfma_f32_16x16x32_bf16 v[24:27], v[136:139], v[180:183], v[24:27]
	v_mfma_f32_16x16x32_bf16 v[12:15], v[128:131], v[188:191], v[12:15]
	v_mfma_f32_16x16x32_bf16 v[8:11], v[136:139], v[188:191], v[8:11]
	v_mfma_f32_16x16x32_bf16 v[60:63], v[132:135], v[148:151], v[60:63]
	v_mfma_f32_16x16x32_bf16 v[56:59], v[140:143], v[148:151], v[56:59]
	v_mfma_f32_16x16x32_bf16 v[44:47], v[132:135], v[176:179], v[44:47]
	v_mfma_f32_16x16x32_bf16 v[40:43], v[140:143], v[176:179], v[40:43]
	v_mfma_f32_16x16x32_bf16 v[28:31], v[132:135], v[184:187], v[28:31]
	v_mfma_f32_16x16x32_bf16 v[24:27], v[140:143], v[184:187], v[24:27]
	v_mfma_f32_16x16x32_bf16 v[12:15], v[132:135], v[192:195], v[12:15]
	v_mfma_f32_16x16x32_bf16 v[8:11], v[140:143], v[192:195], v[8:11]
	s_setprio 0
	s_barrier
	s_add_u32 s26, s26, 0x24000
	s_addc_u32 s27, s27, 0
	s_add_i32 s28, s51, s13
	v_lshl_add_u64 v[128:129], s[26:27], 0, v[156:157]
	s_mov_b32 m0, s28
	s_nop 0
	global_load_lds_dwordx4 v[128:129], off
	v_lshl_add_u64 v[128:129], s[26:27], 0, v[152:153]
	s_add_i32 m0, s28, 0x2000
	s_nop 0
	global_load_lds_dwordx4 v[128:129], off
	s_waitcnt vmcnt(6)
	s_barrier
	s_setprio 1
	v_mfma_f32_16x16x32_bf16 v[52:55], v[196:199], v[144:147], v[52:55]
	v_mfma_f32_16x16x32_bf16 v[48:51], v[212:215], v[144:147], v[48:51]
	v_mfma_f32_16x16x32_bf16 v[36:39], v[196:199], v[172:175], v[36:39]
	v_mfma_f32_16x16x32_bf16 v[32:35], v[212:215], v[172:175], v[32:35]
	v_mfma_f32_16x16x32_bf16 v[20:23], v[196:199], v[180:183], v[20:23]
	v_mfma_f32_16x16x32_bf16 v[16:19], v[212:215], v[180:183], v[16:19]
	v_mfma_f32_16x16x32_bf16 v[4:7], v[196:199], v[188:191], v[4:7]
	v_mfma_f32_16x16x32_bf16 v[0:3], v[212:215], v[188:191], v[0:3]
	v_mfma_f32_16x16x32_bf16 v[52:55], v[208:211], v[148:151], v[52:55]
	v_mfma_f32_16x16x32_bf16 v[48:51], v[216:219], v[148:151], v[48:51]
	v_mfma_f32_16x16x32_bf16 v[36:39], v[208:211], v[176:179], v[36:39]
	v_mfma_f32_16x16x32_bf16 v[32:35], v[216:219], v[176:179], v[32:35]
	v_mfma_f32_16x16x32_bf16 v[20:23], v[208:211], v[184:187], v[20:23]
	v_mfma_f32_16x16x32_bf16 v[16:19], v[216:219], v[184:187], v[16:19]
	v_mfma_f32_16x16x32_bf16 v[4:7], v[208:211], v[192:195], v[4:7]
	v_mfma_f32_16x16x32_bf16 v[0:3], v[216:219], v[192:195], v[0:3]
	s_setprio 0
	s_add_i32 s49, s49, 2
	s_add_u32 s17, s17, 0x40000
	s_addc_u32 s48, s48, 0
	s_add_u32 s24, s24, 0x800000
	s_addc_u32 s25, s25, 0
	s_cmp_gt_u32 s49, 61
	s_barrier
	s_cbranch_scc0 .LBB0_1512
	s_nop 0
	s_lshl_b32 s24, s4, 8
	v_readlane_b32 s68, v253, 38
	v_readlane_b32 s69, v253, 39
	s_ashr_i32 s25, s24, 31
	s_lshl_b32 s4, s4, 2
	v_readlane_b32 s70, v253, 40
	v_readlane_b32 s71, v253, 41
	s_mov_b64 s[48:49], s[68:69]
	v_lshl_add_u32 v178, s6, 8, v163
	s_ashr_i32 s5, s4, 31
	s_lshl_b64 s[26:27], s[24:25], 1
	s_mov_b64 s[50:51], s[70:71]
	s_add_u32 s26, s50, s26
	v_ashrrev_i32_e32 v179, 31, v178
	s_addc_u32 s27, s51, s27
	v_lshlrev_b64 v[128:129], 11, v[178:179]
	v_lshl_add_u64 v[128:129], s[26:27], 0, v[128:129]
	v_lshl_add_u64 v[128:129], v[128:129], 0, v[160:161]
	global_load_dwordx4 v[180:183], v[128:129], off
	global_load_dwordx4 v[184:187], v[128:129], off offset:256
	v_or_b32_e32 v176, 16, v178
	v_or_b32_e32 v174, 32, v178
	v_or_b32_e32 v172, 48, v178
	v_ashrrev_i32_e32 v177, 31, v176
	v_ashrrev_i32_e32 v175, 31, v174
	v_ashrrev_i32_e32 v173, 31, v172
	v_lshlrev_b64 v[128:129], 11, v[176:177]
	v_lshlrev_b64 v[130:131], 11, v[174:175]
	v_lshlrev_b64 v[132:133], 11, v[172:173]
	v_lshl_add_u64 v[128:129], s[26:27], 0, v[128:129]
	v_lshl_add_u64 v[130:131], s[26:27], 0, v[130:131]
	v_lshl_add_u64 v[132:133], s[26:27], 0, v[132:133]
	v_lshl_add_u64 v[128:129], v[128:129], 0, v[160:161]
	v_lshl_add_u64 v[130:131], v[130:131], 0, v[160:161]
	v_lshl_add_u64 v[188:189], v[132:133], 0, v[160:161]
	global_load_dwordx4 v[148:151], v[128:129], off
	global_load_dwordx4 v[144:147], v[128:129], off offset:256
	global_load_dwordx4 v[140:143], v[130:131], off
	global_load_dwordx4 v[136:139], v[130:131], off offset:256
	global_load_dwordx4 v[132:135], v[188:189], off
	s_nop 0
	global_load_dwordx4 v[128:131], v[188:189], off offset:256
	v_and_b32_e32 v189, 64, v206
	v_xor_b32_e32 v188, 16, v206
	v_add_u32_e32 v196, 64, v189
	v_cmp_lt_i32_e32 vcc, v188, v196
	s_nop 1
	v_cndmask_b32_e32 v188, v206, v188, vcc
	v_lshlrev_b32_e32 v207, 2, v188
	s_nop 7
	s_nop 0
	s_waitcnt vmcnt(0)
	v_lshlrev_b32_e32 v190, 16, v182
	v_and_b32_e32 v191, 0xffff0000, v182
	v_lshlrev_b32_e32 v188, 16, v180
	v_and_b32_e32 v189, 0xffff0000, v180
	v_lshlrev_b32_e32 v180, 16, v181
	v_and_b32_e32 v181, 0xffff0000, v181
	v_lshlrev_b32_e32 v182, 16, v183
	v_and_b32_e32 v183, 0xffff0000, v183
	v_pk_add_f32 v[120:121], v[120:121], v[190:191]
	v_pk_add_f32 v[126:127], v[126:127], v[180:181]
	v_pk_add_f32 v[124:125], v[124:125], v[188:189]
	v_pk_add_f32 v[122:123], v[122:123], v[182:183]
	v_mul_f32_e32 v180, v120, v120
	v_mul_f32_e32 v181, v121, v121
	v_lshlrev_b32_e32 v194, 16, v186
	v_and_b32_e32 v195, 0xffff0000, v186
	v_mul_f32_e32 v182, v122, v122
	v_fmac_f32_e32 v180, v124, v124
	v_fmac_f32_e32 v181, v125, v125
	v_lshlrev_b32_e32 v192, 16, v184
	v_and_b32_e32 v193, 0xffff0000, v184
	v_lshlrev_b32_e32 v184, 16, v185
	v_and_b32_e32 v185, 0xffff0000, v185
	v_pk_add_f32 v[112:113], v[112:113], v[194:195]
	v_mul_f32_e32 v183, v123, v123
	v_fmac_f32_e32 v182, v126, v126
	v_add_f32_e32 v180, v180, v181
	v_lshlrev_b32_e32 v186, 16, v187
	v_and_b32_e32 v187, 0xffff0000, v187
	v_pk_add_f32 v[118:119], v[118:119], v[184:185]
	v_pk_add_f32 v[116:117], v[116:117], v[192:193]
	v_mul_f32_e32 v184, v112, v112
	v_fmac_f32_e32 v183, v127, v127
	v_add_f32_e32 v180, v182, v180
	v_pk_add_f32 v[114:115], v[114:115], v[186:187]
	v_mul_f32_e32 v185, v113, v113
	v_fmac_f32_e32 v184, v116, v116
	v_add_f32_e32 v180, v183, v180
	v_mul_f32_e32 v186, v114, v114
	v_fmac_f32_e32 v185, v117, v117
	v_add_f32_e32 v180, v184, v180
	v_mul_f32_e32 v187, v115, v115
	v_fmac_f32_e32 v186, v118, v118
	v_add_f32_e32 v180, v185, v180
	v_add_f32_e32 v180, v186, v180
	v_fmac_f32_e32 v187, v119, v119
	v_add_f32_e32 v180, v187, v180
	ds_bpermute_b32 v181, v207, v180
	v_xor_b32_e32 v182, 32, v206
	v_cmp_lt_i32_e32 vcc, v182, v196
	v_lshlrev_b64 v[188:189], 6, v[178:179]
	s_waitcnt lgkmcnt(0)
	v_add_f32_e32 v180, v180, v181
	v_cndmask_b32_e32 v182, v206, v182, vcc
	v_lshlrev_b32_e32 v208, 2, v182
	ds_bpermute_b32 v181, v208, v180
	s_and_saveexec_b64 s[28:29], s[0:1]
	s_cbranch_execz .LBB0_1515
	s_waitcnt lgkmcnt(0)
	v_add_f32_e32 v182, v180, v181
	v_lshl_add_u64 v[180:181], s[88:89], 0, v[188:189]
	v_lshl_add_u64 v[180:181], s[4:5], 2, v[180:181]
	s_lshl_b32 s8, s40, 2
	v_lshl_add_u64 v[180:181], v[180:181], 0, s[8:9]
	global_store_dword v[180:181], v182, off sc1
